# v33: write-through (sc1) f32x4 output stores in the input-projection GEMM epilogue (outputs never re-read on chip; keeps L2 for operand panels)
# baseline (speedup 1.0000x reference)
; template <int EPI>
; DI void gemm_epilogue(const Params& p, f32x4 (&acc)[8][4], int m0, int n0, int wr, int wc, int fr, int fq, u16* Cb, int ldc) {
;     ...
;       } else if (colt < 8080) {
; #pragma clang loop unroll(full)
;         for (int m = 0; m < 8; ++m) *(f32x4*)(p.out + O_Y + (size_t)(rbase + m * 16) * ZRW + (col - 7248)) = acc[m][n];
.LBB0_984:
	s_andn2_saveexec_b64 s[0:1], s[34:35]
	s_cbranch_execz .LBB0_986
	v_readlane_b32 s12, v231, 6
	v_readlane_b32 s20, v231, 14
	v_readlane_b32 s21, v231, 15
	v_mov_b32_e32 v149, v161
	v_lshlrev_b64 v[138:139], 2, v[148:149]
	v_mov_b64_e32 v[134:135], s[20:21]
	v_mad_i64_i32 v[136:137], s[34:35], v130, s86, v[134:135]
	v_lshl_add_u64 v[136:137], v[136:137], 0, v[138:139]
	v_add_co_u32_e32 v136, vcc, 0xffff9000, v136
	v_or_b32_e32 v129, 16, v130
	s_nop 0
	v_addc_co_u32_e32 v137, vcc, -1, v137, vcc
	global_store_dwordx4 v[136:137], v[124:127], off offset:-320 sc1
	v_mad_i64_i32 v[136:137], s[34:35], v129, s86, v[134:135]
	v_lshl_add_u64 v[136:137], v[136:137], 0, v[138:139]
	v_add_co_u32_e32 v136, vcc, 0xffff9000, v136
	v_or_b32_e32 v129, 32, v130
	s_nop 0
	v_addc_co_u32_e32 v137, vcc, -1, v137, vcc
	global_store_dwordx4 v[136:137], v[120:123], off offset:-320 sc1
	v_mad_i64_i32 v[136:137], s[34:35], v129, s86, v[134:135]
	v_lshl_add_u64 v[136:137], v[136:137], 0, v[138:139]
	v_add_co_u32_e32 v136, vcc, 0xffff9000, v136
	v_or_b32_e32 v129, 48, v130
	s_nop 0
	v_addc_co_u32_e32 v137, vcc, -1, v137, vcc
	global_store_dwordx4 v[136:137], v[116:119], off offset:-320 sc1
	v_mad_i64_i32 v[136:137], s[34:35], v129, s86, v[134:135]
	v_lshl_add_u64 v[136:137], v[136:137], 0, v[138:139]
	v_add_co_u32_e32 v136, vcc, 0xffff9000, v136
	v_or_b32_e32 v129, 64, v130
	s_nop 0
	v_addc_co_u32_e32 v137, vcc, -1, v137, vcc
	global_store_dwordx4 v[136:137], v[112:115], off offset:-320 sc1
	v_mad_i64_i32 v[136:137], s[34:35], v129, s86, v[134:135]
	v_lshl_add_u64 v[136:137], v[136:137], 0, v[138:139]
	v_add_co_u32_e32 v136, vcc, 0xffff9000, v136
	v_or_b32_e32 v129, 0x50, v130
	s_nop 0
	v_addc_co_u32_e32 v137, vcc, -1, v137, vcc
	global_store_dwordx4 v[136:137], v[108:111], off offset:-320 sc1
	v_mad_i64_i32 v[136:137], s[34:35], v129, s86, v[134:135]
	v_lshl_add_u64 v[136:137], v[136:137], 0, v[138:139]
	v_add_co_u32_e32 v136, vcc, 0xffff9000, v136
	v_or_b32_e32 v129, 0x60, v130
	s_nop 0
	v_addc_co_u32_e32 v137, vcc, -1, v137, vcc
	global_store_dwordx4 v[136:137], v[104:107], off offset:-320 sc1
	v_mad_i64_i32 v[136:137], s[34:35], v129, s86, v[134:135]
	v_lshl_add_u64 v[136:137], v[136:137], 0, v[138:139]
	v_or_b32_e32 v129, 0x70, v130
	v_add_co_u32_e32 v136, vcc, 0xffff9000, v136
	v_mad_i64_i32 v[134:135], s[34:35], v129, s86, v[134:135]
	s_nop 0
	v_addc_co_u32_e32 v137, vcc, -1, v137, vcc
	v_lshl_add_u64 v[134:135], v[134:135], 0, v[138:139]
	v_add_co_u32_e32 v134, vcc, 0xffff9000, v134
	v_readlane_b32 s13, v231, 7
	s_nop 0
	v_addc_co_u32_e32 v135, vcc, -1, v135, vcc
	v_readlane_b32 s14, v231, 8
	v_readlane_b32 s15, v231, 9
	v_readlane_b32 s16, v231, 10
	v_readlane_b32 s17, v231, 11
	v_readlane_b32 s18, v231, 12
	v_readlane_b32 s19, v231, 13
	v_readlane_b32 s22, v231, 16
	v_readlane_b32 s23, v231, 17
	v_readlane_b32 s24, v231, 18
	v_readlane_b32 s25, v231, 19
	v_readlane_b32 s26, v231, 20
	v_readlane_b32 s27, v231, 21
	global_store_dwordx4 v[136:137], v[100:103], off offset:-320 sc1
	global_store_dwordx4 v[134:135], v[96:99], off offset:-320 sc1

; template <int EPI>
; DI void gemm_epilogue(const Params& p, f32x4 (&acc)[8][4], int m0, int n0, int wr, int wc, int fr, int fq, u16* Cb, int ldc) {
;     ...
;       } else if (colt < 7248) {
; #pragma clang loop unroll(full)
;         for (int m = 0; m < 8; ++m) *(f32x4*)(p.IXW + (size_t)(rbase + m * 16) * 16 + (col - 7232)) = acc[m][n] * 0.25f;
.LBB0_987:
	s_andn2_saveexec_b64 s[28:29], s[28:29]
	s_cbranch_execz .LBB0_989
	v_ashrrev_i32_e32 v131, 31, v130
	v_readlane_b32 s12, v231, 38
	v_mov_b32_e32 v149, v161
	v_lshlrev_b64 v[138:139], 6, v[130:131]
	v_readlane_b32 s14, v231, 40
	v_readlane_b32 s15, v231, 41
	v_lshlrev_b64 v[140:141], 2, v[148:149]
	v_pk_mul_f32 v[136:137], v[126:127], s[30:31] op_sel_hi:[1,0]
	v_lshl_add_u64 v[138:139], s[14:15], 0, v[138:139]
	v_lshl_add_u64 v[138:139], v[138:139], 0, v[140:141]
	v_add_co_u32_e32 v138, vcc, 0xffff9000, v138
	v_pk_mul_f32 v[134:135], v[124:125], s[30:31] op_sel_hi:[1,0]
	s_nop 0
	v_addc_co_u32_e32 v139, vcc, -1, v139, vcc
	global_store_dwordx4 v[138:139], v[134:137], off offset:-256 sc1
	v_or_b32_e32 v138, 16, v130
	v_ashrrev_i32_e32 v139, 31, v138
	v_lshlrev_b64 v[138:139], 6, v[138:139]
	v_lshl_add_u64 v[138:139], s[14:15], 0, v[138:139]
	v_lshl_add_u64 v[138:139], v[138:139], 0, v[140:141]
	v_add_co_u32_e32 v138, vcc, s83, v138
	v_pk_mul_f32 v[136:137], v[122:123], s[30:31] op_sel_hi:[1,0]
	v_pk_mul_f32 v[134:135], v[120:121], s[30:31] op_sel_hi:[1,0]
	v_addc_co_u32_e32 v139, vcc, -1, v139, vcc
	global_store_dwordx4 v[138:139], v[134:137], off offset:-256 sc1
	v_or_b32_e32 v138, 32, v130
	v_ashrrev_i32_e32 v139, 31, v138
	v_lshlrev_b64 v[138:139], 6, v[138:139]
	v_lshl_add_u64 v[138:139], s[14:15], 0, v[138:139]
	v_lshl_add_u64 v[138:139], v[138:139], 0, v[140:141]
	v_add_co_u32_e32 v138, vcc, s83, v138
	v_pk_mul_f32 v[136:137], v[118:119], s[30:31] op_sel_hi:[1,0]
	v_pk_mul_f32 v[134:135], v[116:117], s[30:31] op_sel_hi:[1,0]
	v_addc_co_u32_e32 v139, vcc, -1, v139, vcc
	global_store_dwordx4 v[138:139], v[134:137], off offset:-256 sc1
	v_or_b32_e32 v138, 48, v130
	v_ashrrev_i32_e32 v139, 31, v138
	v_lshlrev_b64 v[138:139], 6, v[138:139]
	v_lshl_add_u64 v[138:139], s[14:15], 0, v[138:139]
	v_lshl_add_u64 v[138:139], v[138:139], 0, v[140:141]
	v_add_co_u32_e32 v138, vcc, s83, v138
	v_pk_mul_f32 v[136:137], v[114:115], s[30:31] op_sel_hi:[1,0]
	v_pk_mul_f32 v[134:135], v[112:113], s[30:31] op_sel_hi:[1,0]
	v_addc_co_u32_e32 v139, vcc, -1, v139, vcc
	global_store_dwordx4 v[138:139], v[134:137], off offset:-256 sc1
	v_or_b32_e32 v138, 64, v130
	v_ashrrev_i32_e32 v139, 31, v138
	v_lshlrev_b64 v[138:139], 6, v[138:139]
	v_lshl_add_u64 v[138:139], s[14:15], 0, v[138:139]
	v_lshl_add_u64 v[138:139], v[138:139], 0, v[140:141]
	v_add_co_u32_e32 v138, vcc, s83, v138
	v_pk_mul_f32 v[136:137], v[110:111], s[30:31] op_sel_hi:[1,0]
	v_pk_mul_f32 v[134:135], v[108:109], s[30:31] op_sel_hi:[1,0]
	v_addc_co_u32_e32 v139, vcc, -1, v139, vcc
	global_store_dwordx4 v[138:139], v[134:137], off offset:-256 sc1
	v_or_b32_e32 v138, 0x50, v130
	v_ashrrev_i32_e32 v139, 31, v138
	v_lshlrev_b64 v[138:139], 6, v[138:139]
	v_lshl_add_u64 v[138:139], s[14:15], 0, v[138:139]
	v_lshl_add_u64 v[138:139], v[138:139], 0, v[140:141]
	v_add_co_u32_e32 v138, vcc, s83, v138
	v_pk_mul_f32 v[136:137], v[106:107], s[30:31] op_sel_hi:[1,0]
	v_pk_mul_f32 v[134:135], v[104:105], s[30:31] op_sel_hi:[1,0]
	v_addc_co_u32_e32 v139, vcc, -1, v139, vcc
	global_store_dwordx4 v[138:139], v[134:137], off offset:-256 sc1
	v_or_b32_e32 v138, 0x60, v130
	v_ashrrev_i32_e32 v139, 31, v138
	v_lshlrev_b64 v[138:139], 6, v[138:139]
	v_lshl_add_u64 v[138:139], s[14:15], 0, v[138:139]
	v_lshl_add_u64 v[138:139], v[138:139], 0, v[140:141]
	v_add_co_u32_e32 v138, vcc, s83, v138
	v_pk_mul_f32 v[136:137], v[102:103], s[30:31] op_sel_hi:[1,0]
	v_pk_mul_f32 v[134:135], v[100:101], s[30:31] op_sel_hi:[1,0]
	v_addc_co_u32_e32 v139, vcc, -1, v139, vcc
	global_store_dwordx4 v[138:139], v[134:137], off offset:-256 sc1
	v_or_b32_e32 v138, 0x70, v130
	v_ashrrev_i32_e32 v139, 31, v138
	v_lshlrev_b64 v[138:139], 6, v[138:139]
	v_lshl_add_u64 v[138:139], s[14:15], 0, v[138:139]
	v_lshl_add_u64 v[138:139], v[138:139], 0, v[140:141]
	v_add_co_u32_e32 v138, vcc, 0xffff9000, v138
	v_pk_mul_f32 v[136:137], v[98:99], s[30:31] op_sel_hi:[1,0]
	v_pk_mul_f32 v[134:135], v[96:97], s[30:31] op_sel_hi:[1,0]
	v_addc_co_u32_e32 v139, vcc, -1, v139, vcc
	v_readlane_b32 s13, v231, 39
	v_readlane_b32 s16, v231, 42
	v_readlane_b32 s17, v231, 43
	v_readlane_b32 s18, v231, 44
	v_readlane_b32 s19, v231, 45
	v_readlane_b32 s20, v231, 46
	v_readlane_b32 s21, v231, 47
	v_readlane_b32 s22, v231, 48
	v_readlane_b32 s23, v231, 49
	v_readlane_b32 s24, v231, 50
	v_readlane_b32 s25, v231, 51
	v_readlane_b32 s26, v231, 52
	v_readlane_b32 s27, v231, 53
	global_store_dwordx4 v[138:139], v[134:137], off offset:-256 sc1

; DI u32x2 pack4(f32x4 v) { u32x2 r; r[0] = cvtpk(v[0], v[1]); r[1] = cvtpk(v[2], v[3]); return r; }
; template <int EPI>
; DI void gemm_epilogue(const Params& p, f32x4 (&acc)[8][4], int m0, int n0, int wr, int wc, int fr, int fq, u16* Cb, int ldc) {
;     ...
;       } else if (colt < 7232) {
;         const int c = col - 7168;
; #pragma clang loop unroll(full)
;         for (int m = 0; m < 8; ++m) {
;           const int row = rbase + m * 16;
;           if (!smp) *(f32x4*)(p.out + O_IDXP + (size_t)row * 64 + c) = acc[m][n];
;           else *(f32x4*)(p.out + O_IDXS + (size_t)(row - MP) * 64 + c) = acc[m][n];
;           *(u32x2*)(p.IXK + (size_t)krow_of(row) * 64 + c) = pack4(acc[m][n]);
;         }
.LBB0_990:
	s_andn2_saveexec_b64 s[4:5], s[4:5]
	s_cbranch_execz .LBB0_992
	s_and_b64 s[0:1], s[2:3], exec
	v_add_u32_e32 v129, 0xffffc000, v130
	s_mov_b32 s0, 0x19e00000
	v_readlane_b32 s12, v231, 6
	v_cndmask_b32_e64 v136, v130, v129, s[2:3]
	s_cselect_b32 s0, s0, 0x18200000
	v_readlane_b32 s20, v231, 14
	v_lshrrev_b32_e32 v129, 4, v129
	s_add_u32 s28, s20, s0
	v_mad_u64_u32 v[140:141], s[0:1], v129, s94, v[132:133]
	s_movk_i32 s0, 0x4000
	s_nop 0
	v_cmp_gt_i32_e32 vcc, s0, v130
	v_add_u32_e32 v134, 0xffffe400, v148
	v_readlane_b32 s13, v231, 7
	v_readlane_b32 s14, v231, 8
	v_readlane_b32 s15, v231, 9
	v_readlane_b32 s16, v231, 10
	v_readlane_b32 s17, v231, 11
	v_readlane_b32 s18, v231, 12
	v_readlane_b32 s19, v231, 13
	v_readlane_b32 s21, v231, 15
	v_readlane_b32 s22, v231, 16
	v_readlane_b32 s23, v231, 17
	v_readlane_b32 s24, v231, 18
	v_readlane_b32 s25, v231, 19
	v_readlane_b32 s26, v231, 20
	v_readlane_b32 s27, v231, 21
	v_ashrrev_i32_e32 v137, 31, v136
	v_cndmask_b32_e32 v140, v140, v130, vcc
	v_ashrrev_i32_e32 v135, 31, v134
	s_addc_u32 s29, s21, 0
	v_lshlrev_b64 v[136:137], 8, v[136:137]
	v_ashrrev_i32_e32 v141, 31, v140
	v_readlane_b32 s12, v231, 38
	v_lshl_add_u64 v[136:137], s[28:29], 0, v[136:137]
	v_lshlrev_b64 v[138:139], 2, v[134:135]
	v_lshlrev_b64 v[140:141], 7, v[140:141]
	v_readlane_b32 s13, v231, 39
	v_lshl_add_u64 v[136:137], v[136:137], 0, v[138:139]
	v_lshlrev_b64 v[134:135], 1, v[134:135]
	v_lshl_add_u64 v[140:141], s[12:13], 0, v[140:141]
	global_store_dwordx4 v[136:137], v[124:127], off sc1
	v_cvt_pk_bf16_f32 v136, v124, v125
	v_cvt_pk_bf16_f32 v137, v126, v127
	v_lshl_add_u64 v[140:141], v[140:141], 0, v[134:135]
	v_or_b32_e32 v129, 16, v130
	v_add_u32_e32 v131, 0xffffc010, v130
	global_store_dwordx2 v[140:141], v[136:137], off
	v_cndmask_b32_e64 v136, v129, v131, s[2:3]
	v_lshrrev_b32_e32 v131, 4, v131
	v_mad_u64_u32 v[140:141], s[0:1], v131, s94, v[132:133]
	s_movk_i32 s0, 0x3ff0
	s_nop 0
	v_cmp_gt_i32_e32 vcc, s0, v130
	v_ashrrev_i32_e32 v137, 31, v136
	v_lshlrev_b64 v[136:137], 8, v[136:137]
	v_cndmask_b32_e32 v140, v140, v129, vcc
	v_ashrrev_i32_e32 v141, 31, v140
	v_lshl_add_u64 v[136:137], s[28:29], 0, v[136:137]
	v_lshlrev_b64 v[140:141], 7, v[140:141]
	v_lshl_add_u64 v[136:137], v[136:137], 0, v[138:139]
	v_lshl_add_u64 v[140:141], s[12:13], 0, v[140:141]
	global_store_dwordx4 v[136:137], v[120:123], off sc1
	v_cvt_pk_bf16_f32 v136, v120, v121
	v_cvt_pk_bf16_f32 v137, v122, v123
	v_lshl_add_u64 v[140:141], v[140:141], 0, v[134:135]
	v_or_b32_e32 v129, 32, v130
	v_add_u32_e32 v131, 0xffffc020, v130
	global_store_dwordx2 v[140:141], v[136:137], off
	v_cndmask_b32_e64 v136, v129, v131, s[2:3]
	v_lshrrev_b32_e32 v131, 4, v131
	v_mad_u64_u32 v[140:141], s[0:1], v131, s94, v[132:133]
	s_movk_i32 s0, 0x3fe0
	s_nop 0
	v_cmp_gt_i32_e32 vcc, s0, v130
	v_ashrrev_i32_e32 v137, 31, v136
	v_lshlrev_b64 v[136:137], 8, v[136:137]
	v_cndmask_b32_e32 v140, v140, v129, vcc
	v_ashrrev_i32_e32 v141, 31, v140
	v_lshl_add_u64 v[136:137], s[28:29], 0, v[136:137]
	v_lshlrev_b64 v[140:141], 7, v[140:141]
	v_lshl_add_u64 v[136:137], v[136:137], 0, v[138:139]
	v_lshl_add_u64 v[140:141], s[12:13], 0, v[140:141]
	global_store_dwordx4 v[136:137], v[116:119], off sc1
	v_cvt_pk_bf16_f32 v136, v116, v117
	v_cvt_pk_bf16_f32 v137, v118, v119
	v_lshl_add_u64 v[140:141], v[140:141], 0, v[134:135]
	v_or_b32_e32 v129, 48, v130
	v_add_u32_e32 v131, 0xffffc030, v130
	global_store_dwordx2 v[140:141], v[136:137], off
	v_cndmask_b32_e64 v136, v129, v131, s[2:3]
	v_lshrrev_b32_e32 v131, 4, v131
	v_mad_u64_u32 v[140:141], s[0:1], v131, s94, v[132:133]
	s_movk_i32 s0, 0x3fd0
	s_nop 0
	v_cmp_gt_i32_e32 vcc, s0, v130
	v_ashrrev_i32_e32 v137, 31, v136
	v_lshlrev_b64 v[136:137], 8, v[136:137]
	v_cndmask_b32_e32 v140, v140, v129, vcc
	v_ashrrev_i32_e32 v141, 31, v140
	v_lshl_add_u64 v[136:137], s[28:29], 0, v[136:137]
	v_lshlrev_b64 v[140:141], 7, v[140:141]
	v_lshl_add_u64 v[136:137], v[136:137], 0, v[138:139]
	v_lshl_add_u64 v[140:141], s[12:13], 0, v[140:141]
; DI u32x2 pack4(f32x4 v) { u32x2 r; r[0] = cvtpk(v[0], v[1]); r[1] = cvtpk(v[2], v[3]); return r; }
; template <int EPI>
; DI void gemm_epilogue(const Params& p, f32x4 (&acc)[8][4], int m0, int n0, int wr, int wc, int fr, int fq, u16* Cb, int ldc) {
;     ...
;       } else if (colt < 7232) {
;         const int c = col - 7168;
; #pragma clang loop unroll(full)
;         for (int m = 0; m < 8; ++m) {
;           const int row = rbase + m * 16;
;           if (!smp) *(f32x4*)(p.out + O_IDXP + (size_t)row * 64 + c) = acc[m][n];
;           else *(f32x4*)(p.out + O_IDXS + (size_t)(row - MP) * 64 + c) = acc[m][n];
;           *(u32x2*)(p.IXK + (size_t)krow_of(row) * 64 + c) = pack4(acc[m][n]);
;         }
	global_store_dwordx4 v[136:137], v[112:115], off sc1
	v_cvt_pk_bf16_f32 v136, v112, v113
	v_cvt_pk_bf16_f32 v137, v114, v115
	v_lshl_add_u64 v[140:141], v[140:141], 0, v[134:135]
	v_or_b32_e32 v129, 64, v130
	v_add_u32_e32 v131, 0xffffc040, v130
	global_store_dwordx2 v[140:141], v[136:137], off
	v_cndmask_b32_e64 v136, v129, v131, s[2:3]
	v_lshrrev_b32_e32 v131, 4, v131
	v_mad_u64_u32 v[140:141], s[0:1], v131, s94, v[132:133]
	s_movk_i32 s0, 0x3fc0
	s_nop 0
	v_cmp_gt_i32_e32 vcc, s0, v130
	v_ashrrev_i32_e32 v137, 31, v136
	v_lshlrev_b64 v[136:137], 8, v[136:137]
	v_cndmask_b32_e32 v140, v140, v129, vcc
	v_ashrrev_i32_e32 v141, 31, v140
	v_lshl_add_u64 v[136:137], s[28:29], 0, v[136:137]
	v_lshlrev_b64 v[140:141], 7, v[140:141]
	v_lshl_add_u64 v[136:137], v[136:137], 0, v[138:139]
	v_lshl_add_u64 v[140:141], s[12:13], 0, v[140:141]
	global_store_dwordx4 v[136:137], v[108:111], off sc1
	v_cvt_pk_bf16_f32 v136, v108, v109
	v_cvt_pk_bf16_f32 v137, v110, v111
	v_lshl_add_u64 v[140:141], v[140:141], 0, v[134:135]
	v_or_b32_e32 v129, 0x50, v130
	v_add_u32_e32 v131, 0xffffc050, v130
	global_store_dwordx2 v[140:141], v[136:137], off
	v_cndmask_b32_e64 v136, v129, v131, s[2:3]
	v_lshrrev_b32_e32 v131, 4, v131
	v_mad_u64_u32 v[140:141], s[0:1], v131, s94, v[132:133]
	s_movk_i32 s0, 0x3fb0
	s_nop 0
	v_cmp_gt_i32_e32 vcc, s0, v130
	v_ashrrev_i32_e32 v137, 31, v136
	v_lshlrev_b64 v[136:137], 8, v[136:137]
	v_cndmask_b32_e32 v140, v140, v129, vcc
	v_ashrrev_i32_e32 v141, 31, v140
	v_lshl_add_u64 v[136:137], s[28:29], 0, v[136:137]
	v_lshlrev_b64 v[140:141], 7, v[140:141]
	v_lshl_add_u64 v[136:137], v[136:137], 0, v[138:139]
	v_lshl_add_u64 v[140:141], s[12:13], 0, v[140:141]
	global_store_dwordx4 v[136:137], v[104:107], off sc1
	v_cvt_pk_bf16_f32 v136, v104, v105
	v_cvt_pk_bf16_f32 v137, v106, v107
	v_lshl_add_u64 v[140:141], v[140:141], 0, v[134:135]
	v_or_b32_e32 v129, 0x60, v130
	v_add_u32_e32 v131, 0xffffc060, v130
	global_store_dwordx2 v[140:141], v[136:137], off
	v_cndmask_b32_e64 v136, v129, v131, s[2:3]
	v_lshrrev_b32_e32 v131, 4, v131
	v_mad_u64_u32 v[140:141], s[0:1], v131, s94, v[132:133]
	s_movk_i32 s0, 0x3fa0
	s_nop 0
	v_cmp_gt_i32_e32 vcc, s0, v130
	v_ashrrev_i32_e32 v137, 31, v136
	v_lshlrev_b64 v[136:137], 8, v[136:137]
	v_cndmask_b32_e32 v140, v140, v129, vcc
	v_ashrrev_i32_e32 v141, 31, v140
	v_lshl_add_u64 v[136:137], s[28:29], 0, v[136:137]
	v_lshlrev_b64 v[140:141], 7, v[140:141]
	v_lshl_add_u64 v[136:137], v[136:137], 0, v[138:139]
	v_lshl_add_u64 v[140:141], s[12:13], 0, v[140:141]
	global_store_dwordx4 v[136:137], v[100:103], off sc1
	v_cvt_pk_bf16_f32 v136, v100, v101
	v_cvt_pk_bf16_f32 v137, v102, v103
	v_lshl_add_u64 v[140:141], v[140:141], 0, v[134:135]
	v_or_b32_e32 v129, 0x70, v130
	v_add_u32_e32 v131, 0xffffc070, v130
	global_store_dwordx2 v[140:141], v[136:137], off
	v_cndmask_b32_e64 v136, v129, v131, s[2:3]
	v_ashrrev_i32_e32 v137, 31, v136
	v_lshlrev_b64 v[136:137], 8, v[136:137]
	v_lshl_add_u64 v[136:137], s[28:29], 0, v[136:137]
	v_lshrrev_b32_e32 v131, 4, v131
	v_lshl_add_u64 v[136:137], v[136:137], 0, v[138:139]
	v_mad_u64_u32 v[138:139], s[0:1], v131, s94, v[132:133]
	s_movk_i32 s0, 0x3f90
	s_nop 0
	v_cmp_gt_i32_e32 vcc, s0, v130
	global_store_dwordx4 v[136:137], v[96:99], off sc1
	v_cvt_pk_bf16_f32 v136, v96, v97
	v_cndmask_b32_e32 v138, v138, v129, vcc
	v_ashrrev_i32_e32 v139, 31, v138
	v_lshlrev_b64 v[138:139], 7, v[138:139]
	v_lshl_add_u64 v[138:139], s[12:13], 0, v[138:139]
	v_cvt_pk_bf16_f32 v137, v98, v99
	v_lshl_add_u64 v[134:135], v[138:139], 0, v[134:135]
	v_readlane_b32 s14, v231, 40
	v_readlane_b32 s15, v231, 41
	v_readlane_b32 s16, v231, 42
	v_readlane_b32 s17, v231, 43
	v_readlane_b32 s18, v231, 44
	v_readlane_b32 s19, v231, 45
	v_readlane_b32 s20, v231, 46
	v_readlane_b32 s21, v231, 47
	v_readlane_b32 s22, v231, 48
	v_readlane_b32 s23, v231, 49
	v_readlane_b32 s24, v231, 50
	v_readlane_b32 s25, v231, 51
	v_readlane_b32 s26, v231, 52
	v_readlane_b32 s27, v231, 53
	global_store_dwordx2 v[134:135], v[136:137], off

; DI u16 f2bf(float x) { return (u16)(cvtpk(x, 0.f) & 0xffffu); }
; template <int EPI>
; DI void gemm_epilogue(const Params& p, f32x4 (&acc)[8][4], int m0, int n0, int wr, int wc, int fr, int fq, u16* Cb, int ldc) {
;     ...
;       } else if (colt < 6144) {
;         const int c = col - 4096;
; #pragma clang loop unroll(full)
;         for (int m = 0; m < 8; ++m) {
;           const int row = rbase + m * 16;
;           if (!smp) {
;             *(f32x4*)(p.out + O_AVP + (size_t)row * 2048 + c) = acc[m][n];
; #pragma clang loop unroll(full)
;             for (int j = 0; j < 4; ++j) p.VAT[(size_t)(c + j) * MP + row] = f2bf(acc[m][n][j]);
;           } else *(f32x4*)(p.out + O_AVS + (size_t)(row - MP) * 2048 + c) = acc[m][n];
;         }
.LBB0_996:
	s_andn2_b64 vcc, exec, s[0:1]
	s_cbranch_vccnz .LBB0_1029
	v_add_u32_e32 v134, 0xfffff000, v148
	v_ashrrev_i32_e32 v135, 31, v134
	v_cndmask_b32_e64 v129, 0, 1, s[88:89]
	s_mov_b64 s[0:1], -1
	v_cmp_ne_u32_e64 s[4:5], 1, v129
	s_andn2_b64 vcc, exec, s[88:89]
	v_lshlrev_b64 v[136:137], 15, v[134:135]
	s_cbranch_vccnz .LBB0_1013
	v_ashrrev_i32_e32 v131, 31, v130
	v_lshlrev_b64 v[138:139], 13, v[130:131]
	v_lshl_add_u64 v[138:139], s[6:7], 0, v[138:139]
	v_lshl_add_u64 v[138:139], v[134:135], 2, v[138:139]
	global_store_dwordx4 v[138:139], v[124:127], off sc1
	v_lshl_add_u64 v[138:139], v[130:131], 1, s[48:49]
	v_cvt_pk_bf16_f32 v129, v124, s0
	v_lshl_add_u64 v[140:141], v[138:139], 0, v[136:137]
	v_ashrrev_i32_e32 v149, 31, v148
	global_store_short v[140:141], v129, off
	v_lshlrev_b64 v[140:141], 15, v[148:149]
	v_cvt_pk_bf16_f32 v129, v125, s0
	v_lshl_add_u64 v[138:139], v[138:139], 0, v[140:141]
	s_mov_b32 s0, 0xf8008000
	v_add_co_u32_e32 v140, vcc, s0, v138
	s_nop 1
	v_addc_co_u32_e32 v141, vcc, -1, v139, vcc
	global_store_short v[140:141], v129, off
	v_add_co_u32_e32 v140, vcc, 0xf8010000, v138
	v_cvt_pk_bf16_f32 v129, v126, s0
	s_nop 0
	v_addc_co_u32_e32 v141, vcc, -1, v139, vcc
	v_add_co_u32_e32 v138, vcc, 0xf8018000, v138
	global_store_short v[140:141], v129, off
	v_cvt_pk_bf16_f32 v129, v127, s0
	v_addc_co_u32_e32 v139, vcc, -1, v139, vcc
	global_store_short v[138:139], v129, off
	s_cbranch_execz .LBB0_1014

; DI u16 f2bf(float x) { return (u16)(cvtpk(x, 0.f) & 0xffffu); }
; template <int EPI>
; DI void gemm_epilogue(const Params& p, f32x4 (&acc)[8][4], int m0, int n0, int wr, int wc, int fr, int fq, u16* Cb, int ldc) {
;     ...
;       } else if (colt < 6144) {
;         const int c = col - 4096;
; #pragma clang loop unroll(full)
;         for (int m = 0; m < 8; ++m) {
;           const int row = rbase + m * 16;
;           if (!smp) {
;             *(f32x4*)(p.out + O_AVP + (size_t)row * 2048 + c) = acc[m][n];
; #pragma clang loop unroll(full)
;             for (int j = 0; j < 4; ++j) p.VAT[(size_t)(c + j) * MP + row] = f2bf(acc[m][n][j]);
;           } else *(f32x4*)(p.out + O_AVS + (size_t)(row - MP) * 2048 + c) = acc[m][n];
;         }
.LBB0_1000:
	v_or_b32_e32 v138, 16, v130
	v_ashrrev_i32_e32 v139, 31, v138
	v_lshlrev_b64 v[138:139], 13, v[138:139]
	v_lshl_add_u64 v[138:139], s[6:7], 0, v[138:139]
	v_lshl_add_u64 v[138:139], v[134:135], 2, v[138:139]
	v_ashrrev_i32_e32 v131, 31, v130
	global_store_dwordx4 v[138:139], v[120:123], off sc1
	v_lshl_add_u64 v[138:139], v[130:131], 1, s[48:49]
	v_cvt_pk_bf16_f32 v129, v120, s0
	v_lshl_add_u64 v[140:141], v[138:139], 0, v[136:137]
	v_ashrrev_i32_e32 v149, 31, v148
	global_store_short v[140:141], v129, off offset:32
	v_lshlrev_b64 v[140:141], 15, v[148:149]
	v_cvt_pk_bf16_f32 v129, v121, s0
	v_lshl_add_u64 v[138:139], v[138:139], 0, v[140:141]
	s_mov_b32 s0, 0xf8009000
	v_add_co_u32_e32 v140, vcc, s0, v138
	s_nop 1
	v_addc_co_u32_e32 v141, vcc, -1, v139, vcc
	global_store_short v[140:141], v129, off offset:-4064
	v_add_co_u32_e32 v140, vcc, 0xf8011000, v138
	v_cvt_pk_bf16_f32 v129, v122, s0
	s_nop 0
	v_addc_co_u32_e32 v141, vcc, -1, v139, vcc
	v_add_co_u32_e32 v138, vcc, 0xf8019000, v138
	global_store_short v[140:141], v129, off offset:-4064
	v_cvt_pk_bf16_f32 v129, v123, s0
	v_addc_co_u32_e32 v139, vcc, -1, v139, vcc
	global_store_short v[138:139], v129, off offset:-4064
	s_cbranch_execz .LBB0_1016

; DI u16 f2bf(float x) { return (u16)(cvtpk(x, 0.f) & 0xffffu); }
; template <int EPI>
; DI void gemm_epilogue(const Params& p, f32x4 (&acc)[8][4], int m0, int n0, int wr, int wc, int fr, int fq, u16* Cb, int ldc) {
;     ...
;       } else if (colt < 6144) {
;         const int c = col - 4096;
; #pragma clang loop unroll(full)
;         for (int m = 0; m < 8; ++m) {
;           const int row = rbase + m * 16;
;           if (!smp) {
;             *(f32x4*)(p.out + O_AVP + (size_t)row * 2048 + c) = acc[m][n];
; #pragma clang loop unroll(full)
;             for (int j = 0; j < 4; ++j) p.VAT[(size_t)(c + j) * MP + row] = f2bf(acc[m][n][j]);
;           } else *(f32x4*)(p.out + O_AVS + (size_t)(row - MP) * 2048 + c) = acc[m][n];
;         }
.LBB0_1002:
	v_or_b32_e32 v138, 32, v130
	v_ashrrev_i32_e32 v139, 31, v138
	v_lshlrev_b64 v[138:139], 13, v[138:139]
	v_lshl_add_u64 v[138:139], s[6:7], 0, v[138:139]
	v_lshl_add_u64 v[138:139], v[134:135], 2, v[138:139]
	v_ashrrev_i32_e32 v131, 31, v130
	global_store_dwordx4 v[138:139], v[116:119], off sc1
	v_lshl_add_u64 v[138:139], v[130:131], 1, s[48:49]
	v_cvt_pk_bf16_f32 v129, v116, s0
	v_lshl_add_u64 v[140:141], v[138:139], 0, v[136:137]
	v_ashrrev_i32_e32 v149, 31, v148
	global_store_short v[140:141], v129, off offset:64
	v_lshlrev_b64 v[140:141], 15, v[148:149]
	v_cvt_pk_bf16_f32 v129, v117, s0
	v_lshl_add_u64 v[138:139], v[138:139], 0, v[140:141]
	s_mov_b32 s0, 0xf8009000
	v_add_co_u32_e32 v140, vcc, s0, v138
	s_nop 1
	v_addc_co_u32_e32 v141, vcc, -1, v139, vcc
	global_store_short v[140:141], v129, off offset:-4032
	v_add_co_u32_e32 v140, vcc, 0xf8011000, v138
	v_cvt_pk_bf16_f32 v129, v118, s0
	s_nop 0
	v_addc_co_u32_e32 v141, vcc, -1, v139, vcc
	v_add_co_u32_e32 v138, vcc, 0xf8019000, v138
	global_store_short v[140:141], v129, off offset:-4032
	v_cvt_pk_bf16_f32 v129, v119, s0
	v_addc_co_u32_e32 v139, vcc, -1, v139, vcc
	global_store_short v[138:139], v129, off offset:-4032
	s_cbranch_execz .LBB0_1018

; DI u16 f2bf(float x) { return (u16)(cvtpk(x, 0.f) & 0xffffu); }
; template <int EPI>
; DI void gemm_epilogue(const Params& p, f32x4 (&acc)[8][4], int m0, int n0, int wr, int wc, int fr, int fq, u16* Cb, int ldc) {
;     ...
;       } else if (colt < 6144) {
;         const int c = col - 4096;
; #pragma clang loop unroll(full)
;         for (int m = 0; m < 8; ++m) {
;           const int row = rbase + m * 16;
;           if (!smp) {
;             *(f32x4*)(p.out + O_AVP + (size_t)row * 2048 + c) = acc[m][n];
; #pragma clang loop unroll(full)
;             for (int j = 0; j < 4; ++j) p.VAT[(size_t)(c + j) * MP + row] = f2bf(acc[m][n][j]);
;           } else *(f32x4*)(p.out + O_AVS + (size_t)(row - MP) * 2048 + c) = acc[m][n];
;         }
.LBB0_1004:
	v_or_b32_e32 v138, 48, v130
	v_ashrrev_i32_e32 v139, 31, v138
	v_lshlrev_b64 v[138:139], 13, v[138:139]
	v_lshl_add_u64 v[138:139], s[6:7], 0, v[138:139]
	v_lshl_add_u64 v[138:139], v[134:135], 2, v[138:139]
	v_ashrrev_i32_e32 v131, 31, v130
	global_store_dwordx4 v[138:139], v[112:115], off sc1
	v_lshl_add_u64 v[138:139], v[130:131], 1, s[48:49]
	v_cvt_pk_bf16_f32 v129, v112, s0
	v_lshl_add_u64 v[140:141], v[138:139], 0, v[136:137]
	v_ashrrev_i32_e32 v149, 31, v148
	global_store_short v[140:141], v129, off offset:96
	v_lshlrev_b64 v[140:141], 15, v[148:149]
	v_cvt_pk_bf16_f32 v129, v113, s0
	v_lshl_add_u64 v[138:139], v[138:139], 0, v[140:141]
	s_mov_b32 s0, 0xf8009000
	v_add_co_u32_e32 v140, vcc, s0, v138
	s_nop 1
	v_addc_co_u32_e32 v141, vcc, -1, v139, vcc
	global_store_short v[140:141], v129, off offset:-4000
	v_add_co_u32_e32 v140, vcc, 0xf8011000, v138
	v_cvt_pk_bf16_f32 v129, v114, s0
	s_nop 0
	v_addc_co_u32_e32 v141, vcc, -1, v139, vcc
	v_add_co_u32_e32 v138, vcc, 0xf8019000, v138
	global_store_short v[140:141], v129, off offset:-4000
	v_cvt_pk_bf16_f32 v129, v115, s0
	v_addc_co_u32_e32 v139, vcc, -1, v139, vcc
	global_store_short v[138:139], v129, off offset:-4000
	s_cbranch_execz .LBB0_1020

; DI u16 f2bf(float x) { return (u16)(cvtpk(x, 0.f) & 0xffffu); }
; template <int EPI>
; DI void gemm_epilogue(const Params& p, f32x4 (&acc)[8][4], int m0, int n0, int wr, int wc, int fr, int fq, u16* Cb, int ldc) {
;     ...
;       } else if (colt < 6144) {
;         const int c = col - 4096;
; #pragma clang loop unroll(full)
;         for (int m = 0; m < 8; ++m) {
;           const int row = rbase + m * 16;
;           if (!smp) {
;             *(f32x4*)(p.out + O_AVP + (size_t)row * 2048 + c) = acc[m][n];
; #pragma clang loop unroll(full)
;             for (int j = 0; j < 4; ++j) p.VAT[(size_t)(c + j) * MP + row] = f2bf(acc[m][n][j]);
;           } else *(f32x4*)(p.out + O_AVS + (size_t)(row - MP) * 2048 + c) = acc[m][n];
;         }
.LBB0_1006:
	v_or_b32_e32 v138, 64, v130
	v_ashrrev_i32_e32 v139, 31, v138
	v_lshlrev_b64 v[138:139], 13, v[138:139]
	v_lshl_add_u64 v[138:139], s[6:7], 0, v[138:139]
	v_lshl_add_u64 v[138:139], v[134:135], 2, v[138:139]
	v_ashrrev_i32_e32 v131, 31, v130
	global_store_dwordx4 v[138:139], v[108:111], off sc1
	v_lshl_add_u64 v[138:139], v[130:131], 1, s[48:49]
	v_cvt_pk_bf16_f32 v129, v108, s0
	v_lshl_add_u64 v[140:141], v[138:139], 0, v[136:137]
	v_ashrrev_i32_e32 v149, 31, v148
	global_store_short v[140:141], v129, off offset:128
	v_lshlrev_b64 v[140:141], 15, v[148:149]
	v_cvt_pk_bf16_f32 v129, v109, s0
	v_lshl_add_u64 v[138:139], v[138:139], 0, v[140:141]
	s_mov_b32 s0, 0xf8009000
	v_add_co_u32_e32 v140, vcc, s0, v138
	s_nop 1
	v_addc_co_u32_e32 v141, vcc, -1, v139, vcc
	global_store_short v[140:141], v129, off offset:-3968
	v_add_co_u32_e32 v140, vcc, 0xf8011000, v138
	v_cvt_pk_bf16_f32 v129, v110, s0
	s_nop 0
	v_addc_co_u32_e32 v141, vcc, -1, v139, vcc
	v_add_co_u32_e32 v138, vcc, 0xf8019000, v138
	global_store_short v[140:141], v129, off offset:-3968
	v_cvt_pk_bf16_f32 v129, v111, s0
	v_addc_co_u32_e32 v139, vcc, -1, v139, vcc
	global_store_short v[138:139], v129, off offset:-3968
	s_cbranch_execz .LBB0_1022

; DI u16 f2bf(float x) { return (u16)(cvtpk(x, 0.f) & 0xffffu); }
; template <int EPI>
; DI void gemm_epilogue(const Params& p, f32x4 (&acc)[8][4], int m0, int n0, int wr, int wc, int fr, int fq, u16* Cb, int ldc) {
;     ...
;       } else if (colt < 6144) {
;         const int c = col - 4096;
; #pragma clang loop unroll(full)
;         for (int m = 0; m < 8; ++m) {
;           const int row = rbase + m * 16;
;           if (!smp) {
;             *(f32x4*)(p.out + O_AVP + (size_t)row * 2048 + c) = acc[m][n];
; #pragma clang loop unroll(full)
;             for (int j = 0; j < 4; ++j) p.VAT[(size_t)(c + j) * MP + row] = f2bf(acc[m][n][j]);
;           } else *(f32x4*)(p.out + O_AVS + (size_t)(row - MP) * 2048 + c) = acc[m][n];
;         }
.LBB0_1008:
	v_or_b32_e32 v138, 0x50, v130
	v_ashrrev_i32_e32 v139, 31, v138
	v_lshlrev_b64 v[138:139], 13, v[138:139]
	v_lshl_add_u64 v[138:139], s[6:7], 0, v[138:139]
	v_lshl_add_u64 v[138:139], v[134:135], 2, v[138:139]
	v_ashrrev_i32_e32 v131, 31, v130
	global_store_dwordx4 v[138:139], v[104:107], off sc1
	v_lshl_add_u64 v[138:139], v[130:131], 1, s[48:49]
	v_cvt_pk_bf16_f32 v129, v104, s0
	v_lshl_add_u64 v[140:141], v[138:139], 0, v[136:137]
	v_ashrrev_i32_e32 v149, 31, v148
	global_store_short v[140:141], v129, off offset:160
	v_lshlrev_b64 v[140:141], 15, v[148:149]
	v_cvt_pk_bf16_f32 v129, v105, s0
	v_lshl_add_u64 v[138:139], v[138:139], 0, v[140:141]
	s_mov_b32 s0, 0xf8009000
	v_add_co_u32_e32 v140, vcc, s0, v138
	s_nop 1
	v_addc_co_u32_e32 v141, vcc, -1, v139, vcc
	global_store_short v[140:141], v129, off offset:-3936
	v_add_co_u32_e32 v140, vcc, 0xf8011000, v138
	v_cvt_pk_bf16_f32 v129, v106, s0
	s_nop 0
	v_addc_co_u32_e32 v141, vcc, -1, v139, vcc
	v_add_co_u32_e32 v138, vcc, 0xf8019000, v138
	global_store_short v[140:141], v129, off offset:-3936
	v_cvt_pk_bf16_f32 v129, v107, s0
	v_addc_co_u32_e32 v139, vcc, -1, v139, vcc
	global_store_short v[138:139], v129, off offset:-3936
	s_cbranch_execz .LBB0_1024

; DI u16 f2bf(float x) { return (u16)(cvtpk(x, 0.f) & 0xffffu); }
; template <int EPI>
; DI void gemm_epilogue(const Params& p, f32x4 (&acc)[8][4], int m0, int n0, int wr, int wc, int fr, int fq, u16* Cb, int ldc) {
;     ...
;       } else if (colt < 6144) {
;         const int c = col - 4096;
; #pragma clang loop unroll(full)
;         for (int m = 0; m < 8; ++m) {
;           const int row = rbase + m * 16;
;           if (!smp) {
;             *(f32x4*)(p.out + O_AVP + (size_t)row * 2048 + c) = acc[m][n];
; #pragma clang loop unroll(full)
;             for (int j = 0; j < 4; ++j) p.VAT[(size_t)(c + j) * MP + row] = f2bf(acc[m][n][j]);
;           } else *(f32x4*)(p.out + O_AVS + (size_t)(row - MP) * 2048 + c) = acc[m][n];
;         }
.LBB0_1010:
	v_or_b32_e32 v138, 0x60, v130
	v_ashrrev_i32_e32 v139, 31, v138
	v_lshlrev_b64 v[138:139], 13, v[138:139]
	v_lshl_add_u64 v[138:139], s[6:7], 0, v[138:139]
	v_lshl_add_u64 v[138:139], v[134:135], 2, v[138:139]
	v_ashrrev_i32_e32 v131, 31, v130
	global_store_dwordx4 v[138:139], v[100:103], off sc1
	v_lshl_add_u64 v[138:139], v[130:131], 1, s[48:49]
	v_cvt_pk_bf16_f32 v129, v100, s0
	v_lshl_add_u64 v[140:141], v[138:139], 0, v[136:137]
	v_ashrrev_i32_e32 v149, 31, v148
	global_store_short v[140:141], v129, off offset:192
	v_lshlrev_b64 v[140:141], 15, v[148:149]
	v_cvt_pk_bf16_f32 v129, v101, s0
	v_lshl_add_u64 v[138:139], v[138:139], 0, v[140:141]
	s_mov_b32 s0, 0xf8009000
	v_add_co_u32_e32 v140, vcc, s0, v138
	s_nop 1
	v_addc_co_u32_e32 v141, vcc, -1, v139, vcc
	global_store_short v[140:141], v129, off offset:-3904
	v_add_co_u32_e32 v140, vcc, 0xf8011000, v138
	v_cvt_pk_bf16_f32 v129, v102, s0
	s_nop 0
	v_addc_co_u32_e32 v141, vcc, -1, v139, vcc
	v_add_co_u32_e32 v138, vcc, 0xf8019000, v138
	global_store_short v[140:141], v129, off offset:-3904
	v_cvt_pk_bf16_f32 v129, v103, s0
	v_addc_co_u32_e32 v139, vcc, -1, v139, vcc
	global_store_short v[138:139], v129, off offset:-3904
	s_cbranch_execz .LBB0_1026

; DI u16 f2bf(float x) { return (u16)(cvtpk(x, 0.f) & 0xffffu); }
; template <int EPI>
; DI void gemm_epilogue(const Params& p, f32x4 (&acc)[8][4], int m0, int n0, int wr, int wc, int fr, int fq, u16* Cb, int ldc) {
;     ...
;       } else if (colt < 6144) {
;         const int c = col - 4096;
; #pragma clang loop unroll(full)
;         for (int m = 0; m < 8; ++m) {
;           const int row = rbase + m * 16;
;           if (!smp) {
;             *(f32x4*)(p.out + O_AVP + (size_t)row * 2048 + c) = acc[m][n];
; #pragma clang loop unroll(full)
;             for (int j = 0; j < 4; ++j) p.VAT[(size_t)(c + j) * MP + row] = f2bf(acc[m][n][j]);
;           } else *(f32x4*)(p.out + O_AVS + (size_t)(row - MP) * 2048 + c) = acc[m][n];
;         }
.LBB0_1012:
	v_or_b32_e32 v138, 0x70, v130
	v_ashrrev_i32_e32 v139, 31, v138
	v_lshlrev_b64 v[138:139], 13, v[138:139]
	v_lshl_add_u64 v[138:139], s[6:7], 0, v[138:139]
	v_lshl_add_u64 v[138:139], v[134:135], 2, v[138:139]
	v_ashrrev_i32_e32 v131, 31, v130
	global_store_dwordx4 v[138:139], v[96:99], off sc1
	v_lshl_add_u64 v[138:139], v[130:131], 1, s[48:49]
	v_cvt_pk_bf16_f32 v129, v96, s0
	v_lshl_add_u64 v[136:137], v[138:139], 0, v[136:137]
	v_ashrrev_i32_e32 v149, 31, v148
	global_store_short v[136:137], v129, off offset:224
	v_lshlrev_b64 v[136:137], 15, v[148:149]
	v_cvt_pk_bf16_f32 v129, v97, s0
	v_lshl_add_u64 v[136:137], v[138:139], 0, v[136:137]
	s_mov_b32 s0, 0xf8009000
	v_add_co_u32_e32 v138, vcc, s0, v136
	s_nop 1
	v_addc_co_u32_e32 v139, vcc, -1, v137, vcc
	global_store_short v[138:139], v129, off offset:-3872
	v_add_co_u32_e32 v138, vcc, 0xf8011000, v136
	v_cvt_pk_bf16_f32 v129, v98, s0
	s_nop 0
	v_addc_co_u32_e32 v139, vcc, -1, v137, vcc
	v_add_co_u32_e32 v136, vcc, 0xf8019000, v136
	global_store_short v[138:139], v129, off offset:-3872
	v_cvt_pk_bf16_f32 v129, v99, s0
	v_addc_co_u32_e32 v137, vcc, -1, v137, vcc
	global_store_short v[136:137], v129, off offset:-3872
	s_cbranch_execz .LBB0_1028
	s_branch .LBB0_1029

; DI u16 f2bf(float x) { return (u16)(cvtpk(x, 0.f) & 0xffffu); }
; template <int EPI>
; DI void gemm_epilogue(const Params& p, f32x4 (&acc)[8][4], int m0, int n0, int wr, int wc, int fr, int fq, u16* Cb, int ldc) {
;     ...
;       } else if (colt < 6144) {
;         const int c = col - 4096;
; #pragma clang loop unroll(full)
;         for (int m = 0; m < 8; ++m) {
;           const int row = rbase + m * 16;
;           if (!smp) {
;             *(f32x4*)(p.out + O_AVP + (size_t)row * 2048 + c) = acc[m][n];
; #pragma clang loop unroll(full)
;             for (int j = 0; j < 4; ++j) p.VAT[(size_t)(c + j) * MP + row] = f2bf(acc[m][n][j]);
;           } else *(f32x4*)(p.out + O_AVS + (size_t)(row - MP) * 2048 + c) = acc[m][n];
;         }
.LBB0_1014:
	v_ashrrev_i32_e32 v131, 31, v130
	v_lshlrev_b64 v[138:139], 13, v[130:131]
	v_lshl_add_u64 v[138:139], s[62:63], 0, v[138:139]
	v_lshl_add_u64 v[138:139], v[134:135], 2, v[138:139]
	v_add_co_u32_e32 v138, vcc, 0xf8000000, v138
	s_nop 1
	v_addc_co_u32_e32 v139, vcc, -1, v139, vcc
	global_store_dwordx4 v[138:139], v[124:127], off sc1
	s_and_b64 vcc, exec, s[4:5]
	s_mov_b64 s[0:1], -1
	s_cbranch_vccz .LBB0_1000

; DI u16 f2bf(float x) { return (u16)(cvtpk(x, 0.f) & 0xffffu); }
; template <int EPI>
; DI void gemm_epilogue(const Params& p, f32x4 (&acc)[8][4], int m0, int n0, int wr, int wc, int fr, int fq, u16* Cb, int ldc) {
;     ...
;       } else if (colt < 6144) {
;         const int c = col - 4096;
; #pragma clang loop unroll(full)
;         for (int m = 0; m < 8; ++m) {
;           const int row = rbase + m * 16;
;           if (!smp) {
;             *(f32x4*)(p.out + O_AVP + (size_t)row * 2048 + c) = acc[m][n];
; #pragma clang loop unroll(full)
;             for (int j = 0; j < 4; ++j) p.VAT[(size_t)(c + j) * MP + row] = f2bf(acc[m][n][j]);
;           } else *(f32x4*)(p.out + O_AVS + (size_t)(row - MP) * 2048 + c) = acc[m][n];
;         }
.LBB0_1016:
	v_ashrrev_i32_e32 v131, 31, v130
	v_lshlrev_b64 v[138:139], 13, v[130:131]
	v_lshl_add_u64 v[138:139], s[62:63], 0, v[138:139]
	v_lshl_add_u64 v[138:139], v[134:135], 2, v[138:139]
	v_add_co_u32_e32 v138, vcc, 0xf8020000, v138
	s_nop 1
	v_addc_co_u32_e32 v139, vcc, -1, v139, vcc
	global_store_dwordx4 v[138:139], v[120:123], off sc1
	s_and_b64 vcc, exec, s[4:5]
	s_mov_b64 s[0:1], -1
	s_cbranch_vccz .LBB0_1002

; DI u16 f2bf(float x) { return (u16)(cvtpk(x, 0.f) & 0xffffu); }
; template <int EPI>
; DI void gemm_epilogue(const Params& p, f32x4 (&acc)[8][4], int m0, int n0, int wr, int wc, int fr, int fq, u16* Cb, int ldc) {
;     ...
;       } else if (colt < 6144) {
;         const int c = col - 4096;
; #pragma clang loop unroll(full)
;         for (int m = 0; m < 8; ++m) {
;           const int row = rbase + m * 16;
;           if (!smp) {
;             *(f32x4*)(p.out + O_AVP + (size_t)row * 2048 + c) = acc[m][n];
; #pragma clang loop unroll(full)
;             for (int j = 0; j < 4; ++j) p.VAT[(size_t)(c + j) * MP + row] = f2bf(acc[m][n][j]);
;           } else *(f32x4*)(p.out + O_AVS + (size_t)(row - MP) * 2048 + c) = acc[m][n];
;         }
.LBB0_1018:
	v_ashrrev_i32_e32 v131, 31, v130
	v_lshlrev_b64 v[138:139], 13, v[130:131]
	v_lshl_add_u64 v[138:139], s[62:63], 0, v[138:139]
	v_lshl_add_u64 v[138:139], v[134:135], 2, v[138:139]
	v_add_co_u32_e32 v138, vcc, 0xf8040000, v138
	s_nop 1
	v_addc_co_u32_e32 v139, vcc, -1, v139, vcc
	global_store_dwordx4 v[138:139], v[116:119], off sc1
	s_and_b64 vcc, exec, s[4:5]
	s_mov_b64 s[0:1], -1
	s_cbranch_vccz .LBB0_1004

; DI u16 f2bf(float x) { return (u16)(cvtpk(x, 0.f) & 0xffffu); }
; template <int EPI>
; DI void gemm_epilogue(const Params& p, f32x4 (&acc)[8][4], int m0, int n0, int wr, int wc, int fr, int fq, u16* Cb, int ldc) {
;     ...
;       } else if (colt < 6144) {
;         const int c = col - 4096;
; #pragma clang loop unroll(full)
;         for (int m = 0; m < 8; ++m) {
;           const int row = rbase + m * 16;
;           if (!smp) {
;             *(f32x4*)(p.out + O_AVP + (size_t)row * 2048 + c) = acc[m][n];
; #pragma clang loop unroll(full)
;             for (int j = 0; j < 4; ++j) p.VAT[(size_t)(c + j) * MP + row] = f2bf(acc[m][n][j]);
;           } else *(f32x4*)(p.out + O_AVS + (size_t)(row - MP) * 2048 + c) = acc[m][n];
;         }
.LBB0_1020:
	v_ashrrev_i32_e32 v131, 31, v130
	v_lshlrev_b64 v[138:139], 13, v[130:131]
	v_lshl_add_u64 v[138:139], s[62:63], 0, v[138:139]
	v_lshl_add_u64 v[138:139], v[134:135], 2, v[138:139]
	v_add_co_u32_e32 v138, vcc, 0xf8060000, v138
	s_nop 1
	v_addc_co_u32_e32 v139, vcc, -1, v139, vcc
	global_store_dwordx4 v[138:139], v[112:115], off sc1
	s_and_b64 vcc, exec, s[4:5]
	s_mov_b64 s[0:1], -1
	s_cbranch_vccz .LBB0_1006

; DI u16 f2bf(float x) { return (u16)(cvtpk(x, 0.f) & 0xffffu); }
; template <int EPI>
; DI void gemm_epilogue(const Params& p, f32x4 (&acc)[8][4], int m0, int n0, int wr, int wc, int fr, int fq, u16* Cb, int ldc) {
;     ...
;       } else if (colt < 6144) {
;         const int c = col - 4096;
; #pragma clang loop unroll(full)
;         for (int m = 0; m < 8; ++m) {
;           const int row = rbase + m * 16;
;           if (!smp) {
;             *(f32x4*)(p.out + O_AVP + (size_t)row * 2048 + c) = acc[m][n];
; #pragma clang loop unroll(full)
;             for (int j = 0; j < 4; ++j) p.VAT[(size_t)(c + j) * MP + row] = f2bf(acc[m][n][j]);
;           } else *(f32x4*)(p.out + O_AVS + (size_t)(row - MP) * 2048 + c) = acc[m][n];
;         }
.LBB0_1022:
	v_ashrrev_i32_e32 v131, 31, v130
	v_lshlrev_b64 v[138:139], 13, v[130:131]
	v_lshl_add_u64 v[138:139], s[62:63], 0, v[138:139]
	v_lshl_add_u64 v[138:139], v[134:135], 2, v[138:139]
	v_add_co_u32_e32 v138, vcc, 0xf8080000, v138
	s_nop 1
	v_addc_co_u32_e32 v139, vcc, -1, v139, vcc
	global_store_dwordx4 v[138:139], v[108:111], off sc1
	s_and_b64 vcc, exec, s[4:5]
	s_mov_b64 s[0:1], -1
	s_cbranch_vccz .LBB0_1008

; DI u16 f2bf(float x) { return (u16)(cvtpk(x, 0.f) & 0xffffu); }
; template <int EPI>
; DI void gemm_epilogue(const Params& p, f32x4 (&acc)[8][4], int m0, int n0, int wr, int wc, int fr, int fq, u16* Cb, int ldc) {
;     ...
;       } else if (colt < 6144) {
;         const int c = col - 4096;
; #pragma clang loop unroll(full)
;         for (int m = 0; m < 8; ++m) {
;           const int row = rbase + m * 16;
;           if (!smp) {
;             *(f32x4*)(p.out + O_AVP + (size_t)row * 2048 + c) = acc[m][n];
; #pragma clang loop unroll(full)
;             for (int j = 0; j < 4; ++j) p.VAT[(size_t)(c + j) * MP + row] = f2bf(acc[m][n][j]);
;           } else *(f32x4*)(p.out + O_AVS + (size_t)(row - MP) * 2048 + c) = acc[m][n];
;         }
.LBB0_1024:
	v_ashrrev_i32_e32 v131, 31, v130
	v_lshlrev_b64 v[138:139], 13, v[130:131]
	v_lshl_add_u64 v[138:139], s[62:63], 0, v[138:139]
	v_lshl_add_u64 v[138:139], v[134:135], 2, v[138:139]
	v_add_co_u32_e32 v138, vcc, 0xf80a0000, v138
	s_nop 1
	v_addc_co_u32_e32 v139, vcc, -1, v139, vcc
	global_store_dwordx4 v[138:139], v[104:107], off sc1
	s_and_b64 vcc, exec, s[4:5]
	s_mov_b64 s[0:1], -1
	s_cbranch_vccz .LBB0_1010

; DI u16 f2bf(float x) { return (u16)(cvtpk(x, 0.f) & 0xffffu); }
; template <int EPI>
; DI void gemm_epilogue(const Params& p, f32x4 (&acc)[8][4], int m0, int n0, int wr, int wc, int fr, int fq, u16* Cb, int ldc) {
;     ...
;       } else if (colt < 6144) {
;         const int c = col - 4096;
; #pragma clang loop unroll(full)
;         for (int m = 0; m < 8; ++m) {
;           const int row = rbase + m * 16;
;           if (!smp) {
;             *(f32x4*)(p.out + O_AVP + (size_t)row * 2048 + c) = acc[m][n];
; #pragma clang loop unroll(full)
;             for (int j = 0; j < 4; ++j) p.VAT[(size_t)(c + j) * MP + row] = f2bf(acc[m][n][j]);
;           } else *(f32x4*)(p.out + O_AVS + (size_t)(row - MP) * 2048 + c) = acc[m][n];
;         }
.LBB0_1026:
	v_ashrrev_i32_e32 v131, 31, v130
	v_lshlrev_b64 v[138:139], 13, v[130:131]
	v_lshl_add_u64 v[138:139], s[62:63], 0, v[138:139]
	v_lshl_add_u64 v[138:139], v[134:135], 2, v[138:139]
	v_add_co_u32_e32 v138, vcc, 0xf80c0000, v138
	s_nop 1
	v_addc_co_u32_e32 v139, vcc, -1, v139, vcc
	global_store_dwordx4 v[138:139], v[100:103], off sc1
	s_and_b64 vcc, exec, s[4:5]
	s_mov_b64 s[0:1], -1
	s_cbranch_vccz .LBB0_1012

; DI u16 f2bf(float x) { return (u16)(cvtpk(x, 0.f) & 0xffffu); }
; template <int EPI>
; DI void gemm_epilogue(const Params& p, f32x4 (&acc)[8][4], int m0, int n0, int wr, int wc, int fr, int fq, u16* Cb, int ldc) {
;     ...
;       } else if (colt < 6144) {
;         const int c = col - 4096;
; #pragma clang loop unroll(full)
;         for (int m = 0; m < 8; ++m) {
;           const int row = rbase + m * 16;
;           if (!smp) {
;             *(f32x4*)(p.out + O_AVP + (size_t)row * 2048 + c) = acc[m][n];
; #pragma clang loop unroll(full)
;             for (int j = 0; j < 4; ++j) p.VAT[(size_t)(c + j) * MP + row] = f2bf(acc[m][n][j]);
;           } else *(f32x4*)(p.out + O_AVS + (size_t)(row - MP) * 2048 + c) = acc[m][n];
;         }
.LBB0_1028:
	v_ashrrev_i32_e32 v131, 31, v130
	v_lshlrev_b64 v[136:137], 13, v[130:131]
	v_lshl_add_u64 v[136:137], s[62:63], 0, v[136:137]
	v_lshl_add_u64 v[134:135], v[134:135], 2, v[136:137]
	v_add_co_u32_e32 v134, vcc, 0xf80e0000, v134
	s_nop 1
	v_addc_co_u32_e32 v135, vcc, -1, v135, vcc
	global_store_dwordx4 v[134:135], v[96:99], off sc1

; DI u32x2 pack4(f32x4 v) { u32x2 r; r[0] = cvtpk(v[0], v[1]); r[1] = cvtpk(v[2], v[3]); return r; }
; template <int EPI>
; DI void gemm_epilogue(const Params& p, f32x4 (&acc)[8][4], int m0, int n0, int wr, int wc, int fr, int fq, u16* Cb, int ldc) {
;     ...
;       } else if (colt < 4096) {
;         const int c = col - 2048;
; #pragma clang loop unroll(full)
;         for (int m = 0; m < 8; ++m) {
;           const int row = rbase + m * 16;
;           if (!smp) { *(f32x4*)(p.out + O_AKP + (size_t)row * 2048 + c) = acc[m][n]; *(u32x2*)(p.KA + (size_t)row * 2048 + c) = pack4(acc[m][n]); }
;           else *(f32x4*)(p.out + O_AKS + (size_t)(row - MP) * 2048 + c) = acc[m][n];
;         }
.LBB0_1030:
	s_andn2_b64 vcc, exec, s[0:1]
	s_cbranch_vccnz .LBB0_1063
	v_add_u32_e32 v134, 0xfffff800, v148
	v_cndmask_b32_e64 v129, 0, 1, s[88:89]
	v_ashrrev_i32_e32 v135, 31, v134
	v_cmp_ne_u32_e64 s[4:5], 1, v129
	s_andn2_b64 vcc, exec, s[88:89]
	s_mov_b64 s[0:1], -1
	s_cbranch_vccnz .LBB0_1047
	v_ashrrev_i32_e32 v131, 31, v130
	v_lshlrev_b64 v[136:137], 13, v[130:131]
	v_lshl_add_u64 v[136:137], s[8:9], 0, v[136:137]
	v_lshlrev_b64 v[138:139], 12, v[130:131]
	v_lshl_add_u64 v[136:137], v[134:135], 2, v[136:137]
	v_lshl_add_u64 v[138:139], s[46:47], 0, v[138:139]
	v_ashrrev_i32_e32 v149, 31, v148
	global_store_dwordx4 v[136:137], v[124:127], off sc1
	v_cvt_pk_bf16_f32 v136, v124, v125
	v_cvt_pk_bf16_f32 v137, v126, v127
	v_lshl_add_u64 v[138:139], v[148:149], 1, v[138:139]
	global_store_dwordx2 v[138:139], v[136:137], off offset:-4096
	s_cbranch_execz .LBB0_1048

; DI u32x2 pack4(f32x4 v) { u32x2 r; r[0] = cvtpk(v[0], v[1]); r[1] = cvtpk(v[2], v[3]); return r; }
; template <int EPI>
; DI void gemm_epilogue(const Params& p, f32x4 (&acc)[8][4], int m0, int n0, int wr, int wc, int fr, int fq, u16* Cb, int ldc) {
;     ...
;       } else if (colt < 4096) {
;         const int c = col - 2048;
; #pragma clang loop unroll(full)
;         for (int m = 0; m < 8; ++m) {
;           const int row = rbase + m * 16;
;           if (!smp) { *(f32x4*)(p.out + O_AKP + (size_t)row * 2048 + c) = acc[m][n]; *(u32x2*)(p.KA + (size_t)row * 2048 + c) = pack4(acc[m][n]); }
;           else *(f32x4*)(p.out + O_AKS + (size_t)(row - MP) * 2048 + c) = acc[m][n];
;         }
.LBB0_1034:
	v_or_b32_e32 v136, 16, v130
	v_ashrrev_i32_e32 v137, 31, v136
	v_lshlrev_b64 v[138:139], 13, v[136:137]
	v_lshl_add_u64 v[138:139], s[8:9], 0, v[138:139]
	v_lshlrev_b64 v[136:137], 12, v[136:137]
	v_lshl_add_u64 v[138:139], v[134:135], 2, v[138:139]
	v_lshl_add_u64 v[136:137], s[46:47], 0, v[136:137]
	v_ashrrev_i32_e32 v149, 31, v148
	global_store_dwordx4 v[138:139], v[120:123], off sc1
	v_cvt_pk_bf16_f32 v138, v120, v121
	v_cvt_pk_bf16_f32 v139, v122, v123
	v_lshl_add_u64 v[136:137], v[148:149], 1, v[136:137]
	global_store_dwordx2 v[136:137], v[138:139], off offset:-4096
	s_cbranch_execz .LBB0_1050

; DI u32x2 pack4(f32x4 v) { u32x2 r; r[0] = cvtpk(v[0], v[1]); r[1] = cvtpk(v[2], v[3]); return r; }
; template <int EPI>
; DI void gemm_epilogue(const Params& p, f32x4 (&acc)[8][4], int m0, int n0, int wr, int wc, int fr, int fq, u16* Cb, int ldc) {
;     ...
;       } else if (colt < 4096) {
;         const int c = col - 2048;
; #pragma clang loop unroll(full)
;         for (int m = 0; m < 8; ++m) {
;           const int row = rbase + m * 16;
;           if (!smp) { *(f32x4*)(p.out + O_AKP + (size_t)row * 2048 + c) = acc[m][n]; *(u32x2*)(p.KA + (size_t)row * 2048 + c) = pack4(acc[m][n]); }
;           else *(f32x4*)(p.out + O_AKS + (size_t)(row - MP) * 2048 + c) = acc[m][n];
;         }
.LBB0_1036:
	v_or_b32_e32 v136, 32, v130
	v_ashrrev_i32_e32 v137, 31, v136
	v_lshlrev_b64 v[138:139], 13, v[136:137]
	v_lshl_add_u64 v[138:139], s[8:9], 0, v[138:139]
	v_lshlrev_b64 v[136:137], 12, v[136:137]
	v_lshl_add_u64 v[138:139], v[134:135], 2, v[138:139]
	v_lshl_add_u64 v[136:137], s[46:47], 0, v[136:137]
	v_ashrrev_i32_e32 v149, 31, v148
	global_store_dwordx4 v[138:139], v[116:119], off sc1
	v_cvt_pk_bf16_f32 v138, v116, v117
	v_cvt_pk_bf16_f32 v139, v118, v119
	v_lshl_add_u64 v[136:137], v[148:149], 1, v[136:137]
	global_store_dwordx2 v[136:137], v[138:139], off offset:-4096
	s_cbranch_execz .LBB0_1052

; DI u32x2 pack4(f32x4 v) { u32x2 r; r[0] = cvtpk(v[0], v[1]); r[1] = cvtpk(v[2], v[3]); return r; }
; template <int EPI>
; DI void gemm_epilogue(const Params& p, f32x4 (&acc)[8][4], int m0, int n0, int wr, int wc, int fr, int fq, u16* Cb, int ldc) {
;     ...
;       } else if (colt < 4096) {
;         const int c = col - 2048;
; #pragma clang loop unroll(full)
;         for (int m = 0; m < 8; ++m) {
;           const int row = rbase + m * 16;
;           if (!smp) { *(f32x4*)(p.out + O_AKP + (size_t)row * 2048 + c) = acc[m][n]; *(u32x2*)(p.KA + (size_t)row * 2048 + c) = pack4(acc[m][n]); }
;           else *(f32x4*)(p.out + O_AKS + (size_t)(row - MP) * 2048 + c) = acc[m][n];
;         }
.LBB0_1038:
	v_or_b32_e32 v136, 48, v130
	v_ashrrev_i32_e32 v137, 31, v136
	v_lshlrev_b64 v[138:139], 13, v[136:137]
	v_lshl_add_u64 v[138:139], s[8:9], 0, v[138:139]
	v_lshlrev_b64 v[136:137], 12, v[136:137]
	v_lshl_add_u64 v[138:139], v[134:135], 2, v[138:139]
	v_lshl_add_u64 v[136:137], s[46:47], 0, v[136:137]
	v_ashrrev_i32_e32 v149, 31, v148
	global_store_dwordx4 v[138:139], v[112:115], off sc1
	v_cvt_pk_bf16_f32 v138, v112, v113
	v_cvt_pk_bf16_f32 v139, v114, v115
	v_lshl_add_u64 v[136:137], v[148:149], 1, v[136:137]
	global_store_dwordx2 v[136:137], v[138:139], off offset:-4096
	s_cbranch_execz .LBB0_1054

; DI u32x2 pack4(f32x4 v) { u32x2 r; r[0] = cvtpk(v[0], v[1]); r[1] = cvtpk(v[2], v[3]); return r; }
; template <int EPI>
; DI void gemm_epilogue(const Params& p, f32x4 (&acc)[8][4], int m0, int n0, int wr, int wc, int fr, int fq, u16* Cb, int ldc) {
;     ...
;       } else if (colt < 4096) {
;         const int c = col - 2048;
; #pragma clang loop unroll(full)
;         for (int m = 0; m < 8; ++m) {
;           const int row = rbase + m * 16;
;           if (!smp) { *(f32x4*)(p.out + O_AKP + (size_t)row * 2048 + c) = acc[m][n]; *(u32x2*)(p.KA + (size_t)row * 2048 + c) = pack4(acc[m][n]); }
;           else *(f32x4*)(p.out + O_AKS + (size_t)(row - MP) * 2048 + c) = acc[m][n];
;         }
.LBB0_1040:
	v_or_b32_e32 v136, 64, v130
	v_ashrrev_i32_e32 v137, 31, v136
	v_lshlrev_b64 v[138:139], 13, v[136:137]
	v_lshl_add_u64 v[138:139], s[8:9], 0, v[138:139]
	v_lshlrev_b64 v[136:137], 12, v[136:137]
	v_lshl_add_u64 v[138:139], v[134:135], 2, v[138:139]
	v_lshl_add_u64 v[136:137], s[46:47], 0, v[136:137]
	v_ashrrev_i32_e32 v149, 31, v148
	global_store_dwordx4 v[138:139], v[108:111], off sc1
	v_cvt_pk_bf16_f32 v138, v108, v109
	v_cvt_pk_bf16_f32 v139, v110, v111
	v_lshl_add_u64 v[136:137], v[148:149], 1, v[136:137]
	global_store_dwordx2 v[136:137], v[138:139], off offset:-4096
	s_cbranch_execz .LBB0_1056

; DI u32x2 pack4(f32x4 v) { u32x2 r; r[0] = cvtpk(v[0], v[1]); r[1] = cvtpk(v[2], v[3]); return r; }
; template <int EPI>
; DI void gemm_epilogue(const Params& p, f32x4 (&acc)[8][4], int m0, int n0, int wr, int wc, int fr, int fq, u16* Cb, int ldc) {
;     ...
;       } else if (colt < 4096) {
;         const int c = col - 2048;
; #pragma clang loop unroll(full)
;         for (int m = 0; m < 8; ++m) {
;           const int row = rbase + m * 16;
;           if (!smp) { *(f32x4*)(p.out + O_AKP + (size_t)row * 2048 + c) = acc[m][n]; *(u32x2*)(p.KA + (size_t)row * 2048 + c) = pack4(acc[m][n]); }
;           else *(f32x4*)(p.out + O_AKS + (size_t)(row - MP) * 2048 + c) = acc[m][n];
;         }
.LBB0_1042:
	v_or_b32_e32 v136, 0x50, v130
	v_ashrrev_i32_e32 v137, 31, v136
	v_lshlrev_b64 v[138:139], 13, v[136:137]
	v_lshl_add_u64 v[138:139], s[8:9], 0, v[138:139]
	v_lshlrev_b64 v[136:137], 12, v[136:137]
	v_lshl_add_u64 v[138:139], v[134:135], 2, v[138:139]
	v_lshl_add_u64 v[136:137], s[46:47], 0, v[136:137]
	v_ashrrev_i32_e32 v149, 31, v148
	global_store_dwordx4 v[138:139], v[104:107], off sc1
	v_cvt_pk_bf16_f32 v138, v104, v105
	v_cvt_pk_bf16_f32 v139, v106, v107
	v_lshl_add_u64 v[136:137], v[148:149], 1, v[136:137]
	global_store_dwordx2 v[136:137], v[138:139], off offset:-4096
	s_cbranch_execz .LBB0_1058

; DI u32x2 pack4(f32x4 v) { u32x2 r; r[0] = cvtpk(v[0], v[1]); r[1] = cvtpk(v[2], v[3]); return r; }
; template <int EPI>
; DI void gemm_epilogue(const Params& p, f32x4 (&acc)[8][4], int m0, int n0, int wr, int wc, int fr, int fq, u16* Cb, int ldc) {
;     ...
;       } else if (colt < 4096) {
;         const int c = col - 2048;
; #pragma clang loop unroll(full)
;         for (int m = 0; m < 8; ++m) {
;           const int row = rbase + m * 16;
;           if (!smp) { *(f32x4*)(p.out + O_AKP + (size_t)row * 2048 + c) = acc[m][n]; *(u32x2*)(p.KA + (size_t)row * 2048 + c) = pack4(acc[m][n]); }
;           else *(f32x4*)(p.out + O_AKS + (size_t)(row - MP) * 2048 + c) = acc[m][n];
;         }
.LBB0_1044:
	v_or_b32_e32 v136, 0x60, v130
	v_ashrrev_i32_e32 v137, 31, v136
	v_lshlrev_b64 v[138:139], 13, v[136:137]
	v_lshl_add_u64 v[138:139], s[8:9], 0, v[138:139]
	v_lshlrev_b64 v[136:137], 12, v[136:137]
	v_lshl_add_u64 v[138:139], v[134:135], 2, v[138:139]
	v_lshl_add_u64 v[136:137], s[46:47], 0, v[136:137]
	v_ashrrev_i32_e32 v149, 31, v148
	global_store_dwordx4 v[138:139], v[100:103], off sc1
	v_cvt_pk_bf16_f32 v138, v100, v101
	v_cvt_pk_bf16_f32 v139, v102, v103
	v_lshl_add_u64 v[136:137], v[148:149], 1, v[136:137]
	global_store_dwordx2 v[136:137], v[138:139], off offset:-4096
	s_cbranch_execz .LBB0_1060

; DI u32x2 pack4(f32x4 v) { u32x2 r; r[0] = cvtpk(v[0], v[1]); r[1] = cvtpk(v[2], v[3]); return r; }
; template <int EPI>
; DI void gemm_epilogue(const Params& p, f32x4 (&acc)[8][4], int m0, int n0, int wr, int wc, int fr, int fq, u16* Cb, int ldc) {
;     ...
;       } else if (colt < 4096) {
;         const int c = col - 2048;
; #pragma clang loop unroll(full)
;         for (int m = 0; m < 8; ++m) {
;           const int row = rbase + m * 16;
;           if (!smp) { *(f32x4*)(p.out + O_AKP + (size_t)row * 2048 + c) = acc[m][n]; *(u32x2*)(p.KA + (size_t)row * 2048 + c) = pack4(acc[m][n]); }
;           else *(f32x4*)(p.out + O_AKS + (size_t)(row - MP) * 2048 + c) = acc[m][n];
;         }
.LBB0_1046:
	v_or_b32_e32 v136, 0x70, v130
	v_ashrrev_i32_e32 v137, 31, v136
	v_lshlrev_b64 v[138:139], 13, v[136:137]
	v_lshl_add_u64 v[138:139], s[8:9], 0, v[138:139]
	v_lshlrev_b64 v[136:137], 12, v[136:137]
	v_lshl_add_u64 v[138:139], v[134:135], 2, v[138:139]
	v_lshl_add_u64 v[136:137], s[46:47], 0, v[136:137]
	v_ashrrev_i32_e32 v149, 31, v148
	global_store_dwordx4 v[138:139], v[96:99], off sc1
	v_cvt_pk_bf16_f32 v138, v96, v97
	v_cvt_pk_bf16_f32 v139, v98, v99
	v_lshl_add_u64 v[136:137], v[148:149], 1, v[136:137]
	global_store_dwordx2 v[136:137], v[138:139], off offset:-4096
	s_cbranch_execz .LBB0_1062
	s_branch .LBB0_1063

; DI u32x2 pack4(f32x4 v) { u32x2 r; r[0] = cvtpk(v[0], v[1]); r[1] = cvtpk(v[2], v[3]); return r; }
; template <int EPI>
; DI void gemm_epilogue(const Params& p, f32x4 (&acc)[8][4], int m0, int n0, int wr, int wc, int fr, int fq, u16* Cb, int ldc) {
;     ...
;       } else if (colt < 4096) {
;         const int c = col - 2048;
; #pragma clang loop unroll(full)
;         for (int m = 0; m < 8; ++m) {
;           const int row = rbase + m * 16;
;           if (!smp) { *(f32x4*)(p.out + O_AKP + (size_t)row * 2048 + c) = acc[m][n]; *(u32x2*)(p.KA + (size_t)row * 2048 + c) = pack4(acc[m][n]); }
;           else *(f32x4*)(p.out + O_AKS + (size_t)(row - MP) * 2048 + c) = acc[m][n];
;         }
.LBB0_1048:
	v_ashrrev_i32_e32 v131, 31, v130
	v_lshlrev_b64 v[136:137], 13, v[130:131]
	v_lshl_add_u64 v[136:137], s[64:65], 0, v[136:137]
	v_lshl_add_u64 v[136:137], v[134:135], 2, v[136:137]
	v_add_co_u32_e32 v136, vcc, 0xf8000000, v136
	s_nop 1
	v_addc_co_u32_e32 v137, vcc, -1, v137, vcc
	global_store_dwordx4 v[136:137], v[124:127], off sc1
	s_and_b64 vcc, exec, s[4:5]
	s_mov_b64 s[0:1], -1
	s_cbranch_vccz .LBB0_1034

; DI u32x2 pack4(f32x4 v) { u32x2 r; r[0] = cvtpk(v[0], v[1]); r[1] = cvtpk(v[2], v[3]); return r; }
; template <int EPI>
; DI void gemm_epilogue(const Params& p, f32x4 (&acc)[8][4], int m0, int n0, int wr, int wc, int fr, int fq, u16* Cb, int ldc) {
;     ...
;       } else if (colt < 4096) {
;         const int c = col - 2048;
; #pragma clang loop unroll(full)
;         for (int m = 0; m < 8; ++m) {
;           const int row = rbase + m * 16;
;           if (!smp) { *(f32x4*)(p.out + O_AKP + (size_t)row * 2048 + c) = acc[m][n]; *(u32x2*)(p.KA + (size_t)row * 2048 + c) = pack4(acc[m][n]); }
;           else *(f32x4*)(p.out + O_AKS + (size_t)(row - MP) * 2048 + c) = acc[m][n];
;         }
.LBB0_1050:
	v_ashrrev_i32_e32 v131, 31, v130
	v_lshlrev_b64 v[136:137], 13, v[130:131]
	v_lshl_add_u64 v[136:137], s[64:65], 0, v[136:137]
	v_lshl_add_u64 v[136:137], v[134:135], 2, v[136:137]
	v_add_co_u32_e32 v136, vcc, 0xf8020000, v136
	s_nop 1
	v_addc_co_u32_e32 v137, vcc, -1, v137, vcc
	global_store_dwordx4 v[136:137], v[120:123], off sc1
	s_and_b64 vcc, exec, s[4:5]
	s_mov_b64 s[0:1], -1
	s_cbranch_vccz .LBB0_1036

; DI u32x2 pack4(f32x4 v) { u32x2 r; r[0] = cvtpk(v[0], v[1]); r[1] = cvtpk(v[2], v[3]); return r; }
; template <int EPI>
; DI void gemm_epilogue(const Params& p, f32x4 (&acc)[8][4], int m0, int n0, int wr, int wc, int fr, int fq, u16* Cb, int ldc) {
;     ...
;       } else if (colt < 4096) {
;         const int c = col - 2048;
; #pragma clang loop unroll(full)
;         for (int m = 0; m < 8; ++m) {
;           const int row = rbase + m * 16;
;           if (!smp) { *(f32x4*)(p.out + O_AKP + (size_t)row * 2048 + c) = acc[m][n]; *(u32x2*)(p.KA + (size_t)row * 2048 + c) = pack4(acc[m][n]); }
;           else *(f32x4*)(p.out + O_AKS + (size_t)(row - MP) * 2048 + c) = acc[m][n];
;         }
.LBB0_1052:
	v_ashrrev_i32_e32 v131, 31, v130
	v_lshlrev_b64 v[136:137], 13, v[130:131]
	v_lshl_add_u64 v[136:137], s[64:65], 0, v[136:137]
	v_lshl_add_u64 v[136:137], v[134:135], 2, v[136:137]
	v_add_co_u32_e32 v136, vcc, 0xf8040000, v136
	s_nop 1
	v_addc_co_u32_e32 v137, vcc, -1, v137, vcc
	global_store_dwordx4 v[136:137], v[116:119], off sc1
	s_and_b64 vcc, exec, s[4:5]
	s_mov_b64 s[0:1], -1
	s_cbranch_vccz .LBB0_1038

; DI u32x2 pack4(f32x4 v) { u32x2 r; r[0] = cvtpk(v[0], v[1]); r[1] = cvtpk(v[2], v[3]); return r; }
; template <int EPI>
; DI void gemm_epilogue(const Params& p, f32x4 (&acc)[8][4], int m0, int n0, int wr, int wc, int fr, int fq, u16* Cb, int ldc) {
;     ...
;       } else if (colt < 4096) {
;         const int c = col - 2048;
; #pragma clang loop unroll(full)
;         for (int m = 0; m < 8; ++m) {
;           const int row = rbase + m * 16;
;           if (!smp) { *(f32x4*)(p.out + O_AKP + (size_t)row * 2048 + c) = acc[m][n]; *(u32x2*)(p.KA + (size_t)row * 2048 + c) = pack4(acc[m][n]); }
;           else *(f32x4*)(p.out + O_AKS + (size_t)(row - MP) * 2048 + c) = acc[m][n];
;         }
.LBB0_1054:
	v_ashrrev_i32_e32 v131, 31, v130
	v_lshlrev_b64 v[136:137], 13, v[130:131]
	v_lshl_add_u64 v[136:137], s[64:65], 0, v[136:137]
	v_lshl_add_u64 v[136:137], v[134:135], 2, v[136:137]
	v_add_co_u32_e32 v136, vcc, 0xf8060000, v136
	s_nop 1
	v_addc_co_u32_e32 v137, vcc, -1, v137, vcc
	global_store_dwordx4 v[136:137], v[112:115], off sc1
	s_and_b64 vcc, exec, s[4:5]
	s_mov_b64 s[0:1], -1
	s_cbranch_vccz .LBB0_1040

; DI u32x2 pack4(f32x4 v) { u32x2 r; r[0] = cvtpk(v[0], v[1]); r[1] = cvtpk(v[2], v[3]); return r; }
; template <int EPI>
; DI void gemm_epilogue(const Params& p, f32x4 (&acc)[8][4], int m0, int n0, int wr, int wc, int fr, int fq, u16* Cb, int ldc) {
;     ...
;         for (int m = 0; m < 8; ++m) {
;           const int row = rbase + m * 16;
;           if (!smp) { *(f32x4*)(p.out + O_AKP + (size_t)row * 2048 + c) = acc[m][n]; *(u32x2*)(p.KA + (size_t)row * 2048 + c) = pack4(acc[m][n]); }
;           else *(f32x4*)(p.out + O_AKS + (size_t)(row - MP) * 2048 + c) = acc[m][n];
;         }
.LBB0_1056:
	v_ashrrev_i32_e32 v131, 31, v130
	v_lshlrev_b64 v[136:137], 13, v[130:131]
	v_lshl_add_u64 v[136:137], s[64:65], 0, v[136:137]
	v_lshl_add_u64 v[136:137], v[134:135], 2, v[136:137]
	v_add_co_u32_e32 v136, vcc, 0xf8080000, v136
	s_nop 1
	v_addc_co_u32_e32 v137, vcc, -1, v137, vcc
	global_store_dwordx4 v[136:137], v[108:111], off sc1
	s_and_b64 vcc, exec, s[4:5]
	s_mov_b64 s[0:1], -1
	s_cbranch_vccz .LBB0_1042

; DI u32x2 pack4(f32x4 v) { u32x2 r; r[0] = cvtpk(v[0], v[1]); r[1] = cvtpk(v[2], v[3]); return r; }
; template <int EPI>
; DI void gemm_epilogue(const Params& p, f32x4 (&acc)[8][4], int m0, int n0, int wr, int wc, int fr, int fq, u16* Cb, int ldc) {
;     ...
;         for (int m = 0; m < 8; ++m) {
;           const int row = rbase + m * 16;
;           if (!smp) { *(f32x4*)(p.out + O_AKP + (size_t)row * 2048 + c) = acc[m][n]; *(u32x2*)(p.KA + (size_t)row * 2048 + c) = pack4(acc[m][n]); }
;           else *(f32x4*)(p.out + O_AKS + (size_t)(row - MP) * 2048 + c) = acc[m][n];
;         }
.LBB0_1058:
	v_ashrrev_i32_e32 v131, 31, v130
	v_lshlrev_b64 v[136:137], 13, v[130:131]
	v_lshl_add_u64 v[136:137], s[64:65], 0, v[136:137]
	v_lshl_add_u64 v[136:137], v[134:135], 2, v[136:137]
	v_add_co_u32_e32 v136, vcc, 0xf80a0000, v136
	s_nop 1
	v_addc_co_u32_e32 v137, vcc, -1, v137, vcc
	global_store_dwordx4 v[136:137], v[104:107], off sc1
	s_and_b64 vcc, exec, s[4:5]
	s_mov_b64 s[0:1], -1
	s_cbranch_vccz .LBB0_1044

; DI u32x2 pack4(f32x4 v) { u32x2 r; r[0] = cvtpk(v[0], v[1]); r[1] = cvtpk(v[2], v[3]); return r; }
; template <int EPI>
; DI void gemm_epilogue(const Params& p, f32x4 (&acc)[8][4], int m0, int n0, int wr, int wc, int fr, int fq, u16* Cb, int ldc) {
;     ...
;         for (int m = 0; m < 8; ++m) {
;           const int row = rbase + m * 16;
;           if (!smp) { *(f32x4*)(p.out + O_AKP + (size_t)row * 2048 + c) = acc[m][n]; *(u32x2*)(p.KA + (size_t)row * 2048 + c) = pack4(acc[m][n]); }
;           else *(f32x4*)(p.out + O_AKS + (size_t)(row - MP) * 2048 + c) = acc[m][n];
;         }
.LBB0_1060:
	v_ashrrev_i32_e32 v131, 31, v130
	v_lshlrev_b64 v[136:137], 13, v[130:131]
	v_lshl_add_u64 v[136:137], s[64:65], 0, v[136:137]
	v_lshl_add_u64 v[136:137], v[134:135], 2, v[136:137]
	v_add_co_u32_e32 v136, vcc, 0xf80c0000, v136
	s_nop 1
	v_addc_co_u32_e32 v137, vcc, -1, v137, vcc
	global_store_dwordx4 v[136:137], v[100:103], off sc1
	s_and_b64 vcc, exec, s[4:5]
	s_mov_b64 s[0:1], -1
	s_cbranch_vccz .LBB0_1046

; DI u32x2 pack4(f32x4 v) { u32x2 r; r[0] = cvtpk(v[0], v[1]); r[1] = cvtpk(v[2], v[3]); return r; }
; template <int EPI>
; DI void gemm_epilogue(const Params& p, f32x4 (&acc)[8][4], int m0, int n0, int wr, int wc, int fr, int fq, u16* Cb, int ldc) {
;     ...
;         for (int m = 0; m < 8; ++m) {
;           const int row = rbase + m * 16;
;           if (!smp) { *(f32x4*)(p.out + O_AKP + (size_t)row * 2048 + c) = acc[m][n]; *(u32x2*)(p.KA + (size_t)row * 2048 + c) = pack4(acc[m][n]); }
;           else *(f32x4*)(p.out + O_AKS + (size_t)(row - MP) * 2048 + c) = acc[m][n];
;         }
.LBB0_1062:
	v_ashrrev_i32_e32 v131, 31, v130
	v_lshlrev_b64 v[136:137], 13, v[130:131]
	v_lshl_add_u64 v[136:137], s[64:65], 0, v[136:137]
	v_lshl_add_u64 v[134:135], v[134:135], 2, v[136:137]
	v_add_co_u32_e32 v134, vcc, 0xf80e0000, v134
	s_nop 1
	v_addc_co_u32_e32 v135, vcc, -1, v135, vcc
	global_store_dwordx4 v[134:135], v[96:99], off sc1

; template <int EPI>
; DI void gemm_epilogue(const Params& p, f32x4 (&acc)[8][4], int m0, int n0, int wr, int wc, int fr, int fq, u16* Cb, int ldc) {
;     ...
;       } else if (colt < 8080) {
; #pragma clang loop unroll(full)
;         for (int m = 0; m < 8; ++m) *(f32x4*)(p.out + O_Y + (size_t)(rbase + m * 16) * ZRW + (col - 7248)) = acc[m][n];
.LBB0_1074:
	s_andn2_saveexec_b64 s[0:1], s[28:29]
	s_cbranch_execz .LBB0_1076
	v_readlane_b32 s12, v231, 6
	v_readlane_b32 s20, v231, 14
	v_readlane_b32 s21, v231, 15
	v_add_u32_e32 v102, v128, v160
	v_mov_b32_e32 v103, v161
	v_mov_b64_e32 v[96:97], s[20:21]
	v_mad_i64_i32 v[100:101], s[28:29], v130, s86, v[96:97]
	v_lshlrev_b64 v[102:103], 2, v[102:103]
	v_lshl_add_u64 v[100:101], v[100:101], 0, v[102:103]
	v_add_co_u32_e32 v100, vcc, 0xffff9000, v100
	v_readlane_b32 s13, v231, 7
	s_nop 0
	v_addc_co_u32_e32 v101, vcc, -1, v101, vcc
	global_store_dwordx4 v[100:101], v[92:95], off offset:-256 sc1
	v_mad_i64_i32 v[100:101], s[28:29], v146, s86, v[96:97]
	v_lshl_add_u64 v[100:101], v[100:101], 0, v[102:103]
	v_add_co_u32_e32 v100, vcc, 0xffff9000, v100
	v_readlane_b32 s14, v231, 8
	s_nop 0
	v_addc_co_u32_e32 v101, vcc, -1, v101, vcc
	global_store_dwordx4 v[100:101], v[88:91], off offset:-256 sc1
	v_mad_i64_i32 v[100:101], s[28:29], v144, s86, v[96:97]
	v_lshl_add_u64 v[100:101], v[100:101], 0, v[102:103]
	v_add_co_u32_e32 v100, vcc, 0xffff9000, v100
	v_readlane_b32 s15, v231, 9
	s_nop 0
	v_addc_co_u32_e32 v101, vcc, -1, v101, vcc
	global_store_dwordx4 v[100:101], v[84:87], off offset:-256 sc1
	v_mad_i64_i32 v[100:101], s[28:29], v142, s86, v[96:97]
	v_lshl_add_u64 v[100:101], v[100:101], 0, v[102:103]
	v_add_co_u32_e32 v100, vcc, 0xffff9000, v100
	v_readlane_b32 s16, v231, 10
	s_nop 0
	v_addc_co_u32_e32 v101, vcc, -1, v101, vcc
	global_store_dwordx4 v[100:101], v[80:83], off offset:-256 sc1
	v_mad_i64_i32 v[100:101], s[28:29], v140, s86, v[96:97]
	v_lshl_add_u64 v[100:101], v[100:101], 0, v[102:103]
	v_add_co_u32_e32 v100, vcc, 0xffff9000, v100
	v_readlane_b32 s17, v231, 11
	s_nop 0
	v_addc_co_u32_e32 v101, vcc, -1, v101, vcc
	global_store_dwordx4 v[100:101], v[76:79], off offset:-256 sc1
	v_mad_i64_i32 v[100:101], s[28:29], v138, s86, v[96:97]
	v_lshl_add_u64 v[100:101], v[100:101], 0, v[102:103]
	v_add_co_u32_e32 v100, vcc, 0xffff9000, v100
	v_readlane_b32 s18, v231, 12
	s_nop 0
	v_addc_co_u32_e32 v101, vcc, -1, v101, vcc
	global_store_dwordx4 v[100:101], v[72:75], off offset:-256 sc1
	v_mad_i64_i32 v[100:101], s[28:29], v136, s86, v[96:97]
	v_lshl_add_u64 v[100:101], v[100:101], 0, v[102:103]
	v_add_co_u32_e32 v100, vcc, 0xffff9000, v100
	v_mad_i64_i32 v[96:97], s[28:29], v134, s86, v[96:97]
	s_nop 0
	v_addc_co_u32_e32 v101, vcc, -1, v101, vcc
	v_lshl_add_u64 v[96:97], v[96:97], 0, v[102:103]
	v_add_co_u32_e32 v96, vcc, 0xffff9000, v96
	v_readlane_b32 s19, v231, 13
	s_nop 0
	v_addc_co_u32_e32 v97, vcc, -1, v97, vcc
	v_readlane_b32 s22, v231, 16
	v_readlane_b32 s23, v231, 17
	v_readlane_b32 s24, v231, 18
	v_readlane_b32 s25, v231, 19
	v_readlane_b32 s26, v231, 20
	v_readlane_b32 s27, v231, 21
	global_store_dwordx4 v[100:101], v[68:71], off offset:-256 sc1
	global_store_dwordx4 v[96:97], v[64:67], off offset:-256 sc1

; DI u32x2 pack4(f32x4 v) { u32x2 r; r[0] = cvtpk(v[0], v[1]); r[1] = cvtpk(v[2], v[3]); return r; }
; template <int EPI>
; DI void gemm_epilogue(const Params& p, f32x4 (&acc)[8][4], int m0, int n0, int wr, int wc, int fr, int fq, u16* Cb, int ldc) {
;     ...
;       } else if (colt < 7232) {
;         const int c = col - 7168;
; #pragma clang loop unroll(full)
;         for (int m = 0; m < 8; ++m) {
;           const int row = rbase + m * 16;
;           if (!smp) *(f32x4*)(p.out + O_IDXP + (size_t)row * 64 + c) = acc[m][n];
;           else *(f32x4*)(p.out + O_IDXS + (size_t)(row - MP) * 64 + c) = acc[m][n];
;           *(u32x2*)(p.IXK + (size_t)krow_of(row) * 64 + c) = pack4(acc[m][n]);
;         }
.LBB0_1077:
	s_andn2_saveexec_b64 s[4:5], s[4:5]
	s_cbranch_execz .LBB0_1079
	s_and_b64 s[0:1], s[2:3], exec
	s_mov_b32 s0, 0x19e00000
	v_readlane_b32 s12, v231, 6
	s_cselect_b32 s0, s0, 0x18200000
	v_readlane_b32 s20, v231, 14
	v_add_u32_e32 v99, 0xffffc000, v130
	s_add_u32 s28, s20, s0
	v_ashrrev_i32_e32 v129, 31, v128
	s_movk_i32 s0, 0xe400
	v_cndmask_b32_e64 v96, v130, v99, s[2:3]
	v_lshl_add_u64 v[100:101], v[128:129], 0, v[160:161]
	s_mov_b32 s1, -1
	v_lshrrev_b32_e32 v99, 4, v99
	v_lshl_add_u64 v[100:101], v[100:101], 0, s[0:1]
	v_mad_u64_u32 v[104:105], s[0:1], v99, s94, v[132:133]
	s_movk_i32 s0, 0x4000
	s_nop 0
	v_cmp_gt_i32_e32 vcc, s0, v130
	v_readlane_b32 s13, v231, 7
	v_readlane_b32 s14, v231, 8
	v_readlane_b32 s15, v231, 9
	v_readlane_b32 s16, v231, 10
	v_readlane_b32 s17, v231, 11
	v_readlane_b32 s18, v231, 12
	v_readlane_b32 s19, v231, 13
	v_readlane_b32 s21, v231, 15
	v_readlane_b32 s22, v231, 16
	v_readlane_b32 s23, v231, 17
	v_readlane_b32 s24, v231, 18
	v_readlane_b32 s25, v231, 19
	v_readlane_b32 s26, v231, 20
	v_readlane_b32 s27, v231, 21
	v_ashrrev_i32_e32 v97, 31, v96
	v_cndmask_b32_e32 v104, v104, v130, vcc
	s_addc_u32 s29, s21, 0
	v_lshlrev_b64 v[96:97], 8, v[96:97]
	v_ashrrev_i32_e32 v105, 31, v104
	v_readlane_b32 s12, v231, 38
	v_lshl_add_u64 v[96:97], s[28:29], 0, v[96:97]
	v_lshlrev_b64 v[102:103], 2, v[100:101]
	v_lshlrev_b64 v[104:105], 7, v[104:105]
	v_readlane_b32 s13, v231, 39
	v_lshl_add_u64 v[96:97], v[96:97], 0, v[102:103]
	v_lshlrev_b64 v[100:101], 1, v[100:101]
	v_lshl_add_u64 v[104:105], s[12:13], 0, v[104:105]
	global_store_dwordx4 v[96:97], v[92:95], off offset:64 sc1
	v_cvt_pk_bf16_f32 v96, v92, v93
	v_cvt_pk_bf16_f32 v97, v94, v95
	v_lshl_add_u64 v[104:105], v[104:105], 0, v[100:101]
	v_add_u32_e32 v99, 0xffffc010, v130
	global_store_dwordx2 v[104:105], v[96:97], off offset:32
	v_cndmask_b32_e64 v96, v146, v99, s[2:3]
	v_lshrrev_b32_e32 v99, 4, v99
	v_mad_u64_u32 v[104:105], s[0:1], v99, s94, v[132:133]
	s_movk_i32 s0, 0x3ff0
	s_nop 0
	v_cmp_gt_i32_e32 vcc, s0, v130
	v_ashrrev_i32_e32 v97, 31, v96
	v_lshlrev_b64 v[96:97], 8, v[96:97]
	v_cndmask_b32_e32 v104, v104, v146, vcc
	v_ashrrev_i32_e32 v105, 31, v104
	v_lshl_add_u64 v[96:97], s[28:29], 0, v[96:97]
	v_lshlrev_b64 v[104:105], 7, v[104:105]
	v_lshl_add_u64 v[96:97], v[96:97], 0, v[102:103]
	v_lshl_add_u64 v[104:105], s[12:13], 0, v[104:105]
	global_store_dwordx4 v[96:97], v[88:91], off offset:64 sc1
	v_cvt_pk_bf16_f32 v96, v88, v89
	v_cvt_pk_bf16_f32 v97, v90, v91
	v_lshl_add_u64 v[104:105], v[104:105], 0, v[100:101]
	v_add_u32_e32 v99, 0xffffc020, v130
	global_store_dwordx2 v[104:105], v[96:97], off offset:32
	v_cndmask_b32_e64 v96, v144, v99, s[2:3]
	v_lshrrev_b32_e32 v99, 4, v99
	v_mad_u64_u32 v[104:105], s[0:1], v99, s94, v[132:133]
	s_movk_i32 s0, 0x3fe0
	s_nop 0
	v_cmp_gt_i32_e32 vcc, s0, v130
	v_ashrrev_i32_e32 v97, 31, v96
	v_lshlrev_b64 v[96:97], 8, v[96:97]
	v_cndmask_b32_e32 v104, v104, v144, vcc
	v_ashrrev_i32_e32 v105, 31, v104
	v_lshl_add_u64 v[96:97], s[28:29], 0, v[96:97]
	v_lshlrev_b64 v[104:105], 7, v[104:105]
	v_lshl_add_u64 v[96:97], v[96:97], 0, v[102:103]
	v_lshl_add_u64 v[104:105], s[12:13], 0, v[104:105]
	global_store_dwordx4 v[96:97], v[84:87], off offset:64 sc1
	v_cvt_pk_bf16_f32 v96, v84, v85
	v_cvt_pk_bf16_f32 v97, v86, v87
	v_lshl_add_u64 v[104:105], v[104:105], 0, v[100:101]
	v_add_u32_e32 v99, 0xffffc030, v130
	global_store_dwordx2 v[104:105], v[96:97], off offset:32
	v_cndmask_b32_e64 v96, v142, v99, s[2:3]
	v_lshrrev_b32_e32 v99, 4, v99
	v_mad_u64_u32 v[104:105], s[0:1], v99, s94, v[132:133]
	s_movk_i32 s0, 0x3fd0
	s_nop 0
	v_cmp_gt_i32_e32 vcc, s0, v130
	v_ashrrev_i32_e32 v97, 31, v96
	v_lshlrev_b64 v[96:97], 8, v[96:97]
	v_cndmask_b32_e32 v104, v104, v142, vcc
	v_ashrrev_i32_e32 v105, 31, v104
	v_lshl_add_u64 v[96:97], s[28:29], 0, v[96:97]
	v_lshlrev_b64 v[104:105], 7, v[104:105]
	v_lshl_add_u64 v[96:97], v[96:97], 0, v[102:103]
; DI u32x2 pack4(f32x4 v) { u32x2 r; r[0] = cvtpk(v[0], v[1]); r[1] = cvtpk(v[2], v[3]); return r; }
; template <int EPI>
; DI void gemm_epilogue(const Params& p, f32x4 (&acc)[8][4], int m0, int n0, int wr, int wc, int fr, int fq, u16* Cb, int ldc) {
;     ...
;       } else if (colt < 7232) {
;         const int c = col - 7168;
; #pragma clang loop unroll(full)
;         for (int m = 0; m < 8; ++m) {
;           const int row = rbase + m * 16;
;           if (!smp) *(f32x4*)(p.out + O_IDXP + (size_t)row * 64 + c) = acc[m][n];
;           else *(f32x4*)(p.out + O_IDXS + (size_t)(row - MP) * 64 + c) = acc[m][n];
;           *(u32x2*)(p.IXK + (size_t)krow_of(row) * 64 + c) = pack4(acc[m][n]);
;         }
	v_lshl_add_u64 v[104:105], s[12:13], 0, v[104:105]
	global_store_dwordx4 v[96:97], v[80:83], off offset:64 sc1
	v_cvt_pk_bf16_f32 v96, v80, v81
	v_cvt_pk_bf16_f32 v97, v82, v83
	v_lshl_add_u64 v[104:105], v[104:105], 0, v[100:101]
	v_add_u32_e32 v99, 0xffffc040, v130
	global_store_dwordx2 v[104:105], v[96:97], off offset:32
	v_cndmask_b32_e64 v96, v140, v99, s[2:3]
	v_lshrrev_b32_e32 v99, 4, v99
	v_mad_u64_u32 v[104:105], s[0:1], v99, s94, v[132:133]
	s_movk_i32 s0, 0x3fc0
	s_nop 0
	v_cmp_gt_i32_e32 vcc, s0, v130
	v_ashrrev_i32_e32 v97, 31, v96
	v_lshlrev_b64 v[96:97], 8, v[96:97]
	v_cndmask_b32_e32 v104, v104, v140, vcc
	v_ashrrev_i32_e32 v105, 31, v104
	v_lshl_add_u64 v[96:97], s[28:29], 0, v[96:97]
	v_lshlrev_b64 v[104:105], 7, v[104:105]
	v_lshl_add_u64 v[96:97], v[96:97], 0, v[102:103]
	v_lshl_add_u64 v[104:105], s[12:13], 0, v[104:105]
	global_store_dwordx4 v[96:97], v[76:79], off offset:64 sc1
	v_cvt_pk_bf16_f32 v96, v76, v77
	v_cvt_pk_bf16_f32 v97, v78, v79
	v_lshl_add_u64 v[104:105], v[104:105], 0, v[100:101]
	v_add_u32_e32 v99, 0xffffc050, v130
	global_store_dwordx2 v[104:105], v[96:97], off offset:32
	v_cndmask_b32_e64 v96, v138, v99, s[2:3]
	v_lshrrev_b32_e32 v99, 4, v99
	v_mad_u64_u32 v[104:105], s[0:1], v99, s94, v[132:133]
	s_movk_i32 s0, 0x3fb0
	s_nop 0
	v_cmp_gt_i32_e32 vcc, s0, v130
	v_ashrrev_i32_e32 v97, 31, v96
	v_lshlrev_b64 v[96:97], 8, v[96:97]
	v_cndmask_b32_e32 v104, v104, v138, vcc
	v_ashrrev_i32_e32 v105, 31, v104
	v_lshl_add_u64 v[96:97], s[28:29], 0, v[96:97]
	v_lshlrev_b64 v[104:105], 7, v[104:105]
	v_lshl_add_u64 v[96:97], v[96:97], 0, v[102:103]
	v_lshl_add_u64 v[104:105], s[12:13], 0, v[104:105]
	global_store_dwordx4 v[96:97], v[72:75], off offset:64 sc1
	v_cvt_pk_bf16_f32 v96, v72, v73
	v_cvt_pk_bf16_f32 v97, v74, v75
	v_lshl_add_u64 v[104:105], v[104:105], 0, v[100:101]
	v_add_u32_e32 v99, 0xffffc060, v130
	global_store_dwordx2 v[104:105], v[96:97], off offset:32
	v_cndmask_b32_e64 v96, v136, v99, s[2:3]
	v_lshrrev_b32_e32 v99, 4, v99
	v_mad_u64_u32 v[104:105], s[0:1], v99, s94, v[132:133]
	s_movk_i32 s0, 0x3fa0
	s_nop 0
	v_cmp_gt_i32_e32 vcc, s0, v130
	v_ashrrev_i32_e32 v97, 31, v96
	v_lshlrev_b64 v[96:97], 8, v[96:97]
	v_cndmask_b32_e32 v104, v104, v136, vcc
	v_ashrrev_i32_e32 v105, 31, v104
	v_lshl_add_u64 v[96:97], s[28:29], 0, v[96:97]
	v_lshlrev_b64 v[104:105], 7, v[104:105]
	v_lshl_add_u64 v[96:97], v[96:97], 0, v[102:103]
	v_lshl_add_u64 v[104:105], s[12:13], 0, v[104:105]
	global_store_dwordx4 v[96:97], v[68:71], off offset:64 sc1
	v_cvt_pk_bf16_f32 v96, v68, v69
	v_cvt_pk_bf16_f32 v97, v70, v71
	v_lshl_add_u64 v[104:105], v[104:105], 0, v[100:101]
	v_add_u32_e32 v99, 0xffffc070, v130
	global_store_dwordx2 v[104:105], v[96:97], off offset:32
	v_cndmask_b32_e64 v96, v134, v99, s[2:3]
	v_ashrrev_i32_e32 v97, 31, v96
	v_lshlrev_b64 v[96:97], 8, v[96:97]
	v_lshl_add_u64 v[96:97], s[28:29], 0, v[96:97]
	v_lshrrev_b32_e32 v99, 4, v99
	v_lshl_add_u64 v[96:97], v[96:97], 0, v[102:103]
	v_mad_u64_u32 v[102:103], s[0:1], v99, s94, v[132:133]
	s_movk_i32 s0, 0x3f90
	s_nop 0
	v_cmp_gt_i32_e32 vcc, s0, v130
	global_store_dwordx4 v[96:97], v[64:67], off offset:64 sc1
	v_cvt_pk_bf16_f32 v96, v64, v65
	v_cndmask_b32_e32 v102, v102, v134, vcc
	v_ashrrev_i32_e32 v103, 31, v102
	v_lshlrev_b64 v[102:103], 7, v[102:103]
	v_lshl_add_u64 v[102:103], s[12:13], 0, v[102:103]
	v_cvt_pk_bf16_f32 v97, v66, v67
	v_lshl_add_u64 v[100:101], v[102:103], 0, v[100:101]
	v_readlane_b32 s14, v231, 40
	v_readlane_b32 s15, v231, 41
	v_readlane_b32 s16, v231, 42
	v_readlane_b32 s17, v231, 43
	v_readlane_b32 s18, v231, 44
	v_readlane_b32 s19, v231, 45
	v_readlane_b32 s20, v231, 46
	v_readlane_b32 s21, v231, 47
	v_readlane_b32 s22, v231, 48
	v_readlane_b32 s23, v231, 49
	v_readlane_b32 s24, v231, 50
	v_readlane_b32 s25, v231, 51
	v_readlane_b32 s26, v231, 52
	v_readlane_b32 s27, v231, 53
	global_store_dwordx2 v[100:101], v[96:97], off offset:32

; DI u16 f2bf(float x) { return (u16)(cvtpk(x, 0.f) & 0xffffu); }
; template <int EPI>
; DI void gemm_epilogue(const Params& p, f32x4 (&acc)[8][4], int m0, int n0, int wr, int wc, int fr, int fq, u16* Cb, int ldc) {
;     ...
; #pragma clang loop unroll(full)
;         for (int m = 0; m < 8; ++m) {
;           const int row = rbase + m * 16;
;           if (!smp) {
;             *(f32x4*)(p.out + O_AVP + (size_t)row * 2048 + c) = acc[m][n];
; #pragma clang loop unroll(full)
;             for (int j = 0; j < 4; ++j) p.VAT[(size_t)(c + j) * MP + row] = f2bf(acc[m][n][j]);
;           } else *(f32x4*)(p.out + O_AVS + (size_t)(row - MP) * 2048 + c) = acc[m][n];
.LBB0_1083:
	s_andn2_b64 vcc, exec, s[0:1]
	s_cbranch_vccnz .LBB0_1116
	v_or_b32_e32 v96, v98, v160
	v_add_u32_e32 v98, 0xfffff000, v96
	v_ashrrev_i32_e32 v99, 31, v98
	v_cndmask_b32_e64 v97, 0, 1, s[88:89]
	s_mov_b64 s[0:1], -1
	v_cmp_ne_u32_e64 s[4:5], 1, v97
	s_andn2_b64 vcc, exec, s[88:89]
	v_lshlrev_b64 v[98:99], 15, v[98:99]
	v_ashrrev_i32_e32 v97, 31, v96
	s_cbranch_vccnz .LBB0_1100
	v_lshlrev_b64 v[100:101], 13, v[130:131]
	v_ashrrev_i32_e32 v129, 31, v128
	v_lshl_add_u64 v[100:101], s[6:7], 0, v[100:101]
	v_lshl_add_u64 v[102:103], v[128:129], 0, v[160:161]
	v_lshl_add_u64 v[100:101], v[102:103], 2, v[100:101]
	v_add_co_u32_e32 v100, vcc, 0xffffd000, v100
	v_cvt_pk_bf16_f32 v104, v92, s0
	s_nop 0
	v_addc_co_u32_e32 v101, vcc, -1, v101, vcc
	global_store_dwordx4 v[100:101], v[92:95], off offset:-4032 sc1
	v_lshl_add_u64 v[100:101], v[130:131], 1, s[48:49]
	v_lshl_add_u64 v[102:103], v[100:101], 0, v[98:99]
	global_store_short v[102:103], v104, off
	v_lshlrev_b64 v[102:103], 15, v[96:97]
	v_lshl_add_u64 v[100:101], v[100:101], 0, v[102:103]
	v_add_co_u32_e32 v102, vcc, 0xf8008000, v100
	v_cvt_pk_bf16_f32 v104, v93, s0
	s_nop 0
	v_addc_co_u32_e32 v103, vcc, -1, v101, vcc
	global_store_short v[102:103], v104, off
	v_add_co_u32_e32 v102, vcc, 0xf8010000, v100
	v_cvt_pk_bf16_f32 v104, v94, s0
	s_nop 0
	v_addc_co_u32_e32 v103, vcc, -1, v101, vcc
	v_add_co_u32_e32 v100, vcc, 0xf8018000, v100
	global_store_short v[102:103], v104, off
	v_cvt_pk_bf16_f32 v102, v95, s0
	v_addc_co_u32_e32 v101, vcc, -1, v101, vcc
	global_store_short v[100:101], v102, off
	s_cbranch_execz .LBB0_1101

; DI u16 f2bf(float x) { return (u16)(cvtpk(x, 0.f) & 0xffffu); }
; template <int EPI>
; DI void gemm_epilogue(const Params& p, f32x4 (&acc)[8][4], int m0, int n0, int wr, int wc, int fr, int fq, u16* Cb, int ldc) {
;     ...
; #pragma clang loop unroll(full)
;         for (int m = 0; m < 8; ++m) {
;           const int row = rbase + m * 16;
;           if (!smp) {
;             *(f32x4*)(p.out + O_AVP + (size_t)row * 2048 + c) = acc[m][n];
; #pragma clang loop unroll(full)
;             for (int j = 0; j < 4; ++j) p.VAT[(size_t)(c + j) * MP + row] = f2bf(acc[m][n][j]);
;           } else *(f32x4*)(p.out + O_AVS + (size_t)(row - MP) * 2048 + c) = acc[m][n];
.LBB0_1087:
	v_lshlrev_b64 v[100:101], 13, v[146:147]
	v_ashrrev_i32_e32 v129, 31, v128
	v_lshl_add_u64 v[100:101], s[6:7], 0, v[100:101]
	v_lshl_add_u64 v[102:103], v[128:129], 0, v[160:161]
	v_lshl_add_u64 v[100:101], v[102:103], 2, v[100:101]
	v_add_co_u32_e32 v100, vcc, 0xffffd000, v100
	v_cvt_pk_bf16_f32 v104, v88, s0
	s_nop 0
	v_addc_co_u32_e32 v101, vcc, -1, v101, vcc
	global_store_dwordx4 v[100:101], v[88:91], off offset:-4032 sc1
	v_lshl_add_u64 v[100:101], v[130:131], 1, s[48:49]
	v_lshl_add_u64 v[102:103], v[100:101], 0, v[98:99]
	global_store_short v[102:103], v104, off offset:32
	v_lshlrev_b64 v[102:103], 15, v[96:97]
	v_lshl_add_u64 v[100:101], v[100:101], 0, v[102:103]
	v_add_co_u32_e32 v102, vcc, 0xf8009000, v100
	v_cvt_pk_bf16_f32 v104, v89, s0
	s_nop 0
	v_addc_co_u32_e32 v103, vcc, -1, v101, vcc
	global_store_short v[102:103], v104, off offset:-4064
	v_add_co_u32_e32 v102, vcc, 0xf8011000, v100
	v_cvt_pk_bf16_f32 v104, v90, s0
	s_nop 0
	v_addc_co_u32_e32 v103, vcc, -1, v101, vcc
	v_add_co_u32_e32 v100, vcc, 0xf8019000, v100
	global_store_short v[102:103], v104, off offset:-4064
	v_cvt_pk_bf16_f32 v102, v91, s0
	v_addc_co_u32_e32 v101, vcc, -1, v101, vcc
	global_store_short v[100:101], v102, off offset:-4064
	s_cbranch_execz .LBB0_1103

; DI u16 f2bf(float x) { return (u16)(cvtpk(x, 0.f) & 0xffffu); }
; template <int EPI>
; DI void gemm_epilogue(const Params& p, f32x4 (&acc)[8][4], int m0, int n0, int wr, int wc, int fr, int fq, u16* Cb, int ldc) {
;     ...
; #pragma clang loop unroll(full)
;         for (int m = 0; m < 8; ++m) {
;           const int row = rbase + m * 16;
;           if (!smp) {
;             *(f32x4*)(p.out + O_AVP + (size_t)row * 2048 + c) = acc[m][n];
; #pragma clang loop unroll(full)
;             for (int j = 0; j < 4; ++j) p.VAT[(size_t)(c + j) * MP + row] = f2bf(acc[m][n][j]);
;           } else *(f32x4*)(p.out + O_AVS + (size_t)(row - MP) * 2048 + c) = acc[m][n];
.LBB0_1089:
	v_lshlrev_b64 v[100:101], 13, v[144:145]
	v_ashrrev_i32_e32 v129, 31, v128
	v_lshl_add_u64 v[100:101], s[6:7], 0, v[100:101]
	v_lshl_add_u64 v[102:103], v[128:129], 0, v[160:161]
	v_lshl_add_u64 v[100:101], v[102:103], 2, v[100:101]
	v_add_co_u32_e32 v100, vcc, 0xffffd000, v100
	v_cvt_pk_bf16_f32 v104, v84, s0
	s_nop 0
	v_addc_co_u32_e32 v101, vcc, -1, v101, vcc
	global_store_dwordx4 v[100:101], v[84:87], off offset:-4032 sc1
	v_lshl_add_u64 v[100:101], v[130:131], 1, s[48:49]
	v_lshl_add_u64 v[102:103], v[100:101], 0, v[98:99]
	global_store_short v[102:103], v104, off offset:64
	v_lshlrev_b64 v[102:103], 15, v[96:97]
	v_lshl_add_u64 v[100:101], v[100:101], 0, v[102:103]
	v_add_co_u32_e32 v102, vcc, 0xf8009000, v100
	v_cvt_pk_bf16_f32 v104, v85, s0
	s_nop 0
	v_addc_co_u32_e32 v103, vcc, -1, v101, vcc
	global_store_short v[102:103], v104, off offset:-4032
	v_add_co_u32_e32 v102, vcc, 0xf8011000, v100
	v_cvt_pk_bf16_f32 v104, v86, s0
	s_nop 0
	v_addc_co_u32_e32 v103, vcc, -1, v101, vcc
	v_add_co_u32_e32 v100, vcc, 0xf8019000, v100
	global_store_short v[102:103], v104, off offset:-4032
	v_cvt_pk_bf16_f32 v102, v87, s0
	v_addc_co_u32_e32 v101, vcc, -1, v101, vcc
	global_store_short v[100:101], v102, off offset:-4032
	s_cbranch_execz .LBB0_1105

; DI u16 f2bf(float x) { return (u16)(cvtpk(x, 0.f) & 0xffffu); }
; template <int EPI>
; DI void gemm_epilogue(const Params& p, f32x4 (&acc)[8][4], int m0, int n0, int wr, int wc, int fr, int fq, u16* Cb, int ldc) {
;     ...
; #pragma clang loop unroll(full)
;         for (int m = 0; m < 8; ++m) {
;           const int row = rbase + m * 16;
;           if (!smp) {
;             *(f32x4*)(p.out + O_AVP + (size_t)row * 2048 + c) = acc[m][n];
; #pragma clang loop unroll(full)
;             for (int j = 0; j < 4; ++j) p.VAT[(size_t)(c + j) * MP + row] = f2bf(acc[m][n][j]);
;           } else *(f32x4*)(p.out + O_AVS + (size_t)(row - MP) * 2048 + c) = acc[m][n];
.LBB0_1091:
	v_lshlrev_b64 v[100:101], 13, v[142:143]
	v_ashrrev_i32_e32 v129, 31, v128
	v_lshl_add_u64 v[100:101], s[6:7], 0, v[100:101]
	v_lshl_add_u64 v[102:103], v[128:129], 0, v[160:161]
	v_lshl_add_u64 v[100:101], v[102:103], 2, v[100:101]
	v_add_co_u32_e32 v100, vcc, 0xffffd000, v100
	v_cvt_pk_bf16_f32 v104, v80, s0
	s_nop 0
	v_addc_co_u32_e32 v101, vcc, -1, v101, vcc
	global_store_dwordx4 v[100:101], v[80:83], off offset:-4032 sc1
	v_lshl_add_u64 v[100:101], v[130:131], 1, s[48:49]
	v_lshl_add_u64 v[102:103], v[100:101], 0, v[98:99]
	global_store_short v[102:103], v104, off offset:96
	v_lshlrev_b64 v[102:103], 15, v[96:97]
	v_lshl_add_u64 v[100:101], v[100:101], 0, v[102:103]
	v_add_co_u32_e32 v102, vcc, 0xf8009000, v100
	v_cvt_pk_bf16_f32 v104, v81, s0
	s_nop 0
	v_addc_co_u32_e32 v103, vcc, -1, v101, vcc
	global_store_short v[102:103], v104, off offset:-4000
	v_add_co_u32_e32 v102, vcc, 0xf8011000, v100
	v_cvt_pk_bf16_f32 v104, v82, s0
	s_nop 0
	v_addc_co_u32_e32 v103, vcc, -1, v101, vcc
	v_add_co_u32_e32 v100, vcc, 0xf8019000, v100
	global_store_short v[102:103], v104, off offset:-4000
	v_cvt_pk_bf16_f32 v102, v83, s0
	v_addc_co_u32_e32 v101, vcc, -1, v101, vcc
	global_store_short v[100:101], v102, off offset:-4000
	s_cbranch_execz .LBB0_1107

; DI u16 f2bf(float x) { return (u16)(cvtpk(x, 0.f) & 0xffffu); }
; template <int EPI>
; DI void gemm_epilogue(const Params& p, f32x4 (&acc)[8][4], int m0, int n0, int wr, int wc, int fr, int fq, u16* Cb, int ldc) {
;     ...
; #pragma clang loop unroll(full)
;         for (int m = 0; m < 8; ++m) {
;           const int row = rbase + m * 16;
;           if (!smp) {
;             *(f32x4*)(p.out + O_AVP + (size_t)row * 2048 + c) = acc[m][n];
; #pragma clang loop unroll(full)
;             for (int j = 0; j < 4; ++j) p.VAT[(size_t)(c + j) * MP + row] = f2bf(acc[m][n][j]);
;           } else *(f32x4*)(p.out + O_AVS + (size_t)(row - MP) * 2048 + c) = acc[m][n];
.LBB0_1093:
	v_lshlrev_b64 v[100:101], 13, v[140:141]
	v_ashrrev_i32_e32 v129, 31, v128
	v_lshl_add_u64 v[100:101], s[6:7], 0, v[100:101]
	v_lshl_add_u64 v[102:103], v[128:129], 0, v[160:161]
	v_lshl_add_u64 v[100:101], v[102:103], 2, v[100:101]
	v_add_co_u32_e32 v100, vcc, 0xffffd000, v100
	v_cvt_pk_bf16_f32 v104, v76, s0
	s_nop 0
	v_addc_co_u32_e32 v101, vcc, -1, v101, vcc
	global_store_dwordx4 v[100:101], v[76:79], off offset:-4032 sc1
	v_lshl_add_u64 v[100:101], v[130:131], 1, s[48:49]
	v_lshl_add_u64 v[102:103], v[100:101], 0, v[98:99]
	global_store_short v[102:103], v104, off offset:128
	v_lshlrev_b64 v[102:103], 15, v[96:97]
	v_lshl_add_u64 v[100:101], v[100:101], 0, v[102:103]
	v_add_co_u32_e32 v102, vcc, 0xf8009000, v100
	v_cvt_pk_bf16_f32 v104, v77, s0
	s_nop 0
	v_addc_co_u32_e32 v103, vcc, -1, v101, vcc
	global_store_short v[102:103], v104, off offset:-3968
	v_add_co_u32_e32 v102, vcc, 0xf8011000, v100
	v_cvt_pk_bf16_f32 v104, v78, s0
	s_nop 0
	v_addc_co_u32_e32 v103, vcc, -1, v101, vcc
	v_add_co_u32_e32 v100, vcc, 0xf8019000, v100
	global_store_short v[102:103], v104, off offset:-3968
	v_cvt_pk_bf16_f32 v102, v79, s0
	v_addc_co_u32_e32 v101, vcc, -1, v101, vcc
	global_store_short v[100:101], v102, off offset:-3968
	s_cbranch_execz .LBB0_1109

; DI u16 f2bf(float x) { return (u16)(cvtpk(x, 0.f) & 0xffffu); }
; template <int EPI>
; DI void gemm_epilogue(const Params& p, f32x4 (&acc)[8][4], int m0, int n0, int wr, int wc, int fr, int fq, u16* Cb, int ldc) {
;     ...
; #pragma clang loop unroll(full)
;         for (int m = 0; m < 8; ++m) {
;           const int row = rbase + m * 16;
;           if (!smp) {
;             *(f32x4*)(p.out + O_AVP + (size_t)row * 2048 + c) = acc[m][n];
; #pragma clang loop unroll(full)
;             for (int j = 0; j < 4; ++j) p.VAT[(size_t)(c + j) * MP + row] = f2bf(acc[m][n][j]);
;           } else *(f32x4*)(p.out + O_AVS + (size_t)(row - MP) * 2048 + c) = acc[m][n];
.LBB0_1095:
	v_lshlrev_b64 v[100:101], 13, v[138:139]
	v_ashrrev_i32_e32 v129, 31, v128
	v_lshl_add_u64 v[100:101], s[6:7], 0, v[100:101]
	v_lshl_add_u64 v[102:103], v[128:129], 0, v[160:161]
	v_lshl_add_u64 v[100:101], v[102:103], 2, v[100:101]
	v_add_co_u32_e32 v100, vcc, 0xffffd000, v100
	v_cvt_pk_bf16_f32 v104, v72, s0
	s_nop 0
	v_addc_co_u32_e32 v101, vcc, -1, v101, vcc
	global_store_dwordx4 v[100:101], v[72:75], off offset:-4032 sc1
	v_lshl_add_u64 v[100:101], v[130:131], 1, s[48:49]
	v_lshl_add_u64 v[102:103], v[100:101], 0, v[98:99]
	global_store_short v[102:103], v104, off offset:160
	v_lshlrev_b64 v[102:103], 15, v[96:97]
	v_lshl_add_u64 v[100:101], v[100:101], 0, v[102:103]
	v_add_co_u32_e32 v102, vcc, 0xf8009000, v100
	v_cvt_pk_bf16_f32 v104, v73, s0
	s_nop 0
	v_addc_co_u32_e32 v103, vcc, -1, v101, vcc
	global_store_short v[102:103], v104, off offset:-3936
	v_add_co_u32_e32 v102, vcc, 0xf8011000, v100
	v_cvt_pk_bf16_f32 v104, v74, s0
	s_nop 0
	v_addc_co_u32_e32 v103, vcc, -1, v101, vcc
	v_add_co_u32_e32 v100, vcc, 0xf8019000, v100
	global_store_short v[102:103], v104, off offset:-3936
	v_cvt_pk_bf16_f32 v102, v75, s0
	v_addc_co_u32_e32 v101, vcc, -1, v101, vcc
	global_store_short v[100:101], v102, off offset:-3936
	s_cbranch_execz .LBB0_1111

; DI u16 f2bf(float x) { return (u16)(cvtpk(x, 0.f) & 0xffffu); }
; template <int EPI>
; DI void gemm_epilogue(const Params& p, f32x4 (&acc)[8][4], int m0, int n0, int wr, int wc, int fr, int fq, u16* Cb, int ldc) {
;     ...
; #pragma clang loop unroll(full)
;         for (int m = 0; m < 8; ++m) {
;           const int row = rbase + m * 16;
;           if (!smp) {
;             *(f32x4*)(p.out + O_AVP + (size_t)row * 2048 + c) = acc[m][n];
; #pragma clang loop unroll(full)
;             for (int j = 0; j < 4; ++j) p.VAT[(size_t)(c + j) * MP + row] = f2bf(acc[m][n][j]);
;           } else *(f32x4*)(p.out + O_AVS + (size_t)(row - MP) * 2048 + c) = acc[m][n];
.LBB0_1097:
	v_lshlrev_b64 v[100:101], 13, v[136:137]
	v_ashrrev_i32_e32 v129, 31, v128
	v_lshl_add_u64 v[100:101], s[6:7], 0, v[100:101]
	v_lshl_add_u64 v[102:103], v[128:129], 0, v[160:161]
	v_lshl_add_u64 v[100:101], v[102:103], 2, v[100:101]
	v_add_co_u32_e32 v100, vcc, 0xffffd000, v100
	v_cvt_pk_bf16_f32 v104, v68, s0
	s_nop 0
	v_addc_co_u32_e32 v101, vcc, -1, v101, vcc
	global_store_dwordx4 v[100:101], v[68:71], off offset:-4032 sc1
	v_lshl_add_u64 v[100:101], v[130:131], 1, s[48:49]
	v_lshl_add_u64 v[102:103], v[100:101], 0, v[98:99]
	global_store_short v[102:103], v104, off offset:192
	v_lshlrev_b64 v[102:103], 15, v[96:97]
	v_lshl_add_u64 v[100:101], v[100:101], 0, v[102:103]
	v_add_co_u32_e32 v102, vcc, 0xf8009000, v100
	v_cvt_pk_bf16_f32 v104, v69, s0
	s_nop 0
	v_addc_co_u32_e32 v103, vcc, -1, v101, vcc
	global_store_short v[102:103], v104, off offset:-3904
	v_add_co_u32_e32 v102, vcc, 0xf8011000, v100
	v_cvt_pk_bf16_f32 v104, v70, s0
	s_nop 0
	v_addc_co_u32_e32 v103, vcc, -1, v101, vcc
	v_add_co_u32_e32 v100, vcc, 0xf8019000, v100
	global_store_short v[102:103], v104, off offset:-3904
	v_cvt_pk_bf16_f32 v102, v71, s0
	v_addc_co_u32_e32 v101, vcc, -1, v101, vcc
	global_store_short v[100:101], v102, off offset:-3904
	s_cbranch_execz .LBB0_1113

; DI u16 f2bf(float x) { return (u16)(cvtpk(x, 0.f) & 0xffffu); }
; template <int EPI>
; DI void gemm_epilogue(const Params& p, f32x4 (&acc)[8][4], int m0, int n0, int wr, int wc, int fr, int fq, u16* Cb, int ldc) {
;     ...
; #pragma clang loop unroll(full)
;         for (int m = 0; m < 8; ++m) {
;           const int row = rbase + m * 16;
;           if (!smp) {
;             *(f32x4*)(p.out + O_AVP + (size_t)row * 2048 + c) = acc[m][n];
; #pragma clang loop unroll(full)
;             for (int j = 0; j < 4; ++j) p.VAT[(size_t)(c + j) * MP + row] = f2bf(acc[m][n][j]);
;           } else *(f32x4*)(p.out + O_AVS + (size_t)(row - MP) * 2048 + c) = acc[m][n];
.LBB0_1099:
	v_lshlrev_b64 v[100:101], 13, v[134:135]
	v_ashrrev_i32_e32 v129, 31, v128
	v_lshl_add_u64 v[100:101], s[6:7], 0, v[100:101]
	v_lshl_add_u64 v[102:103], v[128:129], 0, v[160:161]
	v_lshl_add_u64 v[100:101], v[102:103], 2, v[100:101]
	v_add_co_u32_e32 v100, vcc, 0xffffd000, v100
	v_lshlrev_b64 v[96:97], 15, v[96:97]
	s_nop 0
	v_addc_co_u32_e32 v101, vcc, -1, v101, vcc
	global_store_dwordx4 v[100:101], v[64:67], off offset:-4032 sc1
	v_lshl_add_u64 v[100:101], v[130:131], 1, s[48:49]
	v_cvt_pk_bf16_f32 v102, v64, s0
	v_lshl_add_u64 v[98:99], v[100:101], 0, v[98:99]
	v_lshl_add_u64 v[96:97], v[100:101], 0, v[96:97]
	global_store_short v[98:99], v102, off offset:224
	v_add_co_u32_e32 v98, vcc, 0xf8009000, v96
	v_cvt_pk_bf16_f32 v102, v65, s0
	s_nop 0
	v_addc_co_u32_e32 v99, vcc, -1, v97, vcc
	global_store_short v[98:99], v102, off offset:-3872
	v_add_co_u32_e32 v98, vcc, 0xf8011000, v96
	v_cvt_pk_bf16_f32 v100, v66, s0
	s_nop 0
	v_addc_co_u32_e32 v99, vcc, -1, v97, vcc
	v_add_co_u32_e32 v96, vcc, 0xf8019000, v96
	global_store_short v[98:99], v100, off offset:-3872
	v_cvt_pk_bf16_f32 v98, v67, s0
	v_addc_co_u32_e32 v97, vcc, -1, v97, vcc
	global_store_short v[96:97], v98, off offset:-3872
	s_cbranch_execz .LBB0_1115
	s_branch .LBB0_1116

; DI u16 f2bf(float x) { return (u16)(cvtpk(x, 0.f) & 0xffffu); }
; template <int EPI>
; DI void gemm_epilogue(const Params& p, f32x4 (&acc)[8][4], int m0, int n0, int wr, int wc, int fr, int fq, u16* Cb, int ldc) {
;     ...
; #pragma clang loop unroll(full)
;         for (int m = 0; m < 8; ++m) {
;           const int row = rbase + m * 16;
;           if (!smp) {
;             *(f32x4*)(p.out + O_AVP + (size_t)row * 2048 + c) = acc[m][n];
; #pragma clang loop unroll(full)
;             for (int j = 0; j < 4; ++j) p.VAT[(size_t)(c + j) * MP + row] = f2bf(acc[m][n][j]);
;           } else *(f32x4*)(p.out + O_AVS + (size_t)(row - MP) * 2048 + c) = acc[m][n];
.LBB0_1101:
	v_lshlrev_b64 v[100:101], 13, v[130:131]
	v_ashrrev_i32_e32 v129, 31, v128
	v_lshl_add_u64 v[100:101], s[62:63], 0, v[100:101]
	v_lshl_add_u64 v[102:103], v[128:129], 0, v[160:161]
	v_lshl_add_u64 v[100:101], v[102:103], 2, v[100:101]
	v_add_co_u32_e32 v100, vcc, 0xf7ffd000, v100
	s_nop 1
	v_addc_co_u32_e32 v101, vcc, -1, v101, vcc
	global_store_dwordx4 v[100:101], v[92:95], off offset:-4032 sc1
	s_and_b64 vcc, exec, s[4:5]
	s_mov_b64 s[0:1], -1
	s_cbranch_vccz .LBB0_1087

; DI u16 f2bf(float x) { return (u16)(cvtpk(x, 0.f) & 0xffffu); }
; template <int EPI>
; DI void gemm_epilogue(const Params& p, f32x4 (&acc)[8][4], int m0, int n0, int wr, int wc, int fr, int fq, u16* Cb, int ldc) {
;     ...
; #pragma clang loop unroll(full)
;         for (int m = 0; m < 8; ++m) {
;           const int row = rbase + m * 16;
;           if (!smp) {
;             *(f32x4*)(p.out + O_AVP + (size_t)row * 2048 + c) = acc[m][n];
; #pragma clang loop unroll(full)
;             for (int j = 0; j < 4; ++j) p.VAT[(size_t)(c + j) * MP + row] = f2bf(acc[m][n][j]);
;           } else *(f32x4*)(p.out + O_AVS + (size_t)(row - MP) * 2048 + c) = acc[m][n];
.LBB0_1103:
	v_lshlrev_b64 v[100:101], 13, v[130:131]
	v_ashrrev_i32_e32 v129, 31, v128
	v_lshl_add_u64 v[100:101], s[62:63], 0, v[100:101]
	v_lshl_add_u64 v[102:103], v[128:129], 0, v[160:161]
	v_lshl_add_u64 v[100:101], v[102:103], 2, v[100:101]
	v_add_co_u32_e32 v100, vcc, 0xf801d000, v100
	s_nop 1
	v_addc_co_u32_e32 v101, vcc, -1, v101, vcc
	global_store_dwordx4 v[100:101], v[88:91], off offset:-4032 sc1
	s_and_b64 vcc, exec, s[4:5]
	s_mov_b64 s[0:1], -1
	s_cbranch_vccz .LBB0_1089

; DI u16 f2bf(float x) { return (u16)(cvtpk(x, 0.f) & 0xffffu); }
; template <int EPI>
; DI void gemm_epilogue(const Params& p, f32x4 (&acc)[8][4], int m0, int n0, int wr, int wc, int fr, int fq, u16* Cb, int ldc) {
;     ...
; #pragma clang loop unroll(full)
;         for (int m = 0; m < 8; ++m) {
;           const int row = rbase + m * 16;
;           if (!smp) {
;             *(f32x4*)(p.out + O_AVP + (size_t)row * 2048 + c) = acc[m][n];
; #pragma clang loop unroll(full)
;             for (int j = 0; j < 4; ++j) p.VAT[(size_t)(c + j) * MP + row] = f2bf(acc[m][n][j]);
;           } else *(f32x4*)(p.out + O_AVS + (size_t)(row - MP) * 2048 + c) = acc[m][n];
.LBB0_1105:
	v_lshlrev_b64 v[100:101], 13, v[130:131]
	v_ashrrev_i32_e32 v129, 31, v128
	v_lshl_add_u64 v[100:101], s[62:63], 0, v[100:101]
	v_lshl_add_u64 v[102:103], v[128:129], 0, v[160:161]
	v_lshl_add_u64 v[100:101], v[102:103], 2, v[100:101]
	v_add_co_u32_e32 v100, vcc, 0xf803d000, v100
	s_nop 1
	v_addc_co_u32_e32 v101, vcc, -1, v101, vcc
	global_store_dwordx4 v[100:101], v[84:87], off offset:-4032 sc1
	s_and_b64 vcc, exec, s[4:5]
	s_mov_b64 s[0:1], -1
	s_cbranch_vccz .LBB0_1091

; DI u16 f2bf(float x) { return (u16)(cvtpk(x, 0.f) & 0xffffu); }
; template <int EPI>
; DI void gemm_epilogue(const Params& p, f32x4 (&acc)[8][4], int m0, int n0, int wr, int wc, int fr, int fq, u16* Cb, int ldc) {
;     ...
; #pragma clang loop unroll(full)
;         for (int m = 0; m < 8; ++m) {
;           const int row = rbase + m * 16;
;           if (!smp) {
;             *(f32x4*)(p.out + O_AVP + (size_t)row * 2048 + c) = acc[m][n];
; #pragma clang loop unroll(full)
;             for (int j = 0; j < 4; ++j) p.VAT[(size_t)(c + j) * MP + row] = f2bf(acc[m][n][j]);
;           } else *(f32x4*)(p.out + O_AVS + (size_t)(row - MP) * 2048 + c) = acc[m][n];
.LBB0_1107:
	v_lshlrev_b64 v[100:101], 13, v[130:131]
	v_ashrrev_i32_e32 v129, 31, v128
	v_lshl_add_u64 v[100:101], s[62:63], 0, v[100:101]
	v_lshl_add_u64 v[102:103], v[128:129], 0, v[160:161]
	v_lshl_add_u64 v[100:101], v[102:103], 2, v[100:101]
	v_add_co_u32_e32 v100, vcc, 0xf805d000, v100
	s_nop 1
	v_addc_co_u32_e32 v101, vcc, -1, v101, vcc
	global_store_dwordx4 v[100:101], v[80:83], off offset:-4032 sc1
	s_and_b64 vcc, exec, s[4:5]
	s_mov_b64 s[0:1], -1
	s_cbranch_vccz .LBB0_1093

; DI u16 f2bf(float x) { return (u16)(cvtpk(x, 0.f) & 0xffffu); }
; template <int EPI>
; DI void gemm_epilogue(const Params& p, f32x4 (&acc)[8][4], int m0, int n0, int wr, int wc, int fr, int fq, u16* Cb, int ldc) {
;     ...
; #pragma clang loop unroll(full)
;         for (int m = 0; m < 8; ++m) {
;           const int row = rbase + m * 16;
;           if (!smp) {
;             *(f32x4*)(p.out + O_AVP + (size_t)row * 2048 + c) = acc[m][n];
; #pragma clang loop unroll(full)
;             for (int j = 0; j < 4; ++j) p.VAT[(size_t)(c + j) * MP + row] = f2bf(acc[m][n][j]);
;           } else *(f32x4*)(p.out + O_AVS + (size_t)(row - MP) * 2048 + c) = acc[m][n];
.LBB0_1109:
	v_lshlrev_b64 v[100:101], 13, v[130:131]
	v_ashrrev_i32_e32 v129, 31, v128
	v_lshl_add_u64 v[100:101], s[62:63], 0, v[100:101]
	v_lshl_add_u64 v[102:103], v[128:129], 0, v[160:161]
	v_lshl_add_u64 v[100:101], v[102:103], 2, v[100:101]
	v_add_co_u32_e32 v100, vcc, 0xf807d000, v100
	s_nop 1
	v_addc_co_u32_e32 v101, vcc, -1, v101, vcc
	global_store_dwordx4 v[100:101], v[76:79], off offset:-4032 sc1
	s_and_b64 vcc, exec, s[4:5]
	s_mov_b64 s[0:1], -1
	s_cbranch_vccz .LBB0_1095

; DI u16 f2bf(float x) { return (u16)(cvtpk(x, 0.f) & 0xffffu); }
; template <int EPI>
; DI void gemm_epilogue(const Params& p, f32x4 (&acc)[8][4], int m0, int n0, int wr, int wc, int fr, int fq, u16* Cb, int ldc) {
;     ...
; #pragma clang loop unroll(full)
;         for (int m = 0; m < 8; ++m) {
;           const int row = rbase + m * 16;
;           if (!smp) {
;             *(f32x4*)(p.out + O_AVP + (size_t)row * 2048 + c) = acc[m][n];
; #pragma clang loop unroll(full)
;             for (int j = 0; j < 4; ++j) p.VAT[(size_t)(c + j) * MP + row] = f2bf(acc[m][n][j]);
;           } else *(f32x4*)(p.out + O_AVS + (size_t)(row - MP) * 2048 + c) = acc[m][n];
.LBB0_1111:
	v_lshlrev_b64 v[100:101], 13, v[130:131]
	v_ashrrev_i32_e32 v129, 31, v128
	v_lshl_add_u64 v[100:101], s[62:63], 0, v[100:101]
	v_lshl_add_u64 v[102:103], v[128:129], 0, v[160:161]
	v_lshl_add_u64 v[100:101], v[102:103], 2, v[100:101]
	v_add_co_u32_e32 v100, vcc, 0xf809d000, v100
	s_nop 1
	v_addc_co_u32_e32 v101, vcc, -1, v101, vcc
	global_store_dwordx4 v[100:101], v[72:75], off offset:-4032 sc1
	s_and_b64 vcc, exec, s[4:5]
	s_mov_b64 s[0:1], -1
	s_cbranch_vccz .LBB0_1097

; DI u16 f2bf(float x) { return (u16)(cvtpk(x, 0.f) & 0xffffu); }
; template <int EPI>
; DI void gemm_epilogue(const Params& p, f32x4 (&acc)[8][4], int m0, int n0, int wr, int wc, int fr, int fq, u16* Cb, int ldc) {
;     ...
; #pragma clang loop unroll(full)
;         for (int m = 0; m < 8; ++m) {
;           const int row = rbase + m * 16;
;           if (!smp) {
;             *(f32x4*)(p.out + O_AVP + (size_t)row * 2048 + c) = acc[m][n];
; #pragma clang loop unroll(full)
;             for (int j = 0; j < 4; ++j) p.VAT[(size_t)(c + j) * MP + row] = f2bf(acc[m][n][j]);
;           } else *(f32x4*)(p.out + O_AVS + (size_t)(row - MP) * 2048 + c) = acc[m][n];
.LBB0_1113:
	v_lshlrev_b64 v[100:101], 13, v[130:131]
	v_ashrrev_i32_e32 v129, 31, v128
	v_lshl_add_u64 v[100:101], s[62:63], 0, v[100:101]
	v_lshl_add_u64 v[102:103], v[128:129], 0, v[160:161]
	v_lshl_add_u64 v[100:101], v[102:103], 2, v[100:101]
	v_add_co_u32_e32 v100, vcc, 0xf80bd000, v100
	s_nop 1
	v_addc_co_u32_e32 v101, vcc, -1, v101, vcc
	global_store_dwordx4 v[100:101], v[68:71], off offset:-4032 sc1
	s_and_b64 vcc, exec, s[4:5]
	s_mov_b64 s[0:1], -1
	s_cbranch_vccz .LBB0_1099

; DI u16 f2bf(float x) { return (u16)(cvtpk(x, 0.f) & 0xffffu); }
; template <int EPI>
; DI void gemm_epilogue(const Params& p, f32x4 (&acc)[8][4], int m0, int n0, int wr, int wc, int fr, int fq, u16* Cb, int ldc) {
;     ...
; #pragma clang loop unroll(full)
;         for (int m = 0; m < 8; ++m) {
;           const int row = rbase + m * 16;
;           if (!smp) {
;             *(f32x4*)(p.out + O_AVP + (size_t)row * 2048 + c) = acc[m][n];
; #pragma clang loop unroll(full)
;             for (int j = 0; j < 4; ++j) p.VAT[(size_t)(c + j) * MP + row] = f2bf(acc[m][n][j]);
;           } else *(f32x4*)(p.out + O_AVS + (size_t)(row - MP) * 2048 + c) = acc[m][n];
.LBB0_1115:
	v_lshlrev_b64 v[96:97], 13, v[130:131]
	v_ashrrev_i32_e32 v129, 31, v128
	v_lshl_add_u64 v[96:97], s[62:63], 0, v[96:97]
	v_lshl_add_u64 v[98:99], v[128:129], 0, v[160:161]
	v_lshl_add_u64 v[96:97], v[98:99], 2, v[96:97]
	v_add_co_u32_e32 v96, vcc, 0xf80dd000, v96
	s_nop 1
	v_addc_co_u32_e32 v97, vcc, -1, v97, vcc
	global_store_dwordx4 v[96:97], v[64:67], off offset:-4032 sc1

; DI u32x2 pack4(f32x4 v) { u32x2 r; r[0] = cvtpk(v[0], v[1]); r[1] = cvtpk(v[2], v[3]); return r; }
; template <int EPI>
; DI void gemm_epilogue(const Params& p, f32x4 (&acc)[8][4], int m0, int n0, int wr, int wc, int fr, int fq, u16* Cb, int ldc) {
;     ...
;         for (int m = 0; m < 8; ++m) {
;           const int row = rbase + m * 16;
;           if (!smp) { *(f32x4*)(p.out + O_AKP + (size_t)row * 2048 + c) = acc[m][n]; *(u32x2*)(p.KA + (size_t)row * 2048 + c) = pack4(acc[m][n]); }
;           else *(f32x4*)(p.out + O_AKS + (size_t)(row - MP) * 2048 + c) = acc[m][n];
;         }
.LBB0_1117:
	s_andn2_b64 vcc, exec, s[0:1]
	s_cbranch_vccnz .LBB0_1150
	v_cndmask_b32_e64 v96, 0, 1, s[88:89]
	v_cmp_ne_u32_e64 s[4:5], 1, v96
	s_andn2_b64 vcc, exec, s[88:89]
	s_mov_b64 s[0:1], -1
	s_cbranch_vccnz .LBB0_1134
	v_ashrrev_i32_e32 v129, 31, v128
	v_lshlrev_b64 v[96:97], 13, v[130:131]
	v_lshl_add_u64 v[98:99], v[128:129], 0, v[160:161]
	v_lshl_add_u64 v[96:97], s[8:9], 0, v[96:97]
	v_lshl_add_u64 v[98:99], v[98:99], 0, s[96:97]
	v_lshlrev_b64 v[100:101], 12, v[130:131]
	v_lshl_add_u64 v[96:97], v[98:99], 2, v[96:97]
	v_lshl_add_u64 v[100:101], s[46:47], 0, v[100:101]
	global_store_dwordx4 v[96:97], v[92:95], off offset:64 sc1
	v_cvt_pk_bf16_f32 v96, v92, v93
	v_cvt_pk_bf16_f32 v97, v94, v95
	v_lshl_add_u64 v[98:99], v[98:99], 1, v[100:101]
	global_store_dwordx2 v[98:99], v[96:97], off offset:32
	s_cbranch_execz .LBB0_1135

; DI u32x2 pack4(f32x4 v) { u32x2 r; r[0] = cvtpk(v[0], v[1]); r[1] = cvtpk(v[2], v[3]); return r; }
; template <int EPI>
; DI void gemm_epilogue(const Params& p, f32x4 (&acc)[8][4], int m0, int n0, int wr, int wc, int fr, int fq, u16* Cb, int ldc) {
;     ...
;         for (int m = 0; m < 8; ++m) {
;           const int row = rbase + m * 16;
;           if (!smp) { *(f32x4*)(p.out + O_AKP + (size_t)row * 2048 + c) = acc[m][n]; *(u32x2*)(p.KA + (size_t)row * 2048 + c) = pack4(acc[m][n]); }
;           else *(f32x4*)(p.out + O_AKS + (size_t)(row - MP) * 2048 + c) = acc[m][n];
;         }
.LBB0_1121:
	v_ashrrev_i32_e32 v129, 31, v128
	v_lshlrev_b64 v[96:97], 13, v[146:147]
	v_lshl_add_u64 v[98:99], v[128:129], 0, v[160:161]
	v_lshl_add_u64 v[96:97], s[8:9], 0, v[96:97]
	v_lshl_add_u64 v[98:99], v[98:99], 0, s[96:97]
	v_lshlrev_b64 v[100:101], 12, v[146:147]
	v_lshl_add_u64 v[96:97], v[98:99], 2, v[96:97]
	v_lshl_add_u64 v[100:101], s[46:47], 0, v[100:101]
	global_store_dwordx4 v[96:97], v[88:91], off offset:64 sc1
	v_cvt_pk_bf16_f32 v96, v88, v89
	v_cvt_pk_bf16_f32 v97, v90, v91
	v_lshl_add_u64 v[98:99], v[98:99], 1, v[100:101]
	global_store_dwordx2 v[98:99], v[96:97], off offset:32
	s_cbranch_execz .LBB0_1137

; DI u32x2 pack4(f32x4 v) { u32x2 r; r[0] = cvtpk(v[0], v[1]); r[1] = cvtpk(v[2], v[3]); return r; }
; template <int EPI>
; DI void gemm_epilogue(const Params& p, f32x4 (&acc)[8][4], int m0, int n0, int wr, int wc, int fr, int fq, u16* Cb, int ldc) {
;     ...
;         for (int m = 0; m < 8; ++m) {
;           const int row = rbase + m * 16;
;           if (!smp) { *(f32x4*)(p.out + O_AKP + (size_t)row * 2048 + c) = acc[m][n]; *(u32x2*)(p.KA + (size_t)row * 2048 + c) = pack4(acc[m][n]); }
;           else *(f32x4*)(p.out + O_AKS + (size_t)(row - MP) * 2048 + c) = acc[m][n];
;         }
.LBB0_1123:
	v_ashrrev_i32_e32 v129, 31, v128
	v_lshlrev_b64 v[96:97], 13, v[144:145]
	v_lshl_add_u64 v[98:99], v[128:129], 0, v[160:161]
	v_lshl_add_u64 v[96:97], s[8:9], 0, v[96:97]
	v_lshl_add_u64 v[98:99], v[98:99], 0, s[96:97]
	v_lshlrev_b64 v[100:101], 12, v[144:145]
	v_lshl_add_u64 v[96:97], v[98:99], 2, v[96:97]
	v_lshl_add_u64 v[100:101], s[46:47], 0, v[100:101]
	global_store_dwordx4 v[96:97], v[84:87], off offset:64 sc1
	v_cvt_pk_bf16_f32 v96, v84, v85
	v_cvt_pk_bf16_f32 v97, v86, v87
	v_lshl_add_u64 v[98:99], v[98:99], 1, v[100:101]
	global_store_dwordx2 v[98:99], v[96:97], off offset:32
	s_cbranch_execz .LBB0_1139

; DI u32x2 pack4(f32x4 v) { u32x2 r; r[0] = cvtpk(v[0], v[1]); r[1] = cvtpk(v[2], v[3]); return r; }
; template <int EPI>
; DI void gemm_epilogue(const Params& p, f32x4 (&acc)[8][4], int m0, int n0, int wr, int wc, int fr, int fq, u16* Cb, int ldc) {
;     ...
;         for (int m = 0; m < 8; ++m) {
;           const int row = rbase + m * 16;
;           if (!smp) { *(f32x4*)(p.out + O_AKP + (size_t)row * 2048 + c) = acc[m][n]; *(u32x2*)(p.KA + (size_t)row * 2048 + c) = pack4(acc[m][n]); }
;           else *(f32x4*)(p.out + O_AKS + (size_t)(row - MP) * 2048 + c) = acc[m][n];
;         }
.LBB0_1125:
	v_ashrrev_i32_e32 v129, 31, v128
	v_lshlrev_b64 v[96:97], 13, v[142:143]
	v_lshl_add_u64 v[98:99], v[128:129], 0, v[160:161]
	v_lshl_add_u64 v[96:97], s[8:9], 0, v[96:97]
	v_lshl_add_u64 v[98:99], v[98:99], 0, s[96:97]
	v_lshlrev_b64 v[100:101], 12, v[142:143]
	v_lshl_add_u64 v[96:97], v[98:99], 2, v[96:97]
	v_lshl_add_u64 v[100:101], s[46:47], 0, v[100:101]
	global_store_dwordx4 v[96:97], v[80:83], off offset:64 sc1
	v_cvt_pk_bf16_f32 v96, v80, v81
	v_cvt_pk_bf16_f32 v97, v82, v83
	v_lshl_add_u64 v[98:99], v[98:99], 1, v[100:101]
	global_store_dwordx2 v[98:99], v[96:97], off offset:32
	s_cbranch_execz .LBB0_1141

; DI u32x2 pack4(f32x4 v) { u32x2 r; r[0] = cvtpk(v[0], v[1]); r[1] = cvtpk(v[2], v[3]); return r; }
; template <int EPI>
; DI void gemm_epilogue(const Params& p, f32x4 (&acc)[8][4], int m0, int n0, int wr, int wc, int fr, int fq, u16* Cb, int ldc) {
;     ...
;         for (int m = 0; m < 8; ++m) {
;           const int row = rbase + m * 16;
;           if (!smp) { *(f32x4*)(p.out + O_AKP + (size_t)row * 2048 + c) = acc[m][n]; *(u32x2*)(p.KA + (size_t)row * 2048 + c) = pack4(acc[m][n]); }
;           else *(f32x4*)(p.out + O_AKS + (size_t)(row - MP) * 2048 + c) = acc[m][n];
;         }
.LBB0_1127:
	v_ashrrev_i32_e32 v129, 31, v128
	v_lshlrev_b64 v[96:97], 13, v[140:141]
	v_lshl_add_u64 v[98:99], v[128:129], 0, v[160:161]
	v_lshl_add_u64 v[96:97], s[8:9], 0, v[96:97]
	v_lshl_add_u64 v[98:99], v[98:99], 0, s[96:97]
	v_lshlrev_b64 v[100:101], 12, v[140:141]
	v_lshl_add_u64 v[96:97], v[98:99], 2, v[96:97]
	v_lshl_add_u64 v[100:101], s[46:47], 0, v[100:101]
	global_store_dwordx4 v[96:97], v[76:79], off offset:64 sc1
	v_cvt_pk_bf16_f32 v96, v76, v77
	v_cvt_pk_bf16_f32 v97, v78, v79
	v_lshl_add_u64 v[98:99], v[98:99], 1, v[100:101]
	global_store_dwordx2 v[98:99], v[96:97], off offset:32
	s_cbranch_execz .LBB0_1143

; DI u32x2 pack4(f32x4 v) { u32x2 r; r[0] = cvtpk(v[0], v[1]); r[1] = cvtpk(v[2], v[3]); return r; }
; template <int EPI>
; DI void gemm_epilogue(const Params& p, f32x4 (&acc)[8][4], int m0, int n0, int wr, int wc, int fr, int fq, u16* Cb, int ldc) {
;     ...
;         for (int m = 0; m < 8; ++m) {
;           const int row = rbase + m * 16;
;           if (!smp) { *(f32x4*)(p.out + O_AKP + (size_t)row * 2048 + c) = acc[m][n]; *(u32x2*)(p.KA + (size_t)row * 2048 + c) = pack4(acc[m][n]); }
;           else *(f32x4*)(p.out + O_AKS + (size_t)(row - MP) * 2048 + c) = acc[m][n];
;         }
.LBB0_1129:
	v_ashrrev_i32_e32 v129, 31, v128
	v_lshlrev_b64 v[96:97], 13, v[138:139]
	v_lshl_add_u64 v[98:99], v[128:129], 0, v[160:161]
	v_lshl_add_u64 v[96:97], s[8:9], 0, v[96:97]
	v_lshl_add_u64 v[98:99], v[98:99], 0, s[96:97]
	v_lshlrev_b64 v[100:101], 12, v[138:139]
	v_lshl_add_u64 v[96:97], v[98:99], 2, v[96:97]
	v_lshl_add_u64 v[100:101], s[46:47], 0, v[100:101]
	global_store_dwordx4 v[96:97], v[72:75], off offset:64 sc1
	v_cvt_pk_bf16_f32 v96, v72, v73
	v_cvt_pk_bf16_f32 v97, v74, v75
	v_lshl_add_u64 v[98:99], v[98:99], 1, v[100:101]
	global_store_dwordx2 v[98:99], v[96:97], off offset:32
	s_cbranch_execz .LBB0_1145

; DI u32x2 pack4(f32x4 v) { u32x2 r; r[0] = cvtpk(v[0], v[1]); r[1] = cvtpk(v[2], v[3]); return r; }
; template <int EPI>
; DI void gemm_epilogue(const Params& p, f32x4 (&acc)[8][4], int m0, int n0, int wr, int wc, int fr, int fq, u16* Cb, int ldc) {
;     ...
;         for (int m = 0; m < 8; ++m) {
;           const int row = rbase + m * 16;
;           if (!smp) { *(f32x4*)(p.out + O_AKP + (size_t)row * 2048 + c) = acc[m][n]; *(u32x2*)(p.KA + (size_t)row * 2048 + c) = pack4(acc[m][n]); }
;           else *(f32x4*)(p.out + O_AKS + (size_t)(row - MP) * 2048 + c) = acc[m][n];
;         }
.LBB0_1131:
	v_ashrrev_i32_e32 v129, 31, v128
	v_lshlrev_b64 v[96:97], 13, v[136:137]
	v_lshl_add_u64 v[98:99], v[128:129], 0, v[160:161]
	v_lshl_add_u64 v[96:97], s[8:9], 0, v[96:97]
	v_lshl_add_u64 v[98:99], v[98:99], 0, s[96:97]
	v_lshlrev_b64 v[100:101], 12, v[136:137]
	v_lshl_add_u64 v[96:97], v[98:99], 2, v[96:97]
	v_lshl_add_u64 v[100:101], s[46:47], 0, v[100:101]
	global_store_dwordx4 v[96:97], v[68:71], off offset:64 sc1
	v_cvt_pk_bf16_f32 v96, v68, v69
	v_cvt_pk_bf16_f32 v97, v70, v71
	v_lshl_add_u64 v[98:99], v[98:99], 1, v[100:101]
	global_store_dwordx2 v[98:99], v[96:97], off offset:32
	s_cbranch_execz .LBB0_1147

; DI u32x2 pack4(f32x4 v) { u32x2 r; r[0] = cvtpk(v[0], v[1]); r[1] = cvtpk(v[2], v[3]); return r; }
; template <int EPI>
; DI void gemm_epilogue(const Params& p, f32x4 (&acc)[8][4], int m0, int n0, int wr, int wc, int fr, int fq, u16* Cb, int ldc) {
;     ...
;         for (int m = 0; m < 8; ++m) {
;           const int row = rbase + m * 16;
;           if (!smp) { *(f32x4*)(p.out + O_AKP + (size_t)row * 2048 + c) = acc[m][n]; *(u32x2*)(p.KA + (size_t)row * 2048 + c) = pack4(acc[m][n]); }
;           else *(f32x4*)(p.out + O_AKS + (size_t)(row - MP) * 2048 + c) = acc[m][n];
;         }
.LBB0_1133:
	v_ashrrev_i32_e32 v129, 31, v128
	v_lshlrev_b64 v[96:97], 13, v[134:135]
	v_lshl_add_u64 v[98:99], v[128:129], 0, v[160:161]
	v_lshl_add_u64 v[96:97], s[8:9], 0, v[96:97]
	v_lshl_add_u64 v[98:99], v[98:99], 0, s[96:97]
	v_lshlrev_b64 v[100:101], 12, v[134:135]
	v_lshl_add_u64 v[96:97], v[98:99], 2, v[96:97]
	v_lshl_add_u64 v[100:101], s[46:47], 0, v[100:101]
	global_store_dwordx4 v[96:97], v[64:67], off offset:64 sc1
	v_cvt_pk_bf16_f32 v96, v64, v65
	v_cvt_pk_bf16_f32 v97, v66, v67
	v_lshl_add_u64 v[98:99], v[98:99], 1, v[100:101]
	global_store_dwordx2 v[98:99], v[96:97], off offset:32
	s_cbranch_execz .LBB0_1149
	s_branch .LBB0_1150

; DI u32x2 pack4(f32x4 v) { u32x2 r; r[0] = cvtpk(v[0], v[1]); r[1] = cvtpk(v[2], v[3]); return r; }
; template <int EPI>
; DI void gemm_epilogue(const Params& p, f32x4 (&acc)[8][4], int m0, int n0, int wr, int wc, int fr, int fq, u16* Cb, int ldc) {
;     ...
;         for (int m = 0; m < 8; ++m) {
;           const int row = rbase + m * 16;
;           if (!smp) { *(f32x4*)(p.out + O_AKP + (size_t)row * 2048 + c) = acc[m][n]; *(u32x2*)(p.KA + (size_t)row * 2048 + c) = pack4(acc[m][n]); }
;           else *(f32x4*)(p.out + O_AKS + (size_t)(row - MP) * 2048 + c) = acc[m][n];
;         }
.LBB0_1135:
	v_lshlrev_b64 v[96:97], 13, v[130:131]
	v_ashrrev_i32_e32 v129, 31, v128
	v_lshl_add_u64 v[96:97], s[64:65], 0, v[96:97]
	v_lshl_add_u64 v[98:99], v[128:129], 0, v[160:161]
	v_lshl_add_u64 v[96:97], v[98:99], 2, v[96:97]
	v_add_co_u32_e32 v96, vcc, 0xf7fff000, v96
	s_nop 1
	v_addc_co_u32_e32 v97, vcc, -1, v97, vcc
	global_store_dwordx4 v[96:97], v[92:95], off offset:-4032 sc1
	s_and_b64 vcc, exec, s[4:5]
	s_mov_b64 s[0:1], -1
	s_cbranch_vccz .LBB0_1121

; DI u32x2 pack4(f32x4 v) { u32x2 r; r[0] = cvtpk(v[0], v[1]); r[1] = cvtpk(v[2], v[3]); return r; }
; template <int EPI>
; DI void gemm_epilogue(const Params& p, f32x4 (&acc)[8][4], int m0, int n0, int wr, int wc, int fr, int fq, u16* Cb, int ldc) {
;     ...
;         for (int m = 0; m < 8; ++m) {
;           const int row = rbase + m * 16;
;           if (!smp) { *(f32x4*)(p.out + O_AKP + (size_t)row * 2048 + c) = acc[m][n]; *(u32x2*)(p.KA + (size_t)row * 2048 + c) = pack4(acc[m][n]); }
;           else *(f32x4*)(p.out + O_AKS + (size_t)(row - MP) * 2048 + c) = acc[m][n];
;         }
.LBB0_1137:
	v_lshlrev_b64 v[96:97], 13, v[130:131]
	v_ashrrev_i32_e32 v129, 31, v128
	v_lshl_add_u64 v[96:97], s[64:65], 0, v[96:97]
	v_lshl_add_u64 v[98:99], v[128:129], 0, v[160:161]
	v_lshl_add_u64 v[96:97], v[98:99], 2, v[96:97]
	v_add_co_u32_e32 v96, vcc, 0xf801f000, v96
	s_nop 1
	v_addc_co_u32_e32 v97, vcc, -1, v97, vcc
	global_store_dwordx4 v[96:97], v[88:91], off offset:-4032 sc1
	s_and_b64 vcc, exec, s[4:5]
	s_mov_b64 s[0:1], -1
	s_cbranch_vccz .LBB0_1123

; DI u32x2 pack4(f32x4 v) { u32x2 r; r[0] = cvtpk(v[0], v[1]); r[1] = cvtpk(v[2], v[3]); return r; }
; template <int EPI>
; DI void gemm_epilogue(const Params& p, f32x4 (&acc)[8][4], int m0, int n0, int wr, int wc, int fr, int fq, u16* Cb, int ldc) {
;     ...
;         for (int m = 0; m < 8; ++m) {
;           const int row = rbase + m * 16;
;           if (!smp) { *(f32x4*)(p.out + O_AKP + (size_t)row * 2048 + c) = acc[m][n]; *(u32x2*)(p.KA + (size_t)row * 2048 + c) = pack4(acc[m][n]); }
;           else *(f32x4*)(p.out + O_AKS + (size_t)(row - MP) * 2048 + c) = acc[m][n];
;         }
.LBB0_1139:
	v_lshlrev_b64 v[96:97], 13, v[130:131]
	v_ashrrev_i32_e32 v129, 31, v128
	v_lshl_add_u64 v[96:97], s[64:65], 0, v[96:97]
	v_lshl_add_u64 v[98:99], v[128:129], 0, v[160:161]
	v_lshl_add_u64 v[96:97], v[98:99], 2, v[96:97]
	v_add_co_u32_e32 v96, vcc, 0xf803f000, v96
	s_nop 1
	v_addc_co_u32_e32 v97, vcc, -1, v97, vcc
	global_store_dwordx4 v[96:97], v[84:87], off offset:-4032 sc1
	s_and_b64 vcc, exec, s[4:5]
	s_mov_b64 s[0:1], -1
	s_cbranch_vccz .LBB0_1125

; DI u32x2 pack4(f32x4 v) { u32x2 r; r[0] = cvtpk(v[0], v[1]); r[1] = cvtpk(v[2], v[3]); return r; }
; template <int EPI>
; DI void gemm_epilogue(const Params& p, f32x4 (&acc)[8][4], int m0, int n0, int wr, int wc, int fr, int fq, u16* Cb, int ldc) {
;     ...
;         for (int m = 0; m < 8; ++m) {
;           const int row = rbase + m * 16;
;           if (!smp) { *(f32x4*)(p.out + O_AKP + (size_t)row * 2048 + c) = acc[m][n]; *(u32x2*)(p.KA + (size_t)row * 2048 + c) = pack4(acc[m][n]); }
;           else *(f32x4*)(p.out + O_AKS + (size_t)(row - MP) * 2048 + c) = acc[m][n];
;         }
.LBB0_1141:
	v_lshlrev_b64 v[96:97], 13, v[130:131]
	v_ashrrev_i32_e32 v129, 31, v128
	v_lshl_add_u64 v[96:97], s[64:65], 0, v[96:97]
	v_lshl_add_u64 v[98:99], v[128:129], 0, v[160:161]
	v_lshl_add_u64 v[96:97], v[98:99], 2, v[96:97]
	v_add_co_u32_e32 v96, vcc, 0xf805f000, v96
	s_nop 1
	v_addc_co_u32_e32 v97, vcc, -1, v97, vcc
	global_store_dwordx4 v[96:97], v[80:83], off offset:-4032 sc1
	s_and_b64 vcc, exec, s[4:5]
	s_mov_b64 s[0:1], -1
	s_cbranch_vccz .LBB0_1127

; DI u32x2 pack4(f32x4 v) { u32x2 r; r[0] = cvtpk(v[0], v[1]); r[1] = cvtpk(v[2], v[3]); return r; }
; template <int EPI>
; DI void gemm_epilogue(const Params& p, f32x4 (&acc)[8][4], int m0, int n0, int wr, int wc, int fr, int fq, u16* Cb, int ldc) {
;     ...
;         for (int m = 0; m < 8; ++m) {
;           const int row = rbase + m * 16;
;           if (!smp) { *(f32x4*)(p.out + O_AKP + (size_t)row * 2048 + c) = acc[m][n]; *(u32x2*)(p.KA + (size_t)row * 2048 + c) = pack4(acc[m][n]); }
;           else *(f32x4*)(p.out + O_AKS + (size_t)(row - MP) * 2048 + c) = acc[m][n];
;         }
.LBB0_1143:
	v_lshlrev_b64 v[96:97], 13, v[130:131]
	v_ashrrev_i32_e32 v129, 31, v128
	v_lshl_add_u64 v[96:97], s[64:65], 0, v[96:97]
	v_lshl_add_u64 v[98:99], v[128:129], 0, v[160:161]
	v_lshl_add_u64 v[96:97], v[98:99], 2, v[96:97]
	v_add_co_u32_e32 v96, vcc, 0xf807f000, v96
	s_nop 1
	v_addc_co_u32_e32 v97, vcc, -1, v97, vcc
	global_store_dwordx4 v[96:97], v[76:79], off offset:-4032 sc1
	s_and_b64 vcc, exec, s[4:5]
	s_mov_b64 s[0:1], -1
	s_cbranch_vccz .LBB0_1129

; DI u32x2 pack4(f32x4 v) { u32x2 r; r[0] = cvtpk(v[0], v[1]); r[1] = cvtpk(v[2], v[3]); return r; }
; template <int EPI>
; DI void gemm_epilogue(const Params& p, f32x4 (&acc)[8][4], int m0, int n0, int wr, int wc, int fr, int fq, u16* Cb, int ldc) {
;     ...
;         for (int m = 0; m < 8; ++m) {
;           const int row = rbase + m * 16;
;           if (!smp) { *(f32x4*)(p.out + O_AKP + (size_t)row * 2048 + c) = acc[m][n]; *(u32x2*)(p.KA + (size_t)row * 2048 + c) = pack4(acc[m][n]); }
;           else *(f32x4*)(p.out + O_AKS + (size_t)(row - MP) * 2048 + c) = acc[m][n];
;         }
.LBB0_1145:
	v_lshlrev_b64 v[96:97], 13, v[130:131]
	v_ashrrev_i32_e32 v129, 31, v128
	v_lshl_add_u64 v[96:97], s[64:65], 0, v[96:97]
	v_lshl_add_u64 v[98:99], v[128:129], 0, v[160:161]
	v_lshl_add_u64 v[96:97], v[98:99], 2, v[96:97]
	v_add_co_u32_e32 v96, vcc, 0xf809f000, v96
	s_nop 1
	v_addc_co_u32_e32 v97, vcc, -1, v97, vcc
	global_store_dwordx4 v[96:97], v[72:75], off offset:-4032 sc1
	s_and_b64 vcc, exec, s[4:5]
	s_mov_b64 s[0:1], -1
	s_cbranch_vccz .LBB0_1131

; DI u32x2 pack4(f32x4 v) { u32x2 r; r[0] = cvtpk(v[0], v[1]); r[1] = cvtpk(v[2], v[3]); return r; }
; template <int EPI>
; DI void gemm_epilogue(const Params& p, f32x4 (&acc)[8][4], int m0, int n0, int wr, int wc, int fr, int fq, u16* Cb, int ldc) {
;     ...
;         for (int m = 0; m < 8; ++m) {
;           const int row = rbase + m * 16;
;           if (!smp) { *(f32x4*)(p.out + O_AKP + (size_t)row * 2048 + c) = acc[m][n]; *(u32x2*)(p.KA + (size_t)row * 2048 + c) = pack4(acc[m][n]); }
;           else *(f32x4*)(p.out + O_AKS + (size_t)(row - MP) * 2048 + c) = acc[m][n];
;         }
.LBB0_1147:
	v_lshlrev_b64 v[96:97], 13, v[130:131]
	v_ashrrev_i32_e32 v129, 31, v128
	v_lshl_add_u64 v[96:97], s[64:65], 0, v[96:97]
	v_lshl_add_u64 v[98:99], v[128:129], 0, v[160:161]
	v_lshl_add_u64 v[96:97], v[98:99], 2, v[96:97]
	v_add_co_u32_e32 v96, vcc, 0xf80bf000, v96
	s_nop 1
	v_addc_co_u32_e32 v97, vcc, -1, v97, vcc
	global_store_dwordx4 v[96:97], v[68:71], off offset:-4032 sc1
	s_and_b64 vcc, exec, s[4:5]
	s_mov_b64 s[0:1], -1
	s_cbranch_vccz .LBB0_1133

; DI u32x2 pack4(f32x4 v) { u32x2 r; r[0] = cvtpk(v[0], v[1]); r[1] = cvtpk(v[2], v[3]); return r; }
; template <int EPI>
; DI void gemm_epilogue(const Params& p, f32x4 (&acc)[8][4], int m0, int n0, int wr, int wc, int fr, int fq, u16* Cb, int ldc) {
;     ...
;         for (int m = 0; m < 8; ++m) {
;           const int row = rbase + m * 16;
;           if (!smp) { *(f32x4*)(p.out + O_AKP + (size_t)row * 2048 + c) = acc[m][n]; *(u32x2*)(p.KA + (size_t)row * 2048 + c) = pack4(acc[m][n]); }
;           else *(f32x4*)(p.out + O_AKS + (size_t)(row - MP) * 2048 + c) = acc[m][n];
;         }
.LBB0_1149:
	v_lshlrev_b64 v[96:97], 13, v[130:131]
	v_ashrrev_i32_e32 v129, 31, v128
	v_lshl_add_u64 v[96:97], s[64:65], 0, v[96:97]
	v_lshl_add_u64 v[98:99], v[128:129], 0, v[160:161]
	v_lshl_add_u64 v[96:97], v[98:99], 2, v[96:97]
	v_add_co_u32_e32 v96, vcc, 0xf80df000, v96
	s_nop 1
	v_addc_co_u32_e32 v97, vcc, -1, v97, vcc
	global_store_dwordx4 v[96:97], v[64:67], off offset:-4032 sc1

; template <int EPI>
; DI void gemm_epilogue(const Params& p, f32x4 (&acc)[8][4], int m0, int n0, int wr, int wc, int fr, int fq, u16* Cb, int ldc) {
;     ...
;       } else if (colt < 8080) {
; #pragma clang loop unroll(full)
;         for (int m = 0; m < 8; ++m) *(f32x4*)(p.out + O_Y + (size_t)(rbase + m * 16) * ZRW + (col - 7248)) = acc[m][n];
.LBB0_1161:
	s_andn2_saveexec_b64 s[0:1], s[28:29]
	s_cbranch_execz .LBB0_1163
	v_readlane_b32 s12, v231, 6
	v_readlane_b32 s20, v231, 14
	v_readlane_b32 s21, v231, 15
	v_add_u32_e32 v70, v128, v160
	v_mov_b32_e32 v71, v161
	v_mov_b64_e32 v[64:65], s[20:21]
	v_mad_i64_i32 v[68:69], s[28:29], v130, s86, v[64:65]
	v_lshlrev_b64 v[70:71], 2, v[70:71]
	v_lshl_add_u64 v[68:69], v[68:69], 0, v[70:71]
	v_add_co_u32_e32 v68, vcc, 0xffff9000, v68
	v_readlane_b32 s13, v231, 7
	s_nop 0
	v_addc_co_u32_e32 v69, vcc, -1, v69, vcc
	global_store_dwordx4 v[68:69], v[60:63], off offset:-192 sc1
	v_mad_i64_i32 v[68:69], s[28:29], v146, s86, v[64:65]
	v_lshl_add_u64 v[68:69], v[68:69], 0, v[70:71]
	v_add_co_u32_e32 v68, vcc, 0xffff9000, v68
	v_readlane_b32 s14, v231, 8
	s_nop 0
	v_addc_co_u32_e32 v69, vcc, -1, v69, vcc
	global_store_dwordx4 v[68:69], v[56:59], off offset:-192 sc1
	v_mad_i64_i32 v[68:69], s[28:29], v144, s86, v[64:65]
	v_lshl_add_u64 v[68:69], v[68:69], 0, v[70:71]
	v_add_co_u32_e32 v68, vcc, 0xffff9000, v68
	v_readlane_b32 s15, v231, 9
	s_nop 0
	v_addc_co_u32_e32 v69, vcc, -1, v69, vcc
	global_store_dwordx4 v[68:69], v[52:55], off offset:-192 sc1
	v_mad_i64_i32 v[68:69], s[28:29], v142, s86, v[64:65]
	v_lshl_add_u64 v[68:69], v[68:69], 0, v[70:71]
	v_add_co_u32_e32 v68, vcc, 0xffff9000, v68
	v_readlane_b32 s16, v231, 10
	s_nop 0
	v_addc_co_u32_e32 v69, vcc, -1, v69, vcc
	global_store_dwordx4 v[68:69], v[48:51], off offset:-192 sc1
	v_mad_i64_i32 v[68:69], s[28:29], v140, s86, v[64:65]
	v_lshl_add_u64 v[68:69], v[68:69], 0, v[70:71]
	v_add_co_u32_e32 v68, vcc, 0xffff9000, v68
	v_readlane_b32 s17, v231, 11
	s_nop 0
	v_addc_co_u32_e32 v69, vcc, -1, v69, vcc
	global_store_dwordx4 v[68:69], v[44:47], off offset:-192 sc1
	v_mad_i64_i32 v[68:69], s[28:29], v138, s86, v[64:65]
	v_lshl_add_u64 v[68:69], v[68:69], 0, v[70:71]
	v_add_co_u32_e32 v68, vcc, 0xffff9000, v68
	v_readlane_b32 s18, v231, 12
	s_nop 0
	v_addc_co_u32_e32 v69, vcc, -1, v69, vcc
	global_store_dwordx4 v[68:69], v[40:43], off offset:-192 sc1
	v_mad_i64_i32 v[68:69], s[28:29], v136, s86, v[64:65]
	v_lshl_add_u64 v[68:69], v[68:69], 0, v[70:71]
	v_add_co_u32_e32 v68, vcc, 0xffff9000, v68
	v_mad_i64_i32 v[64:65], s[28:29], v134, s86, v[64:65]
	s_nop 0
	v_addc_co_u32_e32 v69, vcc, -1, v69, vcc
	v_lshl_add_u64 v[64:65], v[64:65], 0, v[70:71]
	v_add_co_u32_e32 v64, vcc, 0xffff9000, v64
	v_readlane_b32 s19, v231, 13
	s_nop 0
	v_addc_co_u32_e32 v65, vcc, -1, v65, vcc
	v_readlane_b32 s22, v231, 16
	v_readlane_b32 s23, v231, 17
	v_readlane_b32 s24, v231, 18
	v_readlane_b32 s25, v231, 19
	v_readlane_b32 s26, v231, 20
	v_readlane_b32 s27, v231, 21
	global_store_dwordx4 v[68:69], v[36:39], off offset:-192 sc1
	global_store_dwordx4 v[64:65], v[32:35], off offset:-192 sc1

; DI u32x2 pack4(f32x4 v) { u32x2 r; r[0] = cvtpk(v[0], v[1]); r[1] = cvtpk(v[2], v[3]); return r; }
; template <int EPI>
; DI void gemm_epilogue(const Params& p, f32x4 (&acc)[8][4], int m0, int n0, int wr, int wc, int fr, int fq, u16* Cb, int ldc) {
;     ...
;       } else if (colt < 7232) {
;         const int c = col - 7168;
; #pragma clang loop unroll(full)
;         for (int m = 0; m < 8; ++m) {
;           const int row = rbase + m * 16;
;           if (!smp) *(f32x4*)(p.out + O_IDXP + (size_t)row * 64 + c) = acc[m][n];
;           else *(f32x4*)(p.out + O_IDXS + (size_t)(row - MP) * 64 + c) = acc[m][n];
;           *(u32x2*)(p.IXK + (size_t)krow_of(row) * 64 + c) = pack4(acc[m][n]);
;         }
.LBB0_1164:
	s_andn2_saveexec_b64 s[4:5], s[4:5]
	s_cbranch_execz .LBB0_1166
	s_and_b64 s[0:1], s[2:3], exec
	s_mov_b32 s0, 0x19e00000
	v_readlane_b32 s12, v231, 6
	s_cselect_b32 s0, s0, 0x18200000
	v_readlane_b32 s20, v231, 14
	v_add_u32_e32 v67, 0xffffc000, v130
	s_add_u32 s28, s20, s0
	s_movk_i32 s0, 0xe400
	v_cndmask_b32_e64 v64, v130, v67, s[2:3]
	v_lshl_add_u64 v[68:69], v[128:129], 0, v[160:161]
	s_mov_b32 s1, -1
	v_lshrrev_b32_e32 v67, 4, v67
	v_lshl_add_u64 v[68:69], v[68:69], 0, s[0:1]
	v_mad_u64_u32 v[72:73], s[0:1], v67, s94, v[132:133]
	s_movk_i32 s0, 0x4000
	s_nop 0
	v_cmp_gt_i32_e32 vcc, s0, v130
	v_readlane_b32 s13, v231, 7
	v_readlane_b32 s14, v231, 8
	v_readlane_b32 s15, v231, 9
	v_readlane_b32 s16, v231, 10
	v_readlane_b32 s17, v231, 11
	v_readlane_b32 s18, v231, 12
	v_readlane_b32 s19, v231, 13
	v_readlane_b32 s21, v231, 15
	v_readlane_b32 s22, v231, 16
	v_readlane_b32 s23, v231, 17
	v_readlane_b32 s24, v231, 18
	v_readlane_b32 s25, v231, 19
	v_readlane_b32 s26, v231, 20
	v_readlane_b32 s27, v231, 21
	v_ashrrev_i32_e32 v65, 31, v64
	v_cndmask_b32_e32 v72, v72, v130, vcc
	s_addc_u32 s29, s21, 0
	v_lshlrev_b64 v[64:65], 8, v[64:65]
	v_ashrrev_i32_e32 v73, 31, v72
	v_readlane_b32 s12, v231, 38
	v_lshl_add_u64 v[64:65], s[28:29], 0, v[64:65]
	v_lshlrev_b64 v[70:71], 2, v[68:69]
	v_lshlrev_b64 v[72:73], 7, v[72:73]
	v_readlane_b32 s13, v231, 39
	v_lshl_add_u64 v[64:65], v[64:65], 0, v[70:71]
	v_lshlrev_b64 v[68:69], 1, v[68:69]
	v_lshl_add_u64 v[72:73], s[12:13], 0, v[72:73]
	global_store_dwordx4 v[64:65], v[60:63], off offset:128 sc1
	v_cvt_pk_bf16_f32 v64, v60, v61
	v_cvt_pk_bf16_f32 v65, v62, v63
	v_lshl_add_u64 v[72:73], v[72:73], 0, v[68:69]
	v_add_u32_e32 v67, 0xffffc010, v130
	global_store_dwordx2 v[72:73], v[64:65], off offset:64
	v_cndmask_b32_e64 v64, v146, v67, s[2:3]
	v_lshrrev_b32_e32 v67, 4, v67
	v_mad_u64_u32 v[72:73], s[0:1], v67, s94, v[132:133]
	s_movk_i32 s0, 0x3ff0
	s_nop 0
	v_cmp_gt_i32_e32 vcc, s0, v130
	v_ashrrev_i32_e32 v65, 31, v64
	v_lshlrev_b64 v[64:65], 8, v[64:65]
	v_cndmask_b32_e32 v72, v72, v146, vcc
	v_ashrrev_i32_e32 v73, 31, v72
	v_lshl_add_u64 v[64:65], s[28:29], 0, v[64:65]
	v_lshlrev_b64 v[72:73], 7, v[72:73]
	v_lshl_add_u64 v[64:65], v[64:65], 0, v[70:71]
	v_lshl_add_u64 v[72:73], s[12:13], 0, v[72:73]
	global_store_dwordx4 v[64:65], v[56:59], off offset:128 sc1
	v_cvt_pk_bf16_f32 v64, v56, v57
	v_cvt_pk_bf16_f32 v65, v58, v59
	v_lshl_add_u64 v[72:73], v[72:73], 0, v[68:69]
	v_add_u32_e32 v67, 0xffffc020, v130
	global_store_dwordx2 v[72:73], v[64:65], off offset:64
	v_cndmask_b32_e64 v64, v144, v67, s[2:3]
	v_lshrrev_b32_e32 v67, 4, v67
	v_mad_u64_u32 v[72:73], s[0:1], v67, s94, v[132:133]
	s_movk_i32 s0, 0x3fe0
	s_nop 0
	v_cmp_gt_i32_e32 vcc, s0, v130
	v_ashrrev_i32_e32 v65, 31, v64
	v_lshlrev_b64 v[64:65], 8, v[64:65]
	v_cndmask_b32_e32 v72, v72, v144, vcc
	v_ashrrev_i32_e32 v73, 31, v72
	v_lshl_add_u64 v[64:65], s[28:29], 0, v[64:65]
	v_lshlrev_b64 v[72:73], 7, v[72:73]
	v_lshl_add_u64 v[64:65], v[64:65], 0, v[70:71]
	v_lshl_add_u64 v[72:73], s[12:13], 0, v[72:73]
	global_store_dwordx4 v[64:65], v[52:55], off offset:128 sc1
	v_cvt_pk_bf16_f32 v64, v52, v53
	v_cvt_pk_bf16_f32 v65, v54, v55
	v_lshl_add_u64 v[72:73], v[72:73], 0, v[68:69]
	v_add_u32_e32 v67, 0xffffc030, v130
	global_store_dwordx2 v[72:73], v[64:65], off offset:64
	v_cndmask_b32_e64 v64, v142, v67, s[2:3]
	v_lshrrev_b32_e32 v67, 4, v67
	v_mad_u64_u32 v[72:73], s[0:1], v67, s94, v[132:133]
	s_movk_i32 s0, 0x3fd0
	s_nop 0
	v_cmp_gt_i32_e32 vcc, s0, v130
	v_ashrrev_i32_e32 v65, 31, v64
	v_lshlrev_b64 v[64:65], 8, v[64:65]
	v_cndmask_b32_e32 v72, v72, v142, vcc
	v_ashrrev_i32_e32 v73, 31, v72
	v_lshl_add_u64 v[64:65], s[28:29], 0, v[64:65]
	v_lshlrev_b64 v[72:73], 7, v[72:73]
	v_lshl_add_u64 v[64:65], v[64:65], 0, v[70:71]
; DI u32x2 pack4(f32x4 v) { u32x2 r; r[0] = cvtpk(v[0], v[1]); r[1] = cvtpk(v[2], v[3]); return r; }
; template <int EPI>
; DI void gemm_epilogue(const Params& p, f32x4 (&acc)[8][4], int m0, int n0, int wr, int wc, int fr, int fq, u16* Cb, int ldc) {
;     ...
;       } else if (colt < 7232) {
;         const int c = col - 7168;
; #pragma clang loop unroll(full)
;         for (int m = 0; m < 8; ++m) {
;           const int row = rbase + m * 16;
;           if (!smp) *(f32x4*)(p.out + O_IDXP + (size_t)row * 64 + c) = acc[m][n];
;           else *(f32x4*)(p.out + O_IDXS + (size_t)(row - MP) * 64 + c) = acc[m][n];
;           *(u32x2*)(p.IXK + (size_t)krow_of(row) * 64 + c) = pack4(acc[m][n]);
;         }
	v_lshl_add_u64 v[72:73], s[12:13], 0, v[72:73]
	global_store_dwordx4 v[64:65], v[48:51], off offset:128 sc1
	v_cvt_pk_bf16_f32 v64, v48, v49
	v_cvt_pk_bf16_f32 v65, v50, v51
	v_lshl_add_u64 v[72:73], v[72:73], 0, v[68:69]
	v_add_u32_e32 v67, 0xffffc040, v130
	global_store_dwordx2 v[72:73], v[64:65], off offset:64
	v_cndmask_b32_e64 v64, v140, v67, s[2:3]
	v_lshrrev_b32_e32 v67, 4, v67
	v_mad_u64_u32 v[72:73], s[0:1], v67, s94, v[132:133]
	s_movk_i32 s0, 0x3fc0
	s_nop 0
	v_cmp_gt_i32_e32 vcc, s0, v130
	v_ashrrev_i32_e32 v65, 31, v64
	v_lshlrev_b64 v[64:65], 8, v[64:65]
	v_cndmask_b32_e32 v72, v72, v140, vcc
	v_ashrrev_i32_e32 v73, 31, v72
	v_lshl_add_u64 v[64:65], s[28:29], 0, v[64:65]
	v_lshlrev_b64 v[72:73], 7, v[72:73]
	v_lshl_add_u64 v[64:65], v[64:65], 0, v[70:71]
	v_lshl_add_u64 v[72:73], s[12:13], 0, v[72:73]
	global_store_dwordx4 v[64:65], v[44:47], off offset:128 sc1
	v_cvt_pk_bf16_f32 v64, v44, v45
	v_cvt_pk_bf16_f32 v65, v46, v47
	v_lshl_add_u64 v[72:73], v[72:73], 0, v[68:69]
	v_add_u32_e32 v67, 0xffffc050, v130
	global_store_dwordx2 v[72:73], v[64:65], off offset:64
	v_cndmask_b32_e64 v64, v138, v67, s[2:3]
	v_lshrrev_b32_e32 v67, 4, v67
	v_mad_u64_u32 v[72:73], s[0:1], v67, s94, v[132:133]
	s_movk_i32 s0, 0x3fb0
	s_nop 0
	v_cmp_gt_i32_e32 vcc, s0, v130
	v_ashrrev_i32_e32 v65, 31, v64
	v_lshlrev_b64 v[64:65], 8, v[64:65]
	v_cndmask_b32_e32 v72, v72, v138, vcc
	v_ashrrev_i32_e32 v73, 31, v72
	v_lshl_add_u64 v[64:65], s[28:29], 0, v[64:65]
	v_lshlrev_b64 v[72:73], 7, v[72:73]
	v_lshl_add_u64 v[64:65], v[64:65], 0, v[70:71]
	v_lshl_add_u64 v[72:73], s[12:13], 0, v[72:73]
	global_store_dwordx4 v[64:65], v[40:43], off offset:128 sc1
	v_cvt_pk_bf16_f32 v64, v40, v41
	v_cvt_pk_bf16_f32 v65, v42, v43
	v_lshl_add_u64 v[72:73], v[72:73], 0, v[68:69]
	v_add_u32_e32 v67, 0xffffc060, v130
	global_store_dwordx2 v[72:73], v[64:65], off offset:64
	v_cndmask_b32_e64 v64, v136, v67, s[2:3]
	v_lshrrev_b32_e32 v67, 4, v67
	v_mad_u64_u32 v[72:73], s[0:1], v67, s94, v[132:133]
	s_movk_i32 s0, 0x3fa0
	s_nop 0
	v_cmp_gt_i32_e32 vcc, s0, v130
	v_ashrrev_i32_e32 v65, 31, v64
	v_lshlrev_b64 v[64:65], 8, v[64:65]
	v_cndmask_b32_e32 v72, v72, v136, vcc
	v_ashrrev_i32_e32 v73, 31, v72
	v_lshl_add_u64 v[64:65], s[28:29], 0, v[64:65]
	v_lshlrev_b64 v[72:73], 7, v[72:73]
	v_lshl_add_u64 v[64:65], v[64:65], 0, v[70:71]
	v_lshl_add_u64 v[72:73], s[12:13], 0, v[72:73]
	global_store_dwordx4 v[64:65], v[36:39], off offset:128 sc1
	v_cvt_pk_bf16_f32 v64, v36, v37
	v_cvt_pk_bf16_f32 v65, v38, v39
	v_lshl_add_u64 v[72:73], v[72:73], 0, v[68:69]
	v_add_u32_e32 v67, 0xffffc070, v130
	global_store_dwordx2 v[72:73], v[64:65], off offset:64
	v_cndmask_b32_e64 v64, v134, v67, s[2:3]
	v_ashrrev_i32_e32 v65, 31, v64
	v_lshlrev_b64 v[64:65], 8, v[64:65]
	v_lshl_add_u64 v[64:65], s[28:29], 0, v[64:65]
	v_lshrrev_b32_e32 v67, 4, v67
	v_lshl_add_u64 v[64:65], v[64:65], 0, v[70:71]
	v_mad_u64_u32 v[70:71], s[0:1], v67, s94, v[132:133]
	s_movk_i32 s0, 0x3f90
	s_nop 0
	v_cmp_gt_i32_e32 vcc, s0, v130
	global_store_dwordx4 v[64:65], v[32:35], off offset:128 sc1
	v_cvt_pk_bf16_f32 v64, v32, v33
	v_cndmask_b32_e32 v70, v70, v134, vcc
	v_ashrrev_i32_e32 v71, 31, v70
	v_lshlrev_b64 v[70:71], 7, v[70:71]
	v_lshl_add_u64 v[70:71], s[12:13], 0, v[70:71]
	v_cvt_pk_bf16_f32 v65, v34, v35
	v_lshl_add_u64 v[68:69], v[70:71], 0, v[68:69]
	v_readlane_b32 s14, v231, 40
	v_readlane_b32 s15, v231, 41
	v_readlane_b32 s16, v231, 42
	v_readlane_b32 s17, v231, 43
	v_readlane_b32 s18, v231, 44
	v_readlane_b32 s19, v231, 45
	v_readlane_b32 s20, v231, 46
	v_readlane_b32 s21, v231, 47
	v_readlane_b32 s22, v231, 48
	v_readlane_b32 s23, v231, 49
	v_readlane_b32 s24, v231, 50
	v_readlane_b32 s25, v231, 51
	v_readlane_b32 s26, v231, 52
	v_readlane_b32 s27, v231, 53
	global_store_dwordx2 v[68:69], v[64:65], off offset:64

; DI u16 f2bf(float x) { return (u16)(cvtpk(x, 0.f) & 0xffffu); }
; template <int EPI>
; DI void gemm_epilogue(const Params& p, f32x4 (&acc)[8][4], int m0, int n0, int wr, int wc, int fr, int fq, u16* Cb, int ldc) {
;     ...
; #pragma clang loop unroll(full)
;         for (int m = 0; m < 8; ++m) {
;           const int row = rbase + m * 16;
;           if (!smp) {
;             *(f32x4*)(p.out + O_AVP + (size_t)row * 2048 + c) = acc[m][n];
; #pragma clang loop unroll(full)
;             for (int j = 0; j < 4; ++j) p.VAT[(size_t)(c + j) * MP + row] = f2bf(acc[m][n][j]);
;           } else *(f32x4*)(p.out + O_AVS + (size_t)(row - MP) * 2048 + c) = acc[m][n];
.LBB0_1170:
	s_andn2_b64 vcc, exec, s[0:1]
	s_cbranch_vccnz .LBB0_1203
	v_or_b32_e32 v64, v66, v160
	v_add_u32_e32 v66, 0xfffff000, v64
	v_ashrrev_i32_e32 v67, 31, v66
	v_cndmask_b32_e64 v65, 0, 1, s[88:89]
	s_mov_b64 s[0:1], -1
	v_cmp_ne_u32_e64 s[4:5], 1, v65
	s_andn2_b64 vcc, exec, s[88:89]
	v_lshlrev_b64 v[66:67], 15, v[66:67]
	v_ashrrev_i32_e32 v65, 31, v64
	s_cbranch_vccnz .LBB0_1187
	v_lshlrev_b64 v[68:69], 13, v[130:131]
	v_lshl_add_u64 v[68:69], s[6:7], 0, v[68:69]
	v_lshl_add_u64 v[70:71], v[128:129], 0, v[160:161]
	v_lshl_add_u64 v[68:69], v[70:71], 2, v[68:69]
	v_add_co_u32_e32 v68, vcc, 0xffffd000, v68
	v_cvt_pk_bf16_f32 v72, v60, s0
	s_nop 0
	v_addc_co_u32_e32 v69, vcc, -1, v69, vcc
	global_store_dwordx4 v[68:69], v[60:63], off offset:-3968 sc1
	v_lshl_add_u64 v[68:69], v[130:131], 1, s[48:49]
	v_lshl_add_u64 v[70:71], v[68:69], 0, v[66:67]
	global_store_short v[70:71], v72, off
	v_lshlrev_b64 v[70:71], 15, v[64:65]
	v_lshl_add_u64 v[68:69], v[68:69], 0, v[70:71]
	v_add_co_u32_e32 v70, vcc, 0xf8008000, v68
	v_cvt_pk_bf16_f32 v72, v61, s0
	s_nop 0
	v_addc_co_u32_e32 v71, vcc, -1, v69, vcc
	global_store_short v[70:71], v72, off
	v_add_co_u32_e32 v70, vcc, 0xf8010000, v68
	v_cvt_pk_bf16_f32 v72, v62, s0
	s_nop 0
	v_addc_co_u32_e32 v71, vcc, -1, v69, vcc
	v_add_co_u32_e32 v68, vcc, 0xf8018000, v68
	global_store_short v[70:71], v72, off
	v_cvt_pk_bf16_f32 v70, v63, s0
	v_addc_co_u32_e32 v69, vcc, -1, v69, vcc
	global_store_short v[68:69], v70, off
	s_cbranch_execz .LBB0_1188

; DI u16 f2bf(float x) { return (u16)(cvtpk(x, 0.f) & 0xffffu); }
; template <int EPI>
; DI void gemm_epilogue(const Params& p, f32x4 (&acc)[8][4], int m0, int n0, int wr, int wc, int fr, int fq, u16* Cb, int ldc) {
;     ...
; #pragma clang loop unroll(full)
;         for (int m = 0; m < 8; ++m) {
;           const int row = rbase + m * 16;
;           if (!smp) {
;             *(f32x4*)(p.out + O_AVP + (size_t)row * 2048 + c) = acc[m][n];
; #pragma clang loop unroll(full)
;             for (int j = 0; j < 4; ++j) p.VAT[(size_t)(c + j) * MP + row] = f2bf(acc[m][n][j]);
;           } else *(f32x4*)(p.out + O_AVS + (size_t)(row - MP) * 2048 + c) = acc[m][n];
.LBB0_1174:
	v_lshlrev_b64 v[68:69], 13, v[146:147]
	v_lshl_add_u64 v[68:69], s[6:7], 0, v[68:69]
	v_lshl_add_u64 v[70:71], v[128:129], 0, v[160:161]
	v_lshl_add_u64 v[68:69], v[70:71], 2, v[68:69]
	v_add_co_u32_e32 v68, vcc, 0xffffd000, v68
	v_cvt_pk_bf16_f32 v72, v56, s0
	s_nop 0
	v_addc_co_u32_e32 v69, vcc, -1, v69, vcc
	global_store_dwordx4 v[68:69], v[56:59], off offset:-3968 sc1
	v_lshl_add_u64 v[68:69], v[130:131], 1, s[48:49]
	v_lshl_add_u64 v[70:71], v[68:69], 0, v[66:67]
	global_store_short v[70:71], v72, off offset:32
	v_lshlrev_b64 v[70:71], 15, v[64:65]
	v_lshl_add_u64 v[68:69], v[68:69], 0, v[70:71]
	v_add_co_u32_e32 v70, vcc, 0xf8009000, v68
	v_cvt_pk_bf16_f32 v72, v57, s0
	s_nop 0
	v_addc_co_u32_e32 v71, vcc, -1, v69, vcc
	global_store_short v[70:71], v72, off offset:-4064
	v_add_co_u32_e32 v70, vcc, 0xf8011000, v68
	v_cvt_pk_bf16_f32 v72, v58, s0
	s_nop 0
	v_addc_co_u32_e32 v71, vcc, -1, v69, vcc
	v_add_co_u32_e32 v68, vcc, 0xf8019000, v68
	global_store_short v[70:71], v72, off offset:-4064
	v_cvt_pk_bf16_f32 v70, v59, s0
	v_addc_co_u32_e32 v69, vcc, -1, v69, vcc
	global_store_short v[68:69], v70, off offset:-4064
	s_cbranch_execz .LBB0_1190

; DI u16 f2bf(float x) { return (u16)(cvtpk(x, 0.f) & 0xffffu); }
; template <int EPI>
; DI void gemm_epilogue(const Params& p, f32x4 (&acc)[8][4], int m0, int n0, int wr, int wc, int fr, int fq, u16* Cb, int ldc) {
;     ...
; #pragma clang loop unroll(full)
;         for (int m = 0; m < 8; ++m) {
;           const int row = rbase + m * 16;
;           if (!smp) {
;             *(f32x4*)(p.out + O_AVP + (size_t)row * 2048 + c) = acc[m][n];
; #pragma clang loop unroll(full)
;             for (int j = 0; j < 4; ++j) p.VAT[(size_t)(c + j) * MP + row] = f2bf(acc[m][n][j]);
;           } else *(f32x4*)(p.out + O_AVS + (size_t)(row - MP) * 2048 + c) = acc[m][n];
.LBB0_1176:
	v_lshlrev_b64 v[68:69], 13, v[144:145]
	v_lshl_add_u64 v[68:69], s[6:7], 0, v[68:69]
	v_lshl_add_u64 v[70:71], v[128:129], 0, v[160:161]
	v_lshl_add_u64 v[68:69], v[70:71], 2, v[68:69]
	v_add_co_u32_e32 v68, vcc, 0xffffd000, v68
	v_cvt_pk_bf16_f32 v72, v52, s0
	s_nop 0
	v_addc_co_u32_e32 v69, vcc, -1, v69, vcc
	global_store_dwordx4 v[68:69], v[52:55], off offset:-3968 sc1
	v_lshl_add_u64 v[68:69], v[130:131], 1, s[48:49]
	v_lshl_add_u64 v[70:71], v[68:69], 0, v[66:67]
	global_store_short v[70:71], v72, off offset:64
	v_lshlrev_b64 v[70:71], 15, v[64:65]
	v_lshl_add_u64 v[68:69], v[68:69], 0, v[70:71]
	v_add_co_u32_e32 v70, vcc, 0xf8009000, v68
	v_cvt_pk_bf16_f32 v72, v53, s0
	s_nop 0
	v_addc_co_u32_e32 v71, vcc, -1, v69, vcc
	global_store_short v[70:71], v72, off offset:-4032
	v_add_co_u32_e32 v70, vcc, 0xf8011000, v68
	v_cvt_pk_bf16_f32 v72, v54, s0
	s_nop 0
	v_addc_co_u32_e32 v71, vcc, -1, v69, vcc
	v_add_co_u32_e32 v68, vcc, 0xf8019000, v68
	global_store_short v[70:71], v72, off offset:-4032
	v_cvt_pk_bf16_f32 v70, v55, s0
	v_addc_co_u32_e32 v69, vcc, -1, v69, vcc
	global_store_short v[68:69], v70, off offset:-4032
	s_cbranch_execz .LBB0_1192

; DI u16 f2bf(float x) { return (u16)(cvtpk(x, 0.f) & 0xffffu); }
; template <int EPI>
; DI void gemm_epilogue(const Params& p, f32x4 (&acc)[8][4], int m0, int n0, int wr, int wc, int fr, int fq, u16* Cb, int ldc) {
;     ...
; #pragma clang loop unroll(full)
;         for (int m = 0; m < 8; ++m) {
;           const int row = rbase + m * 16;
;           if (!smp) {
;             *(f32x4*)(p.out + O_AVP + (size_t)row * 2048 + c) = acc[m][n];
; #pragma clang loop unroll(full)
;             for (int j = 0; j < 4; ++j) p.VAT[(size_t)(c + j) * MP + row] = f2bf(acc[m][n][j]);
;           } else *(f32x4*)(p.out + O_AVS + (size_t)(row - MP) * 2048 + c) = acc[m][n];
.LBB0_1178:
	v_lshlrev_b64 v[68:69], 13, v[142:143]
	v_lshl_add_u64 v[68:69], s[6:7], 0, v[68:69]
	v_lshl_add_u64 v[70:71], v[128:129], 0, v[160:161]
	v_lshl_add_u64 v[68:69], v[70:71], 2, v[68:69]
	v_add_co_u32_e32 v68, vcc, 0xffffd000, v68
	v_cvt_pk_bf16_f32 v72, v48, s0
	s_nop 0
	v_addc_co_u32_e32 v69, vcc, -1, v69, vcc
	global_store_dwordx4 v[68:69], v[48:51], off offset:-3968 sc1
	v_lshl_add_u64 v[68:69], v[130:131], 1, s[48:49]
	v_lshl_add_u64 v[70:71], v[68:69], 0, v[66:67]
	global_store_short v[70:71], v72, off offset:96
	v_lshlrev_b64 v[70:71], 15, v[64:65]
	v_lshl_add_u64 v[68:69], v[68:69], 0, v[70:71]
	v_add_co_u32_e32 v70, vcc, 0xf8009000, v68
	v_cvt_pk_bf16_f32 v72, v49, s0
	s_nop 0
	v_addc_co_u32_e32 v71, vcc, -1, v69, vcc
	global_store_short v[70:71], v72, off offset:-4000
	v_add_co_u32_e32 v70, vcc, 0xf8011000, v68
	v_cvt_pk_bf16_f32 v72, v50, s0
	s_nop 0
	v_addc_co_u32_e32 v71, vcc, -1, v69, vcc
	v_add_co_u32_e32 v68, vcc, 0xf8019000, v68
	global_store_short v[70:71], v72, off offset:-4000
	v_cvt_pk_bf16_f32 v70, v51, s0
	v_addc_co_u32_e32 v69, vcc, -1, v69, vcc
	global_store_short v[68:69], v70, off offset:-4000
	s_cbranch_execz .LBB0_1194

; DI u16 f2bf(float x) { return (u16)(cvtpk(x, 0.f) & 0xffffu); }
; template <int EPI>
; DI void gemm_epilogue(const Params& p, f32x4 (&acc)[8][4], int m0, int n0, int wr, int wc, int fr, int fq, u16* Cb, int ldc) {
;     ...
; #pragma clang loop unroll(full)
;         for (int m = 0; m < 8; ++m) {
;           const int row = rbase + m * 16;
;           if (!smp) {
;             *(f32x4*)(p.out + O_AVP + (size_t)row * 2048 + c) = acc[m][n];
; #pragma clang loop unroll(full)
;             for (int j = 0; j < 4; ++j) p.VAT[(size_t)(c + j) * MP + row] = f2bf(acc[m][n][j]);
;           } else *(f32x4*)(p.out + O_AVS + (size_t)(row - MP) * 2048 + c) = acc[m][n];
.LBB0_1180:
	v_lshlrev_b64 v[68:69], 13, v[140:141]
	v_lshl_add_u64 v[68:69], s[6:7], 0, v[68:69]
	v_lshl_add_u64 v[70:71], v[128:129], 0, v[160:161]
	v_lshl_add_u64 v[68:69], v[70:71], 2, v[68:69]
	v_add_co_u32_e32 v68, vcc, 0xffffd000, v68
	v_cvt_pk_bf16_f32 v72, v44, s0
	s_nop 0
	v_addc_co_u32_e32 v69, vcc, -1, v69, vcc
	global_store_dwordx4 v[68:69], v[44:47], off offset:-3968 sc1
	v_lshl_add_u64 v[68:69], v[130:131], 1, s[48:49]
	v_lshl_add_u64 v[70:71], v[68:69], 0, v[66:67]
	global_store_short v[70:71], v72, off offset:128
	v_lshlrev_b64 v[70:71], 15, v[64:65]
	v_lshl_add_u64 v[68:69], v[68:69], 0, v[70:71]
	v_add_co_u32_e32 v70, vcc, 0xf8009000, v68
	v_cvt_pk_bf16_f32 v72, v45, s0
	s_nop 0
	v_addc_co_u32_e32 v71, vcc, -1, v69, vcc
	global_store_short v[70:71], v72, off offset:-3968
	v_add_co_u32_e32 v70, vcc, 0xf8011000, v68
	v_cvt_pk_bf16_f32 v72, v46, s0
	s_nop 0
	v_addc_co_u32_e32 v71, vcc, -1, v69, vcc
	v_add_co_u32_e32 v68, vcc, 0xf8019000, v68
	global_store_short v[70:71], v72, off offset:-3968
	v_cvt_pk_bf16_f32 v70, v47, s0
	v_addc_co_u32_e32 v69, vcc, -1, v69, vcc
	global_store_short v[68:69], v70, off offset:-3968
	s_cbranch_execz .LBB0_1196

; DI u16 f2bf(float x) { return (u16)(cvtpk(x, 0.f) & 0xffffu); }
; template <int EPI>
; DI void gemm_epilogue(const Params& p, f32x4 (&acc)[8][4], int m0, int n0, int wr, int wc, int fr, int fq, u16* Cb, int ldc) {
;     ...
; #pragma clang loop unroll(full)
;         for (int m = 0; m < 8; ++m) {
;           const int row = rbase + m * 16;
;           if (!smp) {
;             *(f32x4*)(p.out + O_AVP + (size_t)row * 2048 + c) = acc[m][n];
; #pragma clang loop unroll(full)
;             for (int j = 0; j < 4; ++j) p.VAT[(size_t)(c + j) * MP + row] = f2bf(acc[m][n][j]);
;           } else *(f32x4*)(p.out + O_AVS + (size_t)(row - MP) * 2048 + c) = acc[m][n];
.LBB0_1182:
	v_lshlrev_b64 v[68:69], 13, v[138:139]
	v_lshl_add_u64 v[68:69], s[6:7], 0, v[68:69]
	v_lshl_add_u64 v[70:71], v[128:129], 0, v[160:161]
	v_lshl_add_u64 v[68:69], v[70:71], 2, v[68:69]
	v_add_co_u32_e32 v68, vcc, 0xffffd000, v68
	v_cvt_pk_bf16_f32 v72, v40, s0
	s_nop 0
	v_addc_co_u32_e32 v69, vcc, -1, v69, vcc
	global_store_dwordx4 v[68:69], v[40:43], off offset:-3968 sc1
	v_lshl_add_u64 v[68:69], v[130:131], 1, s[48:49]
	v_lshl_add_u64 v[70:71], v[68:69], 0, v[66:67]
	global_store_short v[70:71], v72, off offset:160
	v_lshlrev_b64 v[70:71], 15, v[64:65]
	v_lshl_add_u64 v[68:69], v[68:69], 0, v[70:71]
	v_add_co_u32_e32 v70, vcc, 0xf8009000, v68
	v_cvt_pk_bf16_f32 v72, v41, s0
	s_nop 0
	v_addc_co_u32_e32 v71, vcc, -1, v69, vcc
	global_store_short v[70:71], v72, off offset:-3936
	v_add_co_u32_e32 v70, vcc, 0xf8011000, v68
	v_cvt_pk_bf16_f32 v72, v42, s0
	s_nop 0
	v_addc_co_u32_e32 v71, vcc, -1, v69, vcc
	v_add_co_u32_e32 v68, vcc, 0xf8019000, v68
	global_store_short v[70:71], v72, off offset:-3936
	v_cvt_pk_bf16_f32 v70, v43, s0
	v_addc_co_u32_e32 v69, vcc, -1, v69, vcc
	global_store_short v[68:69], v70, off offset:-3936
	s_cbranch_execz .LBB0_1198

; DI u16 f2bf(float x) { return (u16)(cvtpk(x, 0.f) & 0xffffu); }
; template <int EPI>
; DI void gemm_epilogue(const Params& p, f32x4 (&acc)[8][4], int m0, int n0, int wr, int wc, int fr, int fq, u16* Cb, int ldc) {
;     ...
; #pragma clang loop unroll(full)
;         for (int m = 0; m < 8; ++m) {
;           const int row = rbase + m * 16;
;           if (!smp) {
;             *(f32x4*)(p.out + O_AVP + (size_t)row * 2048 + c) = acc[m][n];
; #pragma clang loop unroll(full)
;             for (int j = 0; j < 4; ++j) p.VAT[(size_t)(c + j) * MP + row] = f2bf(acc[m][n][j]);
;           } else *(f32x4*)(p.out + O_AVS + (size_t)(row - MP) * 2048 + c) = acc[m][n];
.LBB0_1184:
	v_lshlrev_b64 v[68:69], 13, v[136:137]
	v_lshl_add_u64 v[68:69], s[6:7], 0, v[68:69]
	v_lshl_add_u64 v[70:71], v[128:129], 0, v[160:161]
	v_lshl_add_u64 v[68:69], v[70:71], 2, v[68:69]
	v_add_co_u32_e32 v68, vcc, 0xffffd000, v68
	v_cvt_pk_bf16_f32 v72, v36, s0
	s_nop 0
	v_addc_co_u32_e32 v69, vcc, -1, v69, vcc
	global_store_dwordx4 v[68:69], v[36:39], off offset:-3968 sc1
	v_lshl_add_u64 v[68:69], v[130:131], 1, s[48:49]
	v_lshl_add_u64 v[70:71], v[68:69], 0, v[66:67]
	global_store_short v[70:71], v72, off offset:192
	v_lshlrev_b64 v[70:71], 15, v[64:65]
	v_lshl_add_u64 v[68:69], v[68:69], 0, v[70:71]
	v_add_co_u32_e32 v70, vcc, 0xf8009000, v68
	v_cvt_pk_bf16_f32 v72, v37, s0
	s_nop 0
	v_addc_co_u32_e32 v71, vcc, -1, v69, vcc
	global_store_short v[70:71], v72, off offset:-3904
	v_add_co_u32_e32 v70, vcc, 0xf8011000, v68
	v_cvt_pk_bf16_f32 v72, v38, s0
	s_nop 0
	v_addc_co_u32_e32 v71, vcc, -1, v69, vcc
	v_add_co_u32_e32 v68, vcc, 0xf8019000, v68
	global_store_short v[70:71], v72, off offset:-3904
	v_cvt_pk_bf16_f32 v70, v39, s0
	v_addc_co_u32_e32 v69, vcc, -1, v69, vcc
	global_store_short v[68:69], v70, off offset:-3904
	s_cbranch_execz .LBB0_1200

; DI u16 f2bf(float x) { return (u16)(cvtpk(x, 0.f) & 0xffffu); }
; template <int EPI>
; DI void gemm_epilogue(const Params& p, f32x4 (&acc)[8][4], int m0, int n0, int wr, int wc, int fr, int fq, u16* Cb, int ldc) {
;     ...
; #pragma clang loop unroll(full)
;         for (int m = 0; m < 8; ++m) {
;           const int row = rbase + m * 16;
;           if (!smp) {
;             *(f32x4*)(p.out + O_AVP + (size_t)row * 2048 + c) = acc[m][n];
; #pragma clang loop unroll(full)
;             for (int j = 0; j < 4; ++j) p.VAT[(size_t)(c + j) * MP + row] = f2bf(acc[m][n][j]);
;           } else *(f32x4*)(p.out + O_AVS + (size_t)(row - MP) * 2048 + c) = acc[m][n];
.LBB0_1186:
	v_lshlrev_b64 v[68:69], 13, v[134:135]
	v_lshl_add_u64 v[68:69], s[6:7], 0, v[68:69]
	v_lshl_add_u64 v[70:71], v[128:129], 0, v[160:161]
	v_lshl_add_u64 v[68:69], v[70:71], 2, v[68:69]
	v_add_co_u32_e32 v68, vcc, 0xffffd000, v68
	v_lshlrev_b64 v[64:65], 15, v[64:65]
	s_nop 0
	v_addc_co_u32_e32 v69, vcc, -1, v69, vcc
	global_store_dwordx4 v[68:69], v[32:35], off offset:-3968 sc1
	v_lshl_add_u64 v[68:69], v[130:131], 1, s[48:49]
	v_cvt_pk_bf16_f32 v70, v32, s0
	v_lshl_add_u64 v[66:67], v[68:69], 0, v[66:67]
	v_lshl_add_u64 v[64:65], v[68:69], 0, v[64:65]
	global_store_short v[66:67], v70, off offset:224
	v_add_co_u32_e32 v66, vcc, 0xf8009000, v64
	v_cvt_pk_bf16_f32 v70, v33, s0
	s_nop 0
	v_addc_co_u32_e32 v67, vcc, -1, v65, vcc
	global_store_short v[66:67], v70, off offset:-3872
	v_add_co_u32_e32 v66, vcc, 0xf8011000, v64
	v_cvt_pk_bf16_f32 v68, v34, s0
	s_nop 0
	v_addc_co_u32_e32 v67, vcc, -1, v65, vcc
	v_add_co_u32_e32 v64, vcc, 0xf8019000, v64
	global_store_short v[66:67], v68, off offset:-3872
	v_cvt_pk_bf16_f32 v66, v35, s0
	v_addc_co_u32_e32 v65, vcc, -1, v65, vcc
	global_store_short v[64:65], v66, off offset:-3872
	s_cbranch_execz .LBB0_1202
	s_branch .LBB0_1203

; DI u16 f2bf(float x) { return (u16)(cvtpk(x, 0.f) & 0xffffu); }
; template <int EPI>
; DI void gemm_epilogue(const Params& p, f32x4 (&acc)[8][4], int m0, int n0, int wr, int wc, int fr, int fq, u16* Cb, int ldc) {
;     ...
; #pragma clang loop unroll(full)
;         for (int m = 0; m < 8; ++m) {
;           const int row = rbase + m * 16;
;           if (!smp) {
;             *(f32x4*)(p.out + O_AVP + (size_t)row * 2048 + c) = acc[m][n];
; #pragma clang loop unroll(full)
;             for (int j = 0; j < 4; ++j) p.VAT[(size_t)(c + j) * MP + row] = f2bf(acc[m][n][j]);
;           } else *(f32x4*)(p.out + O_AVS + (size_t)(row - MP) * 2048 + c) = acc[m][n];
.LBB0_1188:
	v_lshlrev_b64 v[68:69], 13, v[130:131]
	v_lshl_add_u64 v[68:69], s[62:63], 0, v[68:69]
	v_lshl_add_u64 v[70:71], v[128:129], 0, v[160:161]
	v_lshl_add_u64 v[68:69], v[70:71], 2, v[68:69]
	v_add_co_u32_e32 v68, vcc, 0xf7ffd000, v68
	s_nop 1
	v_addc_co_u32_e32 v69, vcc, -1, v69, vcc
	global_store_dwordx4 v[68:69], v[60:63], off offset:-3968 sc1
	s_and_b64 vcc, exec, s[4:5]
	s_mov_b64 s[0:1], -1
	s_cbranch_vccz .LBB0_1174

; DI u16 f2bf(float x) { return (u16)(cvtpk(x, 0.f) & 0xffffu); }
; template <int EPI>
; DI void gemm_epilogue(const Params& p, f32x4 (&acc)[8][4], int m0, int n0, int wr, int wc, int fr, int fq, u16* Cb, int ldc) {
;     ...
; #pragma clang loop unroll(full)
;         for (int m = 0; m < 8; ++m) {
;           const int row = rbase + m * 16;
;           if (!smp) {
;             *(f32x4*)(p.out + O_AVP + (size_t)row * 2048 + c) = acc[m][n];
; #pragma clang loop unroll(full)
;             for (int j = 0; j < 4; ++j) p.VAT[(size_t)(c + j) * MP + row] = f2bf(acc[m][n][j]);
;           } else *(f32x4*)(p.out + O_AVS + (size_t)(row - MP) * 2048 + c) = acc[m][n];
.LBB0_1190:
	v_lshlrev_b64 v[68:69], 13, v[130:131]
	v_lshl_add_u64 v[68:69], s[62:63], 0, v[68:69]
	v_lshl_add_u64 v[70:71], v[128:129], 0, v[160:161]
	v_lshl_add_u64 v[68:69], v[70:71], 2, v[68:69]
	v_add_co_u32_e32 v68, vcc, 0xf801d000, v68
	s_nop 1
	v_addc_co_u32_e32 v69, vcc, -1, v69, vcc
	global_store_dwordx4 v[68:69], v[56:59], off offset:-3968 sc1
	s_and_b64 vcc, exec, s[4:5]
	s_mov_b64 s[0:1], -1
	s_cbranch_vccz .LBB0_1176

; DI u16 f2bf(float x) { return (u16)(cvtpk(x, 0.f) & 0xffffu); }
; template <int EPI>
; DI void gemm_epilogue(const Params& p, f32x4 (&acc)[8][4], int m0, int n0, int wr, int wc, int fr, int fq, u16* Cb, int ldc) {
;     ...
; #pragma clang loop unroll(full)
;         for (int m = 0; m < 8; ++m) {
;           const int row = rbase + m * 16;
;           if (!smp) {
;             *(f32x4*)(p.out + O_AVP + (size_t)row * 2048 + c) = acc[m][n];
; #pragma clang loop unroll(full)
;             for (int j = 0; j < 4; ++j) p.VAT[(size_t)(c + j) * MP + row] = f2bf(acc[m][n][j]);
;           } else *(f32x4*)(p.out + O_AVS + (size_t)(row - MP) * 2048 + c) = acc[m][n];
.LBB0_1192:
	v_lshlrev_b64 v[68:69], 13, v[130:131]
	v_lshl_add_u64 v[68:69], s[62:63], 0, v[68:69]
	v_lshl_add_u64 v[70:71], v[128:129], 0, v[160:161]
	v_lshl_add_u64 v[68:69], v[70:71], 2, v[68:69]
	v_add_co_u32_e32 v68, vcc, 0xf803d000, v68
	s_nop 1
	v_addc_co_u32_e32 v69, vcc, -1, v69, vcc
	global_store_dwordx4 v[68:69], v[52:55], off offset:-3968 sc1
	s_and_b64 vcc, exec, s[4:5]
	s_mov_b64 s[0:1], -1
	s_cbranch_vccz .LBB0_1178

; DI u16 f2bf(float x) { return (u16)(cvtpk(x, 0.f) & 0xffffu); }
; template <int EPI>
; DI void gemm_epilogue(const Params& p, f32x4 (&acc)[8][4], int m0, int n0, int wr, int wc, int fr, int fq, u16* Cb, int ldc) {
;     ...
; #pragma clang loop unroll(full)
;         for (int m = 0; m < 8; ++m) {
;           const int row = rbase + m * 16;
;           if (!smp) {
;             *(f32x4*)(p.out + O_AVP + (size_t)row * 2048 + c) = acc[m][n];
; #pragma clang loop unroll(full)
;             for (int j = 0; j < 4; ++j) p.VAT[(size_t)(c + j) * MP + row] = f2bf(acc[m][n][j]);
;           } else *(f32x4*)(p.out + O_AVS + (size_t)(row - MP) * 2048 + c) = acc[m][n];
.LBB0_1194:
	v_lshlrev_b64 v[68:69], 13, v[130:131]
	v_lshl_add_u64 v[68:69], s[62:63], 0, v[68:69]
	v_lshl_add_u64 v[70:71], v[128:129], 0, v[160:161]
	v_lshl_add_u64 v[68:69], v[70:71], 2, v[68:69]
	v_add_co_u32_e32 v68, vcc, 0xf805d000, v68
	s_nop 1
	v_addc_co_u32_e32 v69, vcc, -1, v69, vcc
	global_store_dwordx4 v[68:69], v[48:51], off offset:-3968 sc1
	s_and_b64 vcc, exec, s[4:5]
	s_mov_b64 s[0:1], -1
	s_cbranch_vccz .LBB0_1180

; DI u16 f2bf(float x) { return (u16)(cvtpk(x, 0.f) & 0xffffu); }
; template <int EPI>
; DI void gemm_epilogue(const Params& p, f32x4 (&acc)[8][4], int m0, int n0, int wr, int wc, int fr, int fq, u16* Cb, int ldc) {
;     ...
; #pragma clang loop unroll(full)
;         for (int m = 0; m < 8; ++m) {
;           const int row = rbase + m * 16;
;           if (!smp) {
;             *(f32x4*)(p.out + O_AVP + (size_t)row * 2048 + c) = acc[m][n];
; #pragma clang loop unroll(full)
;             for (int j = 0; j < 4; ++j) p.VAT[(size_t)(c + j) * MP + row] = f2bf(acc[m][n][j]);
;           } else *(f32x4*)(p.out + O_AVS + (size_t)(row - MP) * 2048 + c) = acc[m][n];
.LBB0_1196:
	v_lshlrev_b64 v[68:69], 13, v[130:131]
	v_lshl_add_u64 v[68:69], s[62:63], 0, v[68:69]
	v_lshl_add_u64 v[70:71], v[128:129], 0, v[160:161]
	v_lshl_add_u64 v[68:69], v[70:71], 2, v[68:69]
	v_add_co_u32_e32 v68, vcc, 0xf807d000, v68
	s_nop 1
	v_addc_co_u32_e32 v69, vcc, -1, v69, vcc
	global_store_dwordx4 v[68:69], v[44:47], off offset:-3968 sc1
	s_and_b64 vcc, exec, s[4:5]
	s_mov_b64 s[0:1], -1
	s_cbranch_vccz .LBB0_1182

; DI u16 f2bf(float x) { return (u16)(cvtpk(x, 0.f) & 0xffffu); }
; template <int EPI>
; DI void gemm_epilogue(const Params& p, f32x4 (&acc)[8][4], int m0, int n0, int wr, int wc, int fr, int fq, u16* Cb, int ldc) {
;     ...
; #pragma clang loop unroll(full)
;         for (int m = 0; m < 8; ++m) {
;           const int row = rbase + m * 16;
;           if (!smp) {
;             *(f32x4*)(p.out + O_AVP + (size_t)row * 2048 + c) = acc[m][n];
; #pragma clang loop unroll(full)
;             for (int j = 0; j < 4; ++j) p.VAT[(size_t)(c + j) * MP + row] = f2bf(acc[m][n][j]);
;           } else *(f32x4*)(p.out + O_AVS + (size_t)(row - MP) * 2048 + c) = acc[m][n];
.LBB0_1198:
	v_lshlrev_b64 v[68:69], 13, v[130:131]
	v_lshl_add_u64 v[68:69], s[62:63], 0, v[68:69]
	v_lshl_add_u64 v[70:71], v[128:129], 0, v[160:161]
	v_lshl_add_u64 v[68:69], v[70:71], 2, v[68:69]
	v_add_co_u32_e32 v68, vcc, 0xf809d000, v68
	s_nop 1
	v_addc_co_u32_e32 v69, vcc, -1, v69, vcc
	global_store_dwordx4 v[68:69], v[40:43], off offset:-3968 sc1
	s_and_b64 vcc, exec, s[4:5]
	s_mov_b64 s[0:1], -1
	s_cbranch_vccz .LBB0_1184

; DI u16 f2bf(float x) { return (u16)(cvtpk(x, 0.f) & 0xffffu); }
; template <int EPI>
; DI void gemm_epilogue(const Params& p, f32x4 (&acc)[8][4], int m0, int n0, int wr, int wc, int fr, int fq, u16* Cb, int ldc) {
;     ...
; #pragma clang loop unroll(full)
;         for (int m = 0; m < 8; ++m) {
;           const int row = rbase + m * 16;
;           if (!smp) {
;             *(f32x4*)(p.out + O_AVP + (size_t)row * 2048 + c) = acc[m][n];
; #pragma clang loop unroll(full)
;             for (int j = 0; j < 4; ++j) p.VAT[(size_t)(c + j) * MP + row] = f2bf(acc[m][n][j]);
;           } else *(f32x4*)(p.out + O_AVS + (size_t)(row - MP) * 2048 + c) = acc[m][n];
.LBB0_1200:
	v_lshlrev_b64 v[68:69], 13, v[130:131]
	v_lshl_add_u64 v[68:69], s[62:63], 0, v[68:69]
	v_lshl_add_u64 v[70:71], v[128:129], 0, v[160:161]
	v_lshl_add_u64 v[68:69], v[70:71], 2, v[68:69]
	v_add_co_u32_e32 v68, vcc, 0xf80bd000, v68
	s_nop 1
	v_addc_co_u32_e32 v69, vcc, -1, v69, vcc
	global_store_dwordx4 v[68:69], v[36:39], off offset:-3968 sc1
	s_and_b64 vcc, exec, s[4:5]
	s_mov_b64 s[0:1], -1
	s_cbranch_vccz .LBB0_1186

; DI u16 f2bf(float x) { return (u16)(cvtpk(x, 0.f) & 0xffffu); }
; template <int EPI>
; DI void gemm_epilogue(const Params& p, f32x4 (&acc)[8][4], int m0, int n0, int wr, int wc, int fr, int fq, u16* Cb, int ldc) {
;     ...
; #pragma clang loop unroll(full)
;         for (int m = 0; m < 8; ++m) {
;           const int row = rbase + m * 16;
;           if (!smp) {
;             *(f32x4*)(p.out + O_AVP + (size_t)row * 2048 + c) = acc[m][n];
; #pragma clang loop unroll(full)
;             for (int j = 0; j < 4; ++j) p.VAT[(size_t)(c + j) * MP + row] = f2bf(acc[m][n][j]);
;           } else *(f32x4*)(p.out + O_AVS + (size_t)(row - MP) * 2048 + c) = acc[m][n];
.LBB0_1202:
	v_lshlrev_b64 v[64:65], 13, v[130:131]
	v_lshl_add_u64 v[64:65], s[62:63], 0, v[64:65]
	v_lshl_add_u64 v[66:67], v[128:129], 0, v[160:161]
	v_lshl_add_u64 v[64:65], v[66:67], 2, v[64:65]
	v_add_co_u32_e32 v64, vcc, 0xf80dd000, v64
	s_nop 1
	v_addc_co_u32_e32 v65, vcc, -1, v65, vcc
	global_store_dwordx4 v[64:65], v[32:35], off offset:-3968 sc1

; DI u32x2 pack4(f32x4 v) { u32x2 r; r[0] = cvtpk(v[0], v[1]); r[1] = cvtpk(v[2], v[3]); return r; }
; template <int EPI>
; DI void gemm_epilogue(const Params& p, f32x4 (&acc)[8][4], int m0, int n0, int wr, int wc, int fr, int fq, u16* Cb, int ldc) {
;     ...
;         for (int m = 0; m < 8; ++m) {
;           const int row = rbase + m * 16;
;           if (!smp) { *(f32x4*)(p.out + O_AKP + (size_t)row * 2048 + c) = acc[m][n]; *(u32x2*)(p.KA + (size_t)row * 2048 + c) = pack4(acc[m][n]); }
;           else *(f32x4*)(p.out + O_AKS + (size_t)(row - MP) * 2048 + c) = acc[m][n];
;         }
.LBB0_1204:
	s_andn2_b64 vcc, exec, s[0:1]
	s_cbranch_vccnz .LBB0_1237
	v_cndmask_b32_e64 v64, 0, 1, s[88:89]
	v_cmp_ne_u32_e64 s[4:5], 1, v64
	s_andn2_b64 vcc, exec, s[88:89]
	s_mov_b64 s[0:1], -1
	s_cbranch_vccnz .LBB0_1221
	v_lshlrev_b64 v[64:65], 13, v[130:131]
	v_lshl_add_u64 v[66:67], v[128:129], 0, v[160:161]
	v_lshl_add_u64 v[64:65], s[8:9], 0, v[64:65]
	v_lshl_add_u64 v[66:67], v[66:67], 0, s[96:97]
	v_lshlrev_b64 v[68:69], 12, v[130:131]
	v_lshl_add_u64 v[64:65], v[66:67], 2, v[64:65]
	v_lshl_add_u64 v[68:69], s[46:47], 0, v[68:69]
	global_store_dwordx4 v[64:65], v[60:63], off offset:128 sc1
	v_cvt_pk_bf16_f32 v64, v60, v61
	v_cvt_pk_bf16_f32 v65, v62, v63
	v_lshl_add_u64 v[66:67], v[66:67], 1, v[68:69]
	global_store_dwordx2 v[66:67], v[64:65], off offset:64
	s_cbranch_execz .LBB0_1222

; DI u32x2 pack4(f32x4 v) { u32x2 r; r[0] = cvtpk(v[0], v[1]); r[1] = cvtpk(v[2], v[3]); return r; }
; template <int EPI>
; DI void gemm_epilogue(const Params& p, f32x4 (&acc)[8][4], int m0, int n0, int wr, int wc, int fr, int fq, u16* Cb, int ldc) {
;     ...
;         for (int m = 0; m < 8; ++m) {
;           const int row = rbase + m * 16;
;           if (!smp) { *(f32x4*)(p.out + O_AKP + (size_t)row * 2048 + c) = acc[m][n]; *(u32x2*)(p.KA + (size_t)row * 2048 + c) = pack4(acc[m][n]); }
;           else *(f32x4*)(p.out + O_AKS + (size_t)(row - MP) * 2048 + c) = acc[m][n];
;         }
.LBB0_1208:
	v_lshlrev_b64 v[64:65], 13, v[146:147]
	v_lshl_add_u64 v[66:67], v[128:129], 0, v[160:161]
	v_lshl_add_u64 v[64:65], s[8:9], 0, v[64:65]
	v_lshl_add_u64 v[66:67], v[66:67], 0, s[96:97]
	v_lshlrev_b64 v[68:69], 12, v[146:147]
	v_lshl_add_u64 v[64:65], v[66:67], 2, v[64:65]
	v_lshl_add_u64 v[68:69], s[46:47], 0, v[68:69]
	global_store_dwordx4 v[64:65], v[56:59], off offset:128 sc1
	v_cvt_pk_bf16_f32 v64, v56, v57
	v_cvt_pk_bf16_f32 v65, v58, v59
	v_lshl_add_u64 v[66:67], v[66:67], 1, v[68:69]
	global_store_dwordx2 v[66:67], v[64:65], off offset:64
	s_cbranch_execz .LBB0_1224

; DI u32x2 pack4(f32x4 v) { u32x2 r; r[0] = cvtpk(v[0], v[1]); r[1] = cvtpk(v[2], v[3]); return r; }
; template <int EPI>
; DI void gemm_epilogue(const Params& p, f32x4 (&acc)[8][4], int m0, int n0, int wr, int wc, int fr, int fq, u16* Cb, int ldc) {
;     ...
;       } else if (colt < 4096) {
;         const int c = col - 2048;
; #pragma clang loop unroll(full)
;         for (int m = 0; m < 8; ++m) {
;           const int row = rbase + m * 16;
;           if (!smp) { *(f32x4*)(p.out + O_AKP + (size_t)row * 2048 + c) = acc[m][n]; *(u32x2*)(p.KA + (size_t)row * 2048 + c) = pack4(acc[m][n]); }
;           else *(f32x4*)(p.out + O_AKS + (size_t)(row - MP) * 2048 + c) = acc[m][n];
;         }
.LBB0_1210:
	v_lshlrev_b64 v[64:65], 13, v[144:145]
	v_lshl_add_u64 v[66:67], v[128:129], 0, v[160:161]
	v_lshl_add_u64 v[64:65], s[8:9], 0, v[64:65]
	v_lshl_add_u64 v[66:67], v[66:67], 0, s[96:97]
	v_lshlrev_b64 v[68:69], 12, v[144:145]
	v_lshl_add_u64 v[64:65], v[66:67], 2, v[64:65]
	v_lshl_add_u64 v[68:69], s[46:47], 0, v[68:69]
	global_store_dwordx4 v[64:65], v[52:55], off offset:128 sc1
	v_cvt_pk_bf16_f32 v64, v52, v53
	v_cvt_pk_bf16_f32 v65, v54, v55
	v_lshl_add_u64 v[66:67], v[66:67], 1, v[68:69]
	global_store_dwordx2 v[66:67], v[64:65], off offset:64
	s_cbranch_execz .LBB0_1226

; DI u32x2 pack4(f32x4 v) { u32x2 r; r[0] = cvtpk(v[0], v[1]); r[1] = cvtpk(v[2], v[3]); return r; }
; template <int EPI>
; DI void gemm_epilogue(const Params& p, f32x4 (&acc)[8][4], int m0, int n0, int wr, int wc, int fr, int fq, u16* Cb, int ldc) {
;     ...
;       } else if (colt < 4096) {
;         const int c = col - 2048;
; #pragma clang loop unroll(full)
;         for (int m = 0; m < 8; ++m) {
;           const int row = rbase + m * 16;
;           if (!smp) { *(f32x4*)(p.out + O_AKP + (size_t)row * 2048 + c) = acc[m][n]; *(u32x2*)(p.KA + (size_t)row * 2048 + c) = pack4(acc[m][n]); }
;           else *(f32x4*)(p.out + O_AKS + (size_t)(row - MP) * 2048 + c) = acc[m][n];
;         }
.LBB0_1212:
	v_lshlrev_b64 v[64:65], 13, v[142:143]
	v_lshl_add_u64 v[66:67], v[128:129], 0, v[160:161]
	v_lshl_add_u64 v[64:65], s[8:9], 0, v[64:65]
	v_lshl_add_u64 v[66:67], v[66:67], 0, s[96:97]
	v_lshlrev_b64 v[68:69], 12, v[142:143]
	v_lshl_add_u64 v[64:65], v[66:67], 2, v[64:65]
	v_lshl_add_u64 v[68:69], s[46:47], 0, v[68:69]
	global_store_dwordx4 v[64:65], v[48:51], off offset:128 sc1
	v_cvt_pk_bf16_f32 v64, v48, v49
	v_cvt_pk_bf16_f32 v65, v50, v51
	v_lshl_add_u64 v[66:67], v[66:67], 1, v[68:69]
	global_store_dwordx2 v[66:67], v[64:65], off offset:64
	s_cbranch_execz .LBB0_1228

; DI u32x2 pack4(f32x4 v) { u32x2 r; r[0] = cvtpk(v[0], v[1]); r[1] = cvtpk(v[2], v[3]); return r; }
; template <int EPI>
; DI void gemm_epilogue(const Params& p, f32x4 (&acc)[8][4], int m0, int n0, int wr, int wc, int fr, int fq, u16* Cb, int ldc) {
;     ...
;       } else if (colt < 4096) {
;         const int c = col - 2048;
; #pragma clang loop unroll(full)
;         for (int m = 0; m < 8; ++m) {
;           const int row = rbase + m * 16;
;           if (!smp) { *(f32x4*)(p.out + O_AKP + (size_t)row * 2048 + c) = acc[m][n]; *(u32x2*)(p.KA + (size_t)row * 2048 + c) = pack4(acc[m][n]); }
;           else *(f32x4*)(p.out + O_AKS + (size_t)(row - MP) * 2048 + c) = acc[m][n];
;         }
.LBB0_1214:
	v_lshlrev_b64 v[64:65], 13, v[140:141]
	v_lshl_add_u64 v[66:67], v[128:129], 0, v[160:161]
	v_lshl_add_u64 v[64:65], s[8:9], 0, v[64:65]
	v_lshl_add_u64 v[66:67], v[66:67], 0, s[96:97]
	v_lshlrev_b64 v[68:69], 12, v[140:141]
	v_lshl_add_u64 v[64:65], v[66:67], 2, v[64:65]
	v_lshl_add_u64 v[68:69], s[46:47], 0, v[68:69]
	global_store_dwordx4 v[64:65], v[44:47], off offset:128 sc1
	v_cvt_pk_bf16_f32 v64, v44, v45
	v_cvt_pk_bf16_f32 v65, v46, v47
	v_lshl_add_u64 v[66:67], v[66:67], 1, v[68:69]
	global_store_dwordx2 v[66:67], v[64:65], off offset:64
	s_cbranch_execz .LBB0_1230

; DI u32x2 pack4(f32x4 v) { u32x2 r; r[0] = cvtpk(v[0], v[1]); r[1] = cvtpk(v[2], v[3]); return r; }
; template <int EPI>
; DI void gemm_epilogue(const Params& p, f32x4 (&acc)[8][4], int m0, int n0, int wr, int wc, int fr, int fq, u16* Cb, int ldc) {
;     ...
;       } else if (colt < 4096) {
;         const int c = col - 2048;
; #pragma clang loop unroll(full)
;         for (int m = 0; m < 8; ++m) {
;           const int row = rbase + m * 16;
;           if (!smp) { *(f32x4*)(p.out + O_AKP + (size_t)row * 2048 + c) = acc[m][n]; *(u32x2*)(p.KA + (size_t)row * 2048 + c) = pack4(acc[m][n]); }
;           else *(f32x4*)(p.out + O_AKS + (size_t)(row - MP) * 2048 + c) = acc[m][n];
;         }
.LBB0_1216:
	v_lshlrev_b64 v[64:65], 13, v[138:139]
	v_lshl_add_u64 v[66:67], v[128:129], 0, v[160:161]
	v_lshl_add_u64 v[64:65], s[8:9], 0, v[64:65]
	v_lshl_add_u64 v[66:67], v[66:67], 0, s[96:97]
	v_lshlrev_b64 v[68:69], 12, v[138:139]
	v_lshl_add_u64 v[64:65], v[66:67], 2, v[64:65]
	v_lshl_add_u64 v[68:69], s[46:47], 0, v[68:69]
	global_store_dwordx4 v[64:65], v[40:43], off offset:128 sc1
	v_cvt_pk_bf16_f32 v64, v40, v41
	v_cvt_pk_bf16_f32 v65, v42, v43
	v_lshl_add_u64 v[66:67], v[66:67], 1, v[68:69]
	global_store_dwordx2 v[66:67], v[64:65], off offset:64
	s_cbranch_execz .LBB0_1232

; DI u32x2 pack4(f32x4 v) { u32x2 r; r[0] = cvtpk(v[0], v[1]); r[1] = cvtpk(v[2], v[3]); return r; }
; template <int EPI>
; DI void gemm_epilogue(const Params& p, f32x4 (&acc)[8][4], int m0, int n0, int wr, int wc, int fr, int fq, u16* Cb, int ldc) {
;     ...
;       } else if (colt < 4096) {
;         const int c = col - 2048;
; #pragma clang loop unroll(full)
;         for (int m = 0; m < 8; ++m) {
;           const int row = rbase + m * 16;
;           if (!smp) { *(f32x4*)(p.out + O_AKP + (size_t)row * 2048 + c) = acc[m][n]; *(u32x2*)(p.KA + (size_t)row * 2048 + c) = pack4(acc[m][n]); }
;           else *(f32x4*)(p.out + O_AKS + (size_t)(row - MP) * 2048 + c) = acc[m][n];
;         }
.LBB0_1218:
	v_lshlrev_b64 v[64:65], 13, v[136:137]
	v_lshl_add_u64 v[66:67], v[128:129], 0, v[160:161]
	v_lshl_add_u64 v[64:65], s[8:9], 0, v[64:65]
	v_lshl_add_u64 v[66:67], v[66:67], 0, s[96:97]
	v_lshlrev_b64 v[68:69], 12, v[136:137]
	v_lshl_add_u64 v[64:65], v[66:67], 2, v[64:65]
	v_lshl_add_u64 v[68:69], s[46:47], 0, v[68:69]
	global_store_dwordx4 v[64:65], v[36:39], off offset:128 sc1
	v_cvt_pk_bf16_f32 v64, v36, v37
	v_cvt_pk_bf16_f32 v65, v38, v39
	v_lshl_add_u64 v[66:67], v[66:67], 1, v[68:69]
	global_store_dwordx2 v[66:67], v[64:65], off offset:64
	s_cbranch_execz .LBB0_1234

; DI u32x2 pack4(f32x4 v) { u32x2 r; r[0] = cvtpk(v[0], v[1]); r[1] = cvtpk(v[2], v[3]); return r; }
; template <int EPI>
; DI void gemm_epilogue(const Params& p, f32x4 (&acc)[8][4], int m0, int n0, int wr, int wc, int fr, int fq, u16* Cb, int ldc) {
;     ...
;       } else if (colt < 4096) {
;         const int c = col - 2048;
; #pragma clang loop unroll(full)
;         for (int m = 0; m < 8; ++m) {
;           const int row = rbase + m * 16;
;           if (!smp) { *(f32x4*)(p.out + O_AKP + (size_t)row * 2048 + c) = acc[m][n]; *(u32x2*)(p.KA + (size_t)row * 2048 + c) = pack4(acc[m][n]); }
;           else *(f32x4*)(p.out + O_AKS + (size_t)(row - MP) * 2048 + c) = acc[m][n];
;         }
.LBB0_1220:
	v_lshlrev_b64 v[64:65], 13, v[134:135]
	v_lshl_add_u64 v[66:67], v[128:129], 0, v[160:161]
	v_lshl_add_u64 v[64:65], s[8:9], 0, v[64:65]
	v_lshl_add_u64 v[66:67], v[66:67], 0, s[96:97]
	v_lshlrev_b64 v[68:69], 12, v[134:135]
	v_lshl_add_u64 v[64:65], v[66:67], 2, v[64:65]
	v_lshl_add_u64 v[68:69], s[46:47], 0, v[68:69]
	global_store_dwordx4 v[64:65], v[32:35], off offset:128 sc1
	v_cvt_pk_bf16_f32 v64, v32, v33
	v_cvt_pk_bf16_f32 v65, v34, v35
	v_lshl_add_u64 v[66:67], v[66:67], 1, v[68:69]
	global_store_dwordx2 v[66:67], v[64:65], off offset:64
	s_cbranch_execz .LBB0_1236
	s_branch .LBB0_1237

; DI u32x2 pack4(f32x4 v) { u32x2 r; r[0] = cvtpk(v[0], v[1]); r[1] = cvtpk(v[2], v[3]); return r; }
; template <int EPI>
; DI void gemm_epilogue(const Params& p, f32x4 (&acc)[8][4], int m0, int n0, int wr, int wc, int fr, int fq, u16* Cb, int ldc) {
;     ...
; #pragma clang loop unroll(full)
;         for (int m = 0; m < 8; ++m) {
;           const int row = rbase + m * 16;
;           if (!smp) { *(f32x4*)(p.out + O_AKP + (size_t)row * 2048 + c) = acc[m][n]; *(u32x2*)(p.KA + (size_t)row * 2048 + c) = pack4(acc[m][n]); }
;           else *(f32x4*)(p.out + O_AKS + (size_t)(row - MP) * 2048 + c) = acc[m][n];
.LBB0_1222:
	v_lshlrev_b64 v[64:65], 13, v[130:131]
	v_lshl_add_u64 v[64:65], s[64:65], 0, v[64:65]
	v_lshl_add_u64 v[66:67], v[128:129], 0, v[160:161]
	v_lshl_add_u64 v[64:65], v[66:67], 2, v[64:65]
	v_add_co_u32_e32 v64, vcc, 0xf7fff000, v64
	s_nop 1
	v_addc_co_u32_e32 v65, vcc, -1, v65, vcc
	global_store_dwordx4 v[64:65], v[60:63], off offset:-3968 sc1
	s_and_b64 vcc, exec, s[4:5]
	s_mov_b64 s[0:1], -1
	s_cbranch_vccz .LBB0_1208

; DI u32x2 pack4(f32x4 v) { u32x2 r; r[0] = cvtpk(v[0], v[1]); r[1] = cvtpk(v[2], v[3]); return r; }
; template <int EPI>
; DI void gemm_epilogue(const Params& p, f32x4 (&acc)[8][4], int m0, int n0, int wr, int wc, int fr, int fq, u16* Cb, int ldc) {
;     ...
; #pragma clang loop unroll(full)
;         for (int m = 0; m < 8; ++m) {
;           const int row = rbase + m * 16;
;           if (!smp) { *(f32x4*)(p.out + O_AKP + (size_t)row * 2048 + c) = acc[m][n]; *(u32x2*)(p.KA + (size_t)row * 2048 + c) = pack4(acc[m][n]); }
;           else *(f32x4*)(p.out + O_AKS + (size_t)(row - MP) * 2048 + c) = acc[m][n];
.LBB0_1224:
	v_lshlrev_b64 v[64:65], 13, v[130:131]
	v_lshl_add_u64 v[64:65], s[64:65], 0, v[64:65]
	v_lshl_add_u64 v[66:67], v[128:129], 0, v[160:161]
	v_lshl_add_u64 v[64:65], v[66:67], 2, v[64:65]
	v_add_co_u32_e32 v64, vcc, 0xf801f000, v64
	s_nop 1
	v_addc_co_u32_e32 v65, vcc, -1, v65, vcc
	global_store_dwordx4 v[64:65], v[56:59], off offset:-3968 sc1
	s_and_b64 vcc, exec, s[4:5]
	s_mov_b64 s[0:1], -1
	s_cbranch_vccz .LBB0_1210

; DI u32x2 pack4(f32x4 v) { u32x2 r; r[0] = cvtpk(v[0], v[1]); r[1] = cvtpk(v[2], v[3]); return r; }
; template <int EPI>
; DI void gemm_epilogue(const Params& p, f32x4 (&acc)[8][4], int m0, int n0, int wr, int wc, int fr, int fq, u16* Cb, int ldc) {
;     ...
; #pragma clang loop unroll(full)
;         for (int m = 0; m < 8; ++m) {
;           const int row = rbase + m * 16;
;           if (!smp) { *(f32x4*)(p.out + O_AKP + (size_t)row * 2048 + c) = acc[m][n]; *(u32x2*)(p.KA + (size_t)row * 2048 + c) = pack4(acc[m][n]); }
;           else *(f32x4*)(p.out + O_AKS + (size_t)(row - MP) * 2048 + c) = acc[m][n];
.LBB0_1226:
	v_lshlrev_b64 v[64:65], 13, v[130:131]
	v_lshl_add_u64 v[64:65], s[64:65], 0, v[64:65]
	v_lshl_add_u64 v[66:67], v[128:129], 0, v[160:161]
	v_lshl_add_u64 v[64:65], v[66:67], 2, v[64:65]
	v_add_co_u32_e32 v64, vcc, 0xf803f000, v64
	s_nop 1
	v_addc_co_u32_e32 v65, vcc, -1, v65, vcc
	global_store_dwordx4 v[64:65], v[52:55], off offset:-3968 sc1
	s_and_b64 vcc, exec, s[4:5]
	s_mov_b64 s[0:1], -1
	s_cbranch_vccz .LBB0_1212

; DI u32x2 pack4(f32x4 v) { u32x2 r; r[0] = cvtpk(v[0], v[1]); r[1] = cvtpk(v[2], v[3]); return r; }
; template <int EPI>
; DI void gemm_epilogue(const Params& p, f32x4 (&acc)[8][4], int m0, int n0, int wr, int wc, int fr, int fq, u16* Cb, int ldc) {
;     ...
; #pragma clang loop unroll(full)
;         for (int m = 0; m < 8; ++m) {
;           const int row = rbase + m * 16;
;           if (!smp) { *(f32x4*)(p.out + O_AKP + (size_t)row * 2048 + c) = acc[m][n]; *(u32x2*)(p.KA + (size_t)row * 2048 + c) = pack4(acc[m][n]); }
;           else *(f32x4*)(p.out + O_AKS + (size_t)(row - MP) * 2048 + c) = acc[m][n];
.LBB0_1228:
	v_lshlrev_b64 v[64:65], 13, v[130:131]
	v_lshl_add_u64 v[64:65], s[64:65], 0, v[64:65]
	v_lshl_add_u64 v[66:67], v[128:129], 0, v[160:161]
	v_lshl_add_u64 v[64:65], v[66:67], 2, v[64:65]
	v_add_co_u32_e32 v64, vcc, 0xf805f000, v64
	s_nop 1
	v_addc_co_u32_e32 v65, vcc, -1, v65, vcc
	global_store_dwordx4 v[64:65], v[48:51], off offset:-3968 sc1
	s_and_b64 vcc, exec, s[4:5]
	s_mov_b64 s[0:1], -1
	s_cbranch_vccz .LBB0_1214

; DI u32x2 pack4(f32x4 v) { u32x2 r; r[0] = cvtpk(v[0], v[1]); r[1] = cvtpk(v[2], v[3]); return r; }
; template <int EPI>
; DI void gemm_epilogue(const Params& p, f32x4 (&acc)[8][4], int m0, int n0, int wr, int wc, int fr, int fq, u16* Cb, int ldc) {
;     ...
; #pragma clang loop unroll(full)
;         for (int m = 0; m < 8; ++m) {
;           const int row = rbase + m * 16;
;           if (!smp) { *(f32x4*)(p.out + O_AKP + (size_t)row * 2048 + c) = acc[m][n]; *(u32x2*)(p.KA + (size_t)row * 2048 + c) = pack4(acc[m][n]); }
;           else *(f32x4*)(p.out + O_AKS + (size_t)(row - MP) * 2048 + c) = acc[m][n];
.LBB0_1230:
	v_lshlrev_b64 v[64:65], 13, v[130:131]
	v_lshl_add_u64 v[64:65], s[64:65], 0, v[64:65]
	v_lshl_add_u64 v[66:67], v[128:129], 0, v[160:161]
	v_lshl_add_u64 v[64:65], v[66:67], 2, v[64:65]
	v_add_co_u32_e32 v64, vcc, 0xf807f000, v64
	s_nop 1
	v_addc_co_u32_e32 v65, vcc, -1, v65, vcc
	global_store_dwordx4 v[64:65], v[44:47], off offset:-3968 sc1
	s_and_b64 vcc, exec, s[4:5]
	s_mov_b64 s[0:1], -1
	s_cbranch_vccz .LBB0_1216

; DI u32x2 pack4(f32x4 v) { u32x2 r; r[0] = cvtpk(v[0], v[1]); r[1] = cvtpk(v[2], v[3]); return r; }
; template <int EPI>
; DI void gemm_epilogue(const Params& p, f32x4 (&acc)[8][4], int m0, int n0, int wr, int wc, int fr, int fq, u16* Cb, int ldc) {
;     ...
; #pragma clang loop unroll(full)
;         for (int m = 0; m < 8; ++m) {
;           const int row = rbase + m * 16;
;           if (!smp) { *(f32x4*)(p.out + O_AKP + (size_t)row * 2048 + c) = acc[m][n]; *(u32x2*)(p.KA + (size_t)row * 2048 + c) = pack4(acc[m][n]); }
;           else *(f32x4*)(p.out + O_AKS + (size_t)(row - MP) * 2048 + c) = acc[m][n];
.LBB0_1232:
	v_lshlrev_b64 v[64:65], 13, v[130:131]
	v_lshl_add_u64 v[64:65], s[64:65], 0, v[64:65]
	v_lshl_add_u64 v[66:67], v[128:129], 0, v[160:161]
	v_lshl_add_u64 v[64:65], v[66:67], 2, v[64:65]
	v_add_co_u32_e32 v64, vcc, 0xf809f000, v64
	s_nop 1
	v_addc_co_u32_e32 v65, vcc, -1, v65, vcc
	global_store_dwordx4 v[64:65], v[40:43], off offset:-3968 sc1
	s_and_b64 vcc, exec, s[4:5]
	s_mov_b64 s[0:1], -1
	s_cbranch_vccz .LBB0_1218

; DI u32x2 pack4(f32x4 v) { u32x2 r; r[0] = cvtpk(v[0], v[1]); r[1] = cvtpk(v[2], v[3]); return r; }
; template <int EPI>
; DI void gemm_epilogue(const Params& p, f32x4 (&acc)[8][4], int m0, int n0, int wr, int wc, int fr, int fq, u16* Cb, int ldc) {
;     ...
; #pragma clang loop unroll(full)
;         for (int m = 0; m < 8; ++m) {
;           const int row = rbase + m * 16;
;           if (!smp) { *(f32x4*)(p.out + O_AKP + (size_t)row * 2048 + c) = acc[m][n]; *(u32x2*)(p.KA + (size_t)row * 2048 + c) = pack4(acc[m][n]); }
;           else *(f32x4*)(p.out + O_AKS + (size_t)(row - MP) * 2048 + c) = acc[m][n];
.LBB0_1234:
	v_lshlrev_b64 v[64:65], 13, v[130:131]
	v_lshl_add_u64 v[64:65], s[64:65], 0, v[64:65]
	v_lshl_add_u64 v[66:67], v[128:129], 0, v[160:161]
	v_lshl_add_u64 v[64:65], v[66:67], 2, v[64:65]
	v_add_co_u32_e32 v64, vcc, 0xf80bf000, v64
	s_nop 1
	v_addc_co_u32_e32 v65, vcc, -1, v65, vcc
	global_store_dwordx4 v[64:65], v[36:39], off offset:-3968 sc1
	s_and_b64 vcc, exec, s[4:5]
	s_mov_b64 s[0:1], -1
	s_cbranch_vccz .LBB0_1220

; DI u32x2 pack4(f32x4 v) { u32x2 r; r[0] = cvtpk(v[0], v[1]); r[1] = cvtpk(v[2], v[3]); return r; }
; template <int EPI>
; DI void gemm_epilogue(const Params& p, f32x4 (&acc)[8][4], int m0, int n0, int wr, int wc, int fr, int fq, u16* Cb, int ldc) {
;     ...
; #pragma clang loop unroll(full)
;         for (int m = 0; m < 8; ++m) {
;           const int row = rbase + m * 16;
;           if (!smp) { *(f32x4*)(p.out + O_AKP + (size_t)row * 2048 + c) = acc[m][n]; *(u32x2*)(p.KA + (size_t)row * 2048 + c) = pack4(acc[m][n]); }
;           else *(f32x4*)(p.out + O_AKS + (size_t)(row - MP) * 2048 + c) = acc[m][n];
.LBB0_1236:
	v_lshlrev_b64 v[64:65], 13, v[130:131]
	v_lshl_add_u64 v[64:65], s[64:65], 0, v[64:65]
	v_lshl_add_u64 v[66:67], v[128:129], 0, v[160:161]
	v_lshl_add_u64 v[64:65], v[66:67], 2, v[64:65]
	v_add_co_u32_e32 v64, vcc, 0xf80df000, v64
	s_nop 1
	v_addc_co_u32_e32 v65, vcc, -1, v65, vcc
	global_store_dwordx4 v[64:65], v[32:35], off offset:-3968 sc1

; template <int EPI>
; DI void gemm_epilogue(const Params& p, f32x4 (&acc)[8][4], int m0, int n0, int wr, int wc, int fr, int fq, u16* Cb, int ldc) {
;     ...
;       } else if (colt < 8080) {
; #pragma clang loop unroll(full)
;         for (int m = 0; m < 8; ++m) *(f32x4*)(p.out + O_Y + (size_t)(rbase + m * 16) * ZRW + (col - 7248)) = acc[m][n];
.LBB0_1248:
	s_andn2_saveexec_b64 s[0:1], s[28:29]
	s_cbranch_execz .LBB0_1250
	v_readlane_b32 s12, v231, 6
	v_readlane_b32 s20, v231, 14
	v_readlane_b32 s21, v231, 15
	v_add_u32_e32 v38, v128, v160
	v_mov_b32_e32 v39, v161
	v_mov_b64_e32 v[32:33], s[20:21]
	v_mad_i64_i32 v[36:37], s[28:29], v130, s86, v[32:33]
	v_lshlrev_b64 v[38:39], 2, v[38:39]
	v_lshl_add_u64 v[36:37], v[36:37], 0, v[38:39]
	v_add_co_u32_e32 v36, vcc, 0xffff9000, v36
	v_readlane_b32 s13, v231, 7
	s_nop 0
	v_addc_co_u32_e32 v37, vcc, -1, v37, vcc
	global_store_dwordx4 v[36:37], v[28:31], off offset:-128 sc1
	v_mad_i64_i32 v[36:37], s[28:29], v146, s86, v[32:33]
	v_lshl_add_u64 v[36:37], v[36:37], 0, v[38:39]
	v_add_co_u32_e32 v36, vcc, 0xffff9000, v36
	v_readlane_b32 s14, v231, 8
	s_nop 0
	v_addc_co_u32_e32 v37, vcc, -1, v37, vcc
	global_store_dwordx4 v[36:37], v[24:27], off offset:-128 sc1
	v_mad_i64_i32 v[36:37], s[28:29], v144, s86, v[32:33]
	v_lshl_add_u64 v[36:37], v[36:37], 0, v[38:39]
	v_add_co_u32_e32 v36, vcc, 0xffff9000, v36
	v_readlane_b32 s15, v231, 9
	s_nop 0
	v_addc_co_u32_e32 v37, vcc, -1, v37, vcc
	global_store_dwordx4 v[36:37], v[20:23], off offset:-128 sc1
	v_mad_i64_i32 v[36:37], s[28:29], v142, s86, v[32:33]
	v_lshl_add_u64 v[36:37], v[36:37], 0, v[38:39]
	v_add_co_u32_e32 v36, vcc, 0xffff9000, v36
	v_readlane_b32 s16, v231, 10
	s_nop 0
	v_addc_co_u32_e32 v37, vcc, -1, v37, vcc
	global_store_dwordx4 v[36:37], v[16:19], off offset:-128 sc1
	v_mad_i64_i32 v[36:37], s[28:29], v140, s86, v[32:33]
	v_lshl_add_u64 v[36:37], v[36:37], 0, v[38:39]
	v_add_co_u32_e32 v36, vcc, 0xffff9000, v36
	v_readlane_b32 s17, v231, 11
	s_nop 0
	v_addc_co_u32_e32 v37, vcc, -1, v37, vcc
	global_store_dwordx4 v[36:37], v[12:15], off offset:-128 sc1
	v_mad_i64_i32 v[36:37], s[28:29], v138, s86, v[32:33]
	v_lshl_add_u64 v[36:37], v[36:37], 0, v[38:39]
	v_add_co_u32_e32 v36, vcc, 0xffff9000, v36
	v_readlane_b32 s18, v231, 12
	s_nop 0
	v_addc_co_u32_e32 v37, vcc, -1, v37, vcc
	global_store_dwordx4 v[36:37], v[8:11], off offset:-128 sc1
	v_mad_i64_i32 v[36:37], s[28:29], v136, s86, v[32:33]
	v_lshl_add_u64 v[36:37], v[36:37], 0, v[38:39]
	v_add_co_u32_e32 v36, vcc, 0xffff9000, v36
	v_mad_i64_i32 v[32:33], s[28:29], v134, s86, v[32:33]
	s_nop 0
	v_addc_co_u32_e32 v37, vcc, -1, v37, vcc
	v_lshl_add_u64 v[32:33], v[32:33], 0, v[38:39]
	v_add_co_u32_e32 v32, vcc, 0xffff9000, v32
	v_readlane_b32 s19, v231, 13
	s_nop 0
	v_addc_co_u32_e32 v33, vcc, -1, v33, vcc
	v_readlane_b32 s22, v231, 16
	v_readlane_b32 s23, v231, 17
	v_readlane_b32 s24, v231, 18
	v_readlane_b32 s25, v231, 19
	v_readlane_b32 s26, v231, 20
	v_readlane_b32 s27, v231, 21
	global_store_dwordx4 v[36:37], v[4:7], off offset:-128 sc1
	global_store_dwordx4 v[32:33], v[0:3], off offset:-128 sc1

; DI u32x2 pack4(f32x4 v) { u32x2 r; r[0] = cvtpk(v[0], v[1]); r[1] = cvtpk(v[2], v[3]); return r; }
; template <int EPI>
; DI void gemm_epilogue(const Params& p, f32x4 (&acc)[8][4], int m0, int n0, int wr, int wc, int fr, int fq, u16* Cb, int ldc) {
;     ...
;       } else if (colt < 7232) {
;         const int c = col - 7168;
; #pragma clang loop unroll(full)
;         for (int m = 0; m < 8; ++m) {
;           const int row = rbase + m * 16;
;           if (!smp) *(f32x4*)(p.out + O_IDXP + (size_t)row * 64 + c) = acc[m][n];
;           else *(f32x4*)(p.out + O_IDXS + (size_t)(row - MP) * 64 + c) = acc[m][n];
;           *(u32x2*)(p.IXK + (size_t)krow_of(row) * 64 + c) = pack4(acc[m][n]);
;         }
.LBB0_1251:
	s_andn2_saveexec_b64 s[34:35], s[60:61]
	s_cbranch_execz .LBB0_1253
	s_and_b64 s[0:1], s[2:3], exec
	s_mov_b32 s0, 0x19e00000
	v_readlane_b32 s12, v231, 6
	s_cselect_b32 s0, s0, 0x18200000
	v_readlane_b32 s20, v231, 14
	v_add_u32_e32 v35, 0xffffc000, v130
	s_add_u32 s28, s20, s0
	s_movk_i32 s0, 0xe400
	v_cndmask_b32_e64 v32, v130, v35, s[2:3]
	v_lshl_add_u64 v[36:37], v[128:129], 0, v[160:161]
	s_mov_b32 s1, -1
	v_lshrrev_b32_e32 v35, 4, v35
	v_lshl_add_u64 v[36:37], v[36:37], 0, s[0:1]
	v_mad_u64_u32 v[40:41], s[0:1], v35, s94, v[132:133]
	s_movk_i32 s0, 0x4000
	s_nop 0
	v_cmp_gt_i32_e32 vcc, s0, v130
	v_readlane_b32 s13, v231, 7
	v_readlane_b32 s14, v231, 8
	v_readlane_b32 s15, v231, 9
	v_readlane_b32 s16, v231, 10
	v_readlane_b32 s17, v231, 11
	v_readlane_b32 s18, v231, 12
	v_readlane_b32 s19, v231, 13
	v_readlane_b32 s21, v231, 15
	v_readlane_b32 s22, v231, 16
	v_readlane_b32 s23, v231, 17
	v_readlane_b32 s24, v231, 18
	v_readlane_b32 s25, v231, 19
	v_readlane_b32 s26, v231, 20
	v_readlane_b32 s27, v231, 21
	v_ashrrev_i32_e32 v33, 31, v32
	v_cndmask_b32_e32 v40, v40, v130, vcc
	s_addc_u32 s29, s21, 0
	v_lshlrev_b64 v[32:33], 8, v[32:33]
	v_ashrrev_i32_e32 v41, 31, v40
	v_readlane_b32 s12, v231, 38
	v_lshl_add_u64 v[32:33], s[28:29], 0, v[32:33]
	v_lshlrev_b64 v[38:39], 2, v[36:37]
	v_lshlrev_b64 v[40:41], 7, v[40:41]
	v_readlane_b32 s13, v231, 39
	v_lshl_add_u64 v[32:33], v[32:33], 0, v[38:39]
	v_lshlrev_b64 v[36:37], 1, v[36:37]
	v_lshl_add_u64 v[40:41], s[12:13], 0, v[40:41]
	global_store_dwordx4 v[32:33], v[28:31], off offset:192 sc1
	v_cvt_pk_bf16_f32 v32, v28, v29
	v_cvt_pk_bf16_f32 v33, v30, v31
	v_lshl_add_u64 v[40:41], v[40:41], 0, v[36:37]
	v_add_u32_e32 v35, 0xffffc010, v130
	global_store_dwordx2 v[40:41], v[32:33], off offset:96
	v_cndmask_b32_e64 v32, v146, v35, s[2:3]
	v_lshrrev_b32_e32 v35, 4, v35
	v_mad_u64_u32 v[40:41], s[0:1], v35, s94, v[132:133]
	s_movk_i32 s0, 0x3ff0
	s_nop 0
	v_cmp_gt_i32_e32 vcc, s0, v130
	v_ashrrev_i32_e32 v33, 31, v32
	v_lshlrev_b64 v[32:33], 8, v[32:33]
	v_cndmask_b32_e32 v40, v40, v146, vcc
	v_ashrrev_i32_e32 v41, 31, v40
	v_lshl_add_u64 v[32:33], s[28:29], 0, v[32:33]
	v_lshlrev_b64 v[40:41], 7, v[40:41]
	v_lshl_add_u64 v[32:33], v[32:33], 0, v[38:39]
	v_lshl_add_u64 v[40:41], s[12:13], 0, v[40:41]
	global_store_dwordx4 v[32:33], v[24:27], off offset:192 sc1
	v_cvt_pk_bf16_f32 v32, v24, v25
	v_cvt_pk_bf16_f32 v33, v26, v27
	v_lshl_add_u64 v[40:41], v[40:41], 0, v[36:37]
	v_add_u32_e32 v35, 0xffffc020, v130
	global_store_dwordx2 v[40:41], v[32:33], off offset:96
	v_cndmask_b32_e64 v32, v144, v35, s[2:3]
	v_lshrrev_b32_e32 v35, 4, v35
	v_mad_u64_u32 v[40:41], s[0:1], v35, s94, v[132:133]
	s_movk_i32 s0, 0x3fe0
	s_nop 0
	v_cmp_gt_i32_e32 vcc, s0, v130
	v_ashrrev_i32_e32 v33, 31, v32
	v_lshlrev_b64 v[32:33], 8, v[32:33]
	v_cndmask_b32_e32 v40, v40, v144, vcc
	v_ashrrev_i32_e32 v41, 31, v40
	v_lshl_add_u64 v[32:33], s[28:29], 0, v[32:33]
	v_lshlrev_b64 v[40:41], 7, v[40:41]
	v_lshl_add_u64 v[32:33], v[32:33], 0, v[38:39]
	v_lshl_add_u64 v[40:41], s[12:13], 0, v[40:41]
	global_store_dwordx4 v[32:33], v[20:23], off offset:192 sc1
	v_cvt_pk_bf16_f32 v32, v20, v21
	v_cvt_pk_bf16_f32 v33, v22, v23
	v_lshl_add_u64 v[40:41], v[40:41], 0, v[36:37]
	v_add_u32_e32 v35, 0xffffc030, v130
	global_store_dwordx2 v[40:41], v[32:33], off offset:96
	v_cndmask_b32_e64 v32, v142, v35, s[2:3]
	v_lshrrev_b32_e32 v35, 4, v35
	v_mad_u64_u32 v[40:41], s[0:1], v35, s94, v[132:133]
	s_movk_i32 s0, 0x3fd0
	s_nop 0
	v_cmp_gt_i32_e32 vcc, s0, v130
	v_ashrrev_i32_e32 v33, 31, v32
	v_lshlrev_b64 v[32:33], 8, v[32:33]
	v_cndmask_b32_e32 v40, v40, v142, vcc
	v_ashrrev_i32_e32 v41, 31, v40
	v_lshl_add_u64 v[32:33], s[28:29], 0, v[32:33]
	v_lshlrev_b64 v[40:41], 7, v[40:41]
	v_lshl_add_u64 v[32:33], v[32:33], 0, v[38:39]
; DI u32x2 pack4(f32x4 v) { u32x2 r; r[0] = cvtpk(v[0], v[1]); r[1] = cvtpk(v[2], v[3]); return r; }
; template <int EPI>
; DI void gemm_epilogue(const Params& p, f32x4 (&acc)[8][4], int m0, int n0, int wr, int wc, int fr, int fq, u16* Cb, int ldc) {
;     ...
;       } else if (colt < 7232) {
;         const int c = col - 7168;
; #pragma clang loop unroll(full)
;         for (int m = 0; m < 8; ++m) {
;           const int row = rbase + m * 16;
;           if (!smp) *(f32x4*)(p.out + O_IDXP + (size_t)row * 64 + c) = acc[m][n];
;           else *(f32x4*)(p.out + O_IDXS + (size_t)(row - MP) * 64 + c) = acc[m][n];
;           *(u32x2*)(p.IXK + (size_t)krow_of(row) * 64 + c) = pack4(acc[m][n]);
;         }
	v_lshl_add_u64 v[40:41], s[12:13], 0, v[40:41]
	global_store_dwordx4 v[32:33], v[16:19], off offset:192 sc1
	v_cvt_pk_bf16_f32 v32, v16, v17
	v_cvt_pk_bf16_f32 v33, v18, v19
	v_lshl_add_u64 v[40:41], v[40:41], 0, v[36:37]
	v_add_u32_e32 v35, 0xffffc040, v130
	global_store_dwordx2 v[40:41], v[32:33], off offset:96
	v_cndmask_b32_e64 v32, v140, v35, s[2:3]
	v_lshrrev_b32_e32 v35, 4, v35
	v_mad_u64_u32 v[40:41], s[0:1], v35, s94, v[132:133]
	s_movk_i32 s0, 0x3fc0
	s_nop 0
	v_cmp_gt_i32_e32 vcc, s0, v130
	v_ashrrev_i32_e32 v33, 31, v32
	v_lshlrev_b64 v[32:33], 8, v[32:33]
	v_cndmask_b32_e32 v40, v40, v140, vcc
	v_ashrrev_i32_e32 v41, 31, v40
	v_lshl_add_u64 v[32:33], s[28:29], 0, v[32:33]
	v_lshlrev_b64 v[40:41], 7, v[40:41]
	v_lshl_add_u64 v[32:33], v[32:33], 0, v[38:39]
	v_lshl_add_u64 v[40:41], s[12:13], 0, v[40:41]
	global_store_dwordx4 v[32:33], v[12:15], off offset:192 sc1
	v_cvt_pk_bf16_f32 v32, v12, v13
	v_cvt_pk_bf16_f32 v33, v14, v15
	v_lshl_add_u64 v[40:41], v[40:41], 0, v[36:37]
	v_add_u32_e32 v35, 0xffffc050, v130
	global_store_dwordx2 v[40:41], v[32:33], off offset:96
	v_cndmask_b32_e64 v32, v138, v35, s[2:3]
	v_lshrrev_b32_e32 v35, 4, v35
	v_mad_u64_u32 v[40:41], s[0:1], v35, s94, v[132:133]
	s_movk_i32 s0, 0x3fb0
	s_nop 0
	v_cmp_gt_i32_e32 vcc, s0, v130
	v_ashrrev_i32_e32 v33, 31, v32
	v_lshlrev_b64 v[32:33], 8, v[32:33]
	v_cndmask_b32_e32 v40, v40, v138, vcc
	v_ashrrev_i32_e32 v41, 31, v40
	v_lshl_add_u64 v[32:33], s[28:29], 0, v[32:33]
	v_lshlrev_b64 v[40:41], 7, v[40:41]
	v_lshl_add_u64 v[32:33], v[32:33], 0, v[38:39]
	v_lshl_add_u64 v[40:41], s[12:13], 0, v[40:41]
	global_store_dwordx4 v[32:33], v[8:11], off offset:192 sc1
	v_cvt_pk_bf16_f32 v32, v8, v9
	v_cvt_pk_bf16_f32 v33, v10, v11
	v_lshl_add_u64 v[40:41], v[40:41], 0, v[36:37]
	v_add_u32_e32 v35, 0xffffc060, v130
	global_store_dwordx2 v[40:41], v[32:33], off offset:96
	v_cndmask_b32_e64 v32, v136, v35, s[2:3]
	v_lshrrev_b32_e32 v35, 4, v35
	v_mad_u64_u32 v[40:41], s[0:1], v35, s94, v[132:133]
	s_movk_i32 s0, 0x3fa0
	s_nop 0
	v_cmp_gt_i32_e32 vcc, s0, v130
	v_ashrrev_i32_e32 v33, 31, v32
	v_lshlrev_b64 v[32:33], 8, v[32:33]
	v_cndmask_b32_e32 v40, v40, v136, vcc
	v_ashrrev_i32_e32 v41, 31, v40
	v_lshl_add_u64 v[32:33], s[28:29], 0, v[32:33]
	v_lshlrev_b64 v[40:41], 7, v[40:41]
	v_lshl_add_u64 v[32:33], v[32:33], 0, v[38:39]
	v_lshl_add_u64 v[40:41], s[12:13], 0, v[40:41]
	global_store_dwordx4 v[32:33], v[4:7], off offset:192 sc1
	v_cvt_pk_bf16_f32 v32, v4, v5
	v_cvt_pk_bf16_f32 v33, v6, v7
	v_lshl_add_u64 v[40:41], v[40:41], 0, v[36:37]
	v_add_u32_e32 v35, 0xffffc070, v130
	global_store_dwordx2 v[40:41], v[32:33], off offset:96
	v_cndmask_b32_e64 v32, v134, v35, s[2:3]
	v_ashrrev_i32_e32 v33, 31, v32
	v_lshlrev_b64 v[32:33], 8, v[32:33]
	v_lshl_add_u64 v[32:33], s[28:29], 0, v[32:33]
	v_lshrrev_b32_e32 v35, 4, v35
	v_lshl_add_u64 v[32:33], v[32:33], 0, v[38:39]
	v_mad_u64_u32 v[38:39], s[0:1], v35, s94, v[132:133]
	s_movk_i32 s0, 0x3f90
	s_nop 0
	v_cmp_gt_i32_e32 vcc, s0, v130
	global_store_dwordx4 v[32:33], v[0:3], off offset:192 sc1
	v_cvt_pk_bf16_f32 v32, v0, v1
	v_cndmask_b32_e32 v38, v38, v134, vcc
	v_ashrrev_i32_e32 v39, 31, v38
	v_lshlrev_b64 v[38:39], 7, v[38:39]
	v_lshl_add_u64 v[38:39], s[12:13], 0, v[38:39]
	v_cvt_pk_bf16_f32 v33, v2, v3
	v_lshl_add_u64 v[36:37], v[38:39], 0, v[36:37]
	v_readlane_b32 s14, v231, 40
	v_readlane_b32 s15, v231, 41
	v_readlane_b32 s16, v231, 42
	v_readlane_b32 s17, v231, 43
	v_readlane_b32 s18, v231, 44
	v_readlane_b32 s19, v231, 45
	v_readlane_b32 s20, v231, 46
	v_readlane_b32 s21, v231, 47
	v_readlane_b32 s22, v231, 48
	v_readlane_b32 s23, v231, 49
	v_readlane_b32 s24, v231, 50
	v_readlane_b32 s25, v231, 51
	v_readlane_b32 s26, v231, 52
	v_readlane_b32 s27, v231, 53
	global_store_dwordx2 v[36:37], v[32:33], off offset:96

; DI u16 f2bf(float x) { return (u16)(cvtpk(x, 0.f) & 0xffffu); }
; template <int EPI>
; DI void gemm_epilogue(const Params& p, f32x4 (&acc)[8][4], int m0, int n0, int wr, int wc, int fr, int fq, u16* Cb, int ldc) {
;     ...
;       } else if (colt < 6144) {
;         const int c = col - 4096;
; #pragma clang loop unroll(full)
;         for (int m = 0; m < 8; ++m) {
;           const int row = rbase + m * 16;
;           if (!smp) {
;             *(f32x4*)(p.out + O_AVP + (size_t)row * 2048 + c) = acc[m][n];
; #pragma clang loop unroll(full)
;             for (int j = 0; j < 4; ++j) p.VAT[(size_t)(c + j) * MP + row] = f2bf(acc[m][n][j]);
;           } else *(f32x4*)(p.out + O_AVS + (size_t)(row - MP) * 2048 + c) = acc[m][n];
;         }
.LBB0_1257:
	s_andn2_b64 vcc, exec, s[0:1]
	s_cbranch_vccnz .LBB0_1290
	v_or_b32_e32 v32, v34, v160
	v_add_u32_e32 v34, 0xfffff000, v32
	v_ashrrev_i32_e32 v35, 31, v34
	v_cndmask_b32_e64 v33, 0, 1, s[88:89]
	s_mov_b64 s[0:1], -1
	v_cmp_ne_u32_e64 s[2:3], 1, v33
	s_andn2_b64 vcc, exec, s[88:89]
	v_lshlrev_b64 v[34:35], 15, v[34:35]
	v_ashrrev_i32_e32 v33, 31, v32
	s_cbranch_vccnz .LBB0_1274
	v_lshlrev_b64 v[36:37], 13, v[130:131]
	v_lshl_add_u64 v[36:37], s[6:7], 0, v[36:37]
	v_lshl_add_u64 v[38:39], v[128:129], 0, v[160:161]
	v_lshl_add_u64 v[36:37], v[38:39], 2, v[36:37]
	v_add_co_u32_e32 v36, vcc, 0xffffd000, v36
	v_cvt_pk_bf16_f32 v40, v28, s0
	s_nop 0
	v_addc_co_u32_e32 v37, vcc, -1, v37, vcc
	global_store_dwordx4 v[36:37], v[28:31], off offset:-3904 sc1
	v_lshl_add_u64 v[36:37], v[130:131], 1, s[48:49]
	v_lshl_add_u64 v[38:39], v[36:37], 0, v[34:35]
	global_store_short v[38:39], v40, off
	v_lshlrev_b64 v[38:39], 15, v[32:33]
	v_lshl_add_u64 v[36:37], v[36:37], 0, v[38:39]
	v_add_co_u32_e32 v38, vcc, 0xf8008000, v36
	v_cvt_pk_bf16_f32 v40, v29, s0
	s_nop 0
	v_addc_co_u32_e32 v39, vcc, -1, v37, vcc
	global_store_short v[38:39], v40, off
	v_add_co_u32_e32 v38, vcc, 0xf8010000, v36
	v_cvt_pk_bf16_f32 v40, v30, s0
	s_nop 0
	v_addc_co_u32_e32 v39, vcc, -1, v37, vcc
	v_add_co_u32_e32 v36, vcc, 0xf8018000, v36
	global_store_short v[38:39], v40, off
	v_cvt_pk_bf16_f32 v38, v31, s0
	v_addc_co_u32_e32 v37, vcc, -1, v37, vcc
	global_store_short v[36:37], v38, off
	s_cbranch_execz .LBB0_1275

; DI u16 f2bf(float x) { return (u16)(cvtpk(x, 0.f) & 0xffffu); }
; template <int EPI>
; DI void gemm_epilogue(const Params& p, f32x4 (&acc)[8][4], int m0, int n0, int wr, int wc, int fr, int fq, u16* Cb, int ldc) {
;     ...
;       } else if (colt < 6144) {
;         const int c = col - 4096;
; #pragma clang loop unroll(full)
;         for (int m = 0; m < 8; ++m) {
;           const int row = rbase + m * 16;
;           if (!smp) {
;             *(f32x4*)(p.out + O_AVP + (size_t)row * 2048 + c) = acc[m][n];
; #pragma clang loop unroll(full)
;             for (int j = 0; j < 4; ++j) p.VAT[(size_t)(c + j) * MP + row] = f2bf(acc[m][n][j]);
;           } else *(f32x4*)(p.out + O_AVS + (size_t)(row - MP) * 2048 + c) = acc[m][n];
;         }
.LBB0_1261:
	v_lshlrev_b64 v[36:37], 13, v[146:147]
	v_lshl_add_u64 v[36:37], s[6:7], 0, v[36:37]
	v_lshl_add_u64 v[38:39], v[128:129], 0, v[160:161]
	v_lshl_add_u64 v[36:37], v[38:39], 2, v[36:37]
	v_add_co_u32_e32 v36, vcc, 0xffffd000, v36
	v_cvt_pk_bf16_f32 v40, v24, s0
	s_nop 0
	v_addc_co_u32_e32 v37, vcc, -1, v37, vcc
	global_store_dwordx4 v[36:37], v[24:27], off offset:-3904 sc1
	v_lshl_add_u64 v[36:37], v[130:131], 1, s[48:49]
	v_lshl_add_u64 v[38:39], v[36:37], 0, v[34:35]
	global_store_short v[38:39], v40, off offset:32
	v_lshlrev_b64 v[38:39], 15, v[32:33]
	v_lshl_add_u64 v[36:37], v[36:37], 0, v[38:39]
	v_add_co_u32_e32 v38, vcc, 0xf8009000, v36
	v_cvt_pk_bf16_f32 v40, v25, s0
	s_nop 0
	v_addc_co_u32_e32 v39, vcc, -1, v37, vcc
	global_store_short v[38:39], v40, off offset:-4064
	v_add_co_u32_e32 v38, vcc, 0xf8011000, v36
	v_cvt_pk_bf16_f32 v40, v26, s0
	s_nop 0
	v_addc_co_u32_e32 v39, vcc, -1, v37, vcc
	v_add_co_u32_e32 v36, vcc, 0xf8019000, v36
	global_store_short v[38:39], v40, off offset:-4064
	v_cvt_pk_bf16_f32 v38, v27, s0
	v_addc_co_u32_e32 v37, vcc, -1, v37, vcc
	global_store_short v[36:37], v38, off offset:-4064
	s_cbranch_execz .LBB0_1277

; DI u16 f2bf(float x) { return (u16)(cvtpk(x, 0.f) & 0xffffu); }
; template <int EPI>
; DI void gemm_epilogue(const Params& p, f32x4 (&acc)[8][4], int m0, int n0, int wr, int wc, int fr, int fq, u16* Cb, int ldc) {
;     ...
;       } else if (colt < 6144) {
;         const int c = col - 4096;
; #pragma clang loop unroll(full)
;         for (int m = 0; m < 8; ++m) {
;           const int row = rbase + m * 16;
;           if (!smp) {
;             *(f32x4*)(p.out + O_AVP + (size_t)row * 2048 + c) = acc[m][n];
; #pragma clang loop unroll(full)
;             for (int j = 0; j < 4; ++j) p.VAT[(size_t)(c + j) * MP + row] = f2bf(acc[m][n][j]);
;           } else *(f32x4*)(p.out + O_AVS + (size_t)(row - MP) * 2048 + c) = acc[m][n];
;         }
.LBB0_1263:
	v_lshlrev_b64 v[36:37], 13, v[144:145]
	v_lshl_add_u64 v[36:37], s[6:7], 0, v[36:37]
	v_lshl_add_u64 v[38:39], v[128:129], 0, v[160:161]
	v_lshl_add_u64 v[36:37], v[38:39], 2, v[36:37]
	v_add_co_u32_e32 v36, vcc, 0xffffd000, v36
	v_cvt_pk_bf16_f32 v40, v20, s0
	s_nop 0
	v_addc_co_u32_e32 v37, vcc, -1, v37, vcc
	global_store_dwordx4 v[36:37], v[20:23], off offset:-3904 sc1
	v_lshl_add_u64 v[36:37], v[130:131], 1, s[48:49]
	v_lshl_add_u64 v[38:39], v[36:37], 0, v[34:35]
	global_store_short v[38:39], v40, off offset:64
	v_lshlrev_b64 v[38:39], 15, v[32:33]
	v_lshl_add_u64 v[36:37], v[36:37], 0, v[38:39]
	v_add_co_u32_e32 v38, vcc, 0xf8009000, v36
	v_cvt_pk_bf16_f32 v40, v21, s0
	s_nop 0
	v_addc_co_u32_e32 v39, vcc, -1, v37, vcc
	global_store_short v[38:39], v40, off offset:-4032
	v_add_co_u32_e32 v38, vcc, 0xf8011000, v36
	v_cvt_pk_bf16_f32 v40, v22, s0
	s_nop 0
	v_addc_co_u32_e32 v39, vcc, -1, v37, vcc
	v_add_co_u32_e32 v36, vcc, 0xf8019000, v36
	global_store_short v[38:39], v40, off offset:-4032
	v_cvt_pk_bf16_f32 v38, v23, s0
	v_addc_co_u32_e32 v37, vcc, -1, v37, vcc
	global_store_short v[36:37], v38, off offset:-4032
	s_cbranch_execz .LBB0_1279

; DI u16 f2bf(float x) { return (u16)(cvtpk(x, 0.f) & 0xffffu); }
; template <int EPI>
; DI void gemm_epilogue(const Params& p, f32x4 (&acc)[8][4], int m0, int n0, int wr, int wc, int fr, int fq, u16* Cb, int ldc) {
;     ...
;       } else if (colt < 6144) {
;         const int c = col - 4096;
; #pragma clang loop unroll(full)
;         for (int m = 0; m < 8; ++m) {
;           const int row = rbase + m * 16;
;           if (!smp) {
;             *(f32x4*)(p.out + O_AVP + (size_t)row * 2048 + c) = acc[m][n];
; #pragma clang loop unroll(full)
;             for (int j = 0; j < 4; ++j) p.VAT[(size_t)(c + j) * MP + row] = f2bf(acc[m][n][j]);
;           } else *(f32x4*)(p.out + O_AVS + (size_t)(row - MP) * 2048 + c) = acc[m][n];
;         }
.LBB0_1265:
	v_lshlrev_b64 v[36:37], 13, v[142:143]
	v_lshl_add_u64 v[36:37], s[6:7], 0, v[36:37]
	v_lshl_add_u64 v[38:39], v[128:129], 0, v[160:161]
	v_lshl_add_u64 v[36:37], v[38:39], 2, v[36:37]
	v_add_co_u32_e32 v36, vcc, 0xffffd000, v36
	v_cvt_pk_bf16_f32 v40, v16, s0
	s_nop 0
	v_addc_co_u32_e32 v37, vcc, -1, v37, vcc
	global_store_dwordx4 v[36:37], v[16:19], off offset:-3904 sc1
	v_lshl_add_u64 v[36:37], v[130:131], 1, s[48:49]
	v_lshl_add_u64 v[38:39], v[36:37], 0, v[34:35]
	global_store_short v[38:39], v40, off offset:96
	v_lshlrev_b64 v[38:39], 15, v[32:33]
	v_lshl_add_u64 v[36:37], v[36:37], 0, v[38:39]
	v_add_co_u32_e32 v38, vcc, 0xf8009000, v36
	v_cvt_pk_bf16_f32 v40, v17, s0
	s_nop 0
	v_addc_co_u32_e32 v39, vcc, -1, v37, vcc
	global_store_short v[38:39], v40, off offset:-4000
	v_add_co_u32_e32 v38, vcc, 0xf8011000, v36
	v_cvt_pk_bf16_f32 v40, v18, s0
	s_nop 0
	v_addc_co_u32_e32 v39, vcc, -1, v37, vcc
	v_add_co_u32_e32 v36, vcc, 0xf8019000, v36
	global_store_short v[38:39], v40, off offset:-4000
	v_cvt_pk_bf16_f32 v38, v19, s0
	v_addc_co_u32_e32 v37, vcc, -1, v37, vcc
	global_store_short v[36:37], v38, off offset:-4000
	s_cbranch_execz .LBB0_1281

; DI u16 f2bf(float x) { return (u16)(cvtpk(x, 0.f) & 0xffffu); }
; template <int EPI>
; DI void gemm_epilogue(const Params& p, f32x4 (&acc)[8][4], int m0, int n0, int wr, int wc, int fr, int fq, u16* Cb, int ldc) {
;     ...
;       } else if (colt < 6144) {
;         const int c = col - 4096;
; #pragma clang loop unroll(full)
;         for (int m = 0; m < 8; ++m) {
;           const int row = rbase + m * 16;
;           if (!smp) {
;             *(f32x4*)(p.out + O_AVP + (size_t)row * 2048 + c) = acc[m][n];
; #pragma clang loop unroll(full)
;             for (int j = 0; j < 4; ++j) p.VAT[(size_t)(c + j) * MP + row] = f2bf(acc[m][n][j]);
;           } else *(f32x4*)(p.out + O_AVS + (size_t)(row - MP) * 2048 + c) = acc[m][n];
;         }
.LBB0_1267:
	v_lshlrev_b64 v[36:37], 13, v[140:141]
	v_lshl_add_u64 v[36:37], s[6:7], 0, v[36:37]
	v_lshl_add_u64 v[38:39], v[128:129], 0, v[160:161]
	v_lshl_add_u64 v[36:37], v[38:39], 2, v[36:37]
	v_add_co_u32_e32 v36, vcc, 0xffffd000, v36
	v_cvt_pk_bf16_f32 v40, v12, s0
	s_nop 0
	v_addc_co_u32_e32 v37, vcc, -1, v37, vcc
	global_store_dwordx4 v[36:37], v[12:15], off offset:-3904 sc1
	v_lshl_add_u64 v[36:37], v[130:131], 1, s[48:49]
	v_lshl_add_u64 v[38:39], v[36:37], 0, v[34:35]
	global_store_short v[38:39], v40, off offset:128
	v_lshlrev_b64 v[38:39], 15, v[32:33]
	v_lshl_add_u64 v[36:37], v[36:37], 0, v[38:39]
	v_add_co_u32_e32 v38, vcc, 0xf8009000, v36
	v_cvt_pk_bf16_f32 v40, v13, s0
	s_nop 0
	v_addc_co_u32_e32 v39, vcc, -1, v37, vcc
	global_store_short v[38:39], v40, off offset:-3968
	v_add_co_u32_e32 v38, vcc, 0xf8011000, v36
	v_cvt_pk_bf16_f32 v40, v14, s0
	s_nop 0
	v_addc_co_u32_e32 v39, vcc, -1, v37, vcc
	v_add_co_u32_e32 v36, vcc, 0xf8019000, v36
	global_store_short v[38:39], v40, off offset:-3968
	v_cvt_pk_bf16_f32 v38, v15, s0
	v_addc_co_u32_e32 v37, vcc, -1, v37, vcc
	global_store_short v[36:37], v38, off offset:-3968
	s_cbranch_execz .LBB0_1283

; DI u16 f2bf(float x) { return (u16)(cvtpk(x, 0.f) & 0xffffu); }
; template <int EPI>
; DI void gemm_epilogue(const Params& p, f32x4 (&acc)[8][4], int m0, int n0, int wr, int wc, int fr, int fq, u16* Cb, int ldc) {
;     ...
;       } else if (colt < 6144) {
;         const int c = col - 4096;
; #pragma clang loop unroll(full)
;         for (int m = 0; m < 8; ++m) {
;           const int row = rbase + m * 16;
;           if (!smp) {
;             *(f32x4*)(p.out + O_AVP + (size_t)row * 2048 + c) = acc[m][n];
; #pragma clang loop unroll(full)
;             for (int j = 0; j < 4; ++j) p.VAT[(size_t)(c + j) * MP + row] = f2bf(acc[m][n][j]);
;           } else *(f32x4*)(p.out + O_AVS + (size_t)(row - MP) * 2048 + c) = acc[m][n];
;         }
.LBB0_1269:
	v_lshlrev_b64 v[36:37], 13, v[138:139]
	v_lshl_add_u64 v[36:37], s[6:7], 0, v[36:37]
	v_lshl_add_u64 v[38:39], v[128:129], 0, v[160:161]
	v_lshl_add_u64 v[36:37], v[38:39], 2, v[36:37]
	v_add_co_u32_e32 v36, vcc, 0xffffd000, v36
	v_cvt_pk_bf16_f32 v40, v8, s0
	s_nop 0
	v_addc_co_u32_e32 v37, vcc, -1, v37, vcc
	global_store_dwordx4 v[36:37], v[8:11], off offset:-3904 sc1
	v_lshl_add_u64 v[36:37], v[130:131], 1, s[48:49]
	v_lshl_add_u64 v[38:39], v[36:37], 0, v[34:35]
	global_store_short v[38:39], v40, off offset:160
	v_lshlrev_b64 v[38:39], 15, v[32:33]
	v_lshl_add_u64 v[36:37], v[36:37], 0, v[38:39]
	v_add_co_u32_e32 v38, vcc, 0xf8009000, v36
	v_cvt_pk_bf16_f32 v40, v9, s0
	s_nop 0
	v_addc_co_u32_e32 v39, vcc, -1, v37, vcc
	global_store_short v[38:39], v40, off offset:-3936
	v_add_co_u32_e32 v38, vcc, 0xf8011000, v36
	v_cvt_pk_bf16_f32 v40, v10, s0
	s_nop 0
	v_addc_co_u32_e32 v39, vcc, -1, v37, vcc
	v_add_co_u32_e32 v36, vcc, 0xf8019000, v36
	global_store_short v[38:39], v40, off offset:-3936
	v_cvt_pk_bf16_f32 v38, v11, s0
	v_addc_co_u32_e32 v37, vcc, -1, v37, vcc
	global_store_short v[36:37], v38, off offset:-3936
	s_cbranch_execz .LBB0_1285

; DI u16 f2bf(float x) { return (u16)(cvtpk(x, 0.f) & 0xffffu); }
; template <int EPI>
; DI void gemm_epilogue(const Params& p, f32x4 (&acc)[8][4], int m0, int n0, int wr, int wc, int fr, int fq, u16* Cb, int ldc) {
;     ...
;       } else if (colt < 6144) {
;         const int c = col - 4096;
; #pragma clang loop unroll(full)
;         for (int m = 0; m < 8; ++m) {
;           const int row = rbase + m * 16;
;           if (!smp) {
;             *(f32x4*)(p.out + O_AVP + (size_t)row * 2048 + c) = acc[m][n];
; #pragma clang loop unroll(full)
;             for (int j = 0; j < 4; ++j) p.VAT[(size_t)(c + j) * MP + row] = f2bf(acc[m][n][j]);
;           } else *(f32x4*)(p.out + O_AVS + (size_t)(row - MP) * 2048 + c) = acc[m][n];
;         }
.LBB0_1271:
	v_lshlrev_b64 v[36:37], 13, v[136:137]
	v_lshl_add_u64 v[36:37], s[6:7], 0, v[36:37]
	v_lshl_add_u64 v[38:39], v[128:129], 0, v[160:161]
	v_lshl_add_u64 v[36:37], v[38:39], 2, v[36:37]
	v_add_co_u32_e32 v36, vcc, 0xffffd000, v36
	v_cvt_pk_bf16_f32 v40, v4, s0
	s_nop 0
	v_addc_co_u32_e32 v37, vcc, -1, v37, vcc
	global_store_dwordx4 v[36:37], v[4:7], off offset:-3904 sc1
	v_lshl_add_u64 v[36:37], v[130:131], 1, s[48:49]
	v_lshl_add_u64 v[38:39], v[36:37], 0, v[34:35]
	global_store_short v[38:39], v40, off offset:192
	v_lshlrev_b64 v[38:39], 15, v[32:33]
	v_lshl_add_u64 v[36:37], v[36:37], 0, v[38:39]
	v_add_co_u32_e32 v38, vcc, 0xf8009000, v36
	v_cvt_pk_bf16_f32 v40, v5, s0
	s_nop 0
	v_addc_co_u32_e32 v39, vcc, -1, v37, vcc
	global_store_short v[38:39], v40, off offset:-3904
	v_add_co_u32_e32 v38, vcc, 0xf8011000, v36
	v_cvt_pk_bf16_f32 v40, v6, s0
	s_nop 0
	v_addc_co_u32_e32 v39, vcc, -1, v37, vcc
	v_add_co_u32_e32 v36, vcc, 0xf8019000, v36
	global_store_short v[38:39], v40, off offset:-3904
	v_cvt_pk_bf16_f32 v38, v7, s0
	v_addc_co_u32_e32 v37, vcc, -1, v37, vcc
	global_store_short v[36:37], v38, off offset:-3904
	s_cbranch_execz .LBB0_1287

; DI u16 f2bf(float x) { return (u16)(cvtpk(x, 0.f) & 0xffffu); }
; template <int EPI>
; DI void gemm_epilogue(const Params& p, f32x4 (&acc)[8][4], int m0, int n0, int wr, int wc, int fr, int fq, u16* Cb, int ldc) {
;     ...
;       } else if (colt < 6144) {
;         const int c = col - 4096;
; #pragma clang loop unroll(full)
;         for (int m = 0; m < 8; ++m) {
;           const int row = rbase + m * 16;
;           if (!smp) {
;             *(f32x4*)(p.out + O_AVP + (size_t)row * 2048 + c) = acc[m][n];
; #pragma clang loop unroll(full)
;             for (int j = 0; j < 4; ++j) p.VAT[(size_t)(c + j) * MP + row] = f2bf(acc[m][n][j]);
;           } else *(f32x4*)(p.out + O_AVS + (size_t)(row - MP) * 2048 + c) = acc[m][n];
;         }
.LBB0_1273:
	v_lshlrev_b64 v[36:37], 13, v[134:135]
	v_lshl_add_u64 v[36:37], s[6:7], 0, v[36:37]
	v_lshl_add_u64 v[38:39], v[128:129], 0, v[160:161]
	v_lshl_add_u64 v[36:37], v[38:39], 2, v[36:37]
	v_add_co_u32_e32 v36, vcc, 0xffffd000, v36
	v_lshlrev_b64 v[32:33], 15, v[32:33]
	s_nop 0
	v_addc_co_u32_e32 v37, vcc, -1, v37, vcc
	global_store_dwordx4 v[36:37], v[0:3], off offset:-3904 sc1
	v_lshl_add_u64 v[36:37], v[130:131], 1, s[48:49]
	v_cvt_pk_bf16_f32 v38, v0, s0
	v_lshl_add_u64 v[34:35], v[36:37], 0, v[34:35]
	v_lshl_add_u64 v[32:33], v[36:37], 0, v[32:33]
	global_store_short v[34:35], v38, off offset:224
	v_add_co_u32_e32 v34, vcc, 0xf8009000, v32
	v_cvt_pk_bf16_f32 v38, v1, s0
	s_nop 0
	v_addc_co_u32_e32 v35, vcc, -1, v33, vcc
	global_store_short v[34:35], v38, off offset:-3872
	v_add_co_u32_e32 v34, vcc, 0xf8011000, v32
	v_cvt_pk_bf16_f32 v36, v2, s0
	s_nop 0
	v_addc_co_u32_e32 v35, vcc, -1, v33, vcc
	v_add_co_u32_e32 v32, vcc, 0xf8019000, v32
	global_store_short v[34:35], v36, off offset:-3872
	v_cvt_pk_bf16_f32 v34, v3, s0
	v_addc_co_u32_e32 v33, vcc, -1, v33, vcc
	global_store_short v[32:33], v34, off offset:-3872
	s_cbranch_execz .LBB0_1289
	s_branch .LBB0_1290

; DI u16 f2bf(float x) { return (u16)(cvtpk(x, 0.f) & 0xffffu); }
; template <int EPI>
; DI void gemm_epilogue(const Params& p, f32x4 (&acc)[8][4], int m0, int n0, int wr, int wc, int fr, int fq, u16* Cb, int ldc) {
;     ...
;           if (!smp) {
;             *(f32x4*)(p.out + O_AVP + (size_t)row * 2048 + c) = acc[m][n];
; #pragma clang loop unroll(full)
;             for (int j = 0; j < 4; ++j) p.VAT[(size_t)(c + j) * MP + row] = f2bf(acc[m][n][j]);
;           } else *(f32x4*)(p.out + O_AVS + (size_t)(row - MP) * 2048 + c) = acc[m][n];
.LBB0_1275:
	v_lshlrev_b64 v[36:37], 13, v[130:131]
	v_lshl_add_u64 v[36:37], s[62:63], 0, v[36:37]
	v_lshl_add_u64 v[38:39], v[128:129], 0, v[160:161]
	v_lshl_add_u64 v[36:37], v[38:39], 2, v[36:37]
	v_add_co_u32_e32 v36, vcc, 0xf7ffd000, v36
	s_nop 1
	v_addc_co_u32_e32 v37, vcc, -1, v37, vcc
	global_store_dwordx4 v[36:37], v[28:31], off offset:-3904 sc1
	s_and_b64 vcc, exec, s[2:3]
	s_mov_b64 s[0:1], -1
	s_cbranch_vccz .LBB0_1261

; DI u16 f2bf(float x) { return (u16)(cvtpk(x, 0.f) & 0xffffu); }
; template <int EPI>
; DI void gemm_epilogue(const Params& p, f32x4 (&acc)[8][4], int m0, int n0, int wr, int wc, int fr, int fq, u16* Cb, int ldc) {
;     ...
;           if (!smp) {
;             *(f32x4*)(p.out + O_AVP + (size_t)row * 2048 + c) = acc[m][n];
; #pragma clang loop unroll(full)
;             for (int j = 0; j < 4; ++j) p.VAT[(size_t)(c + j) * MP + row] = f2bf(acc[m][n][j]);
;           } else *(f32x4*)(p.out + O_AVS + (size_t)(row - MP) * 2048 + c) = acc[m][n];
.LBB0_1277:
	v_lshlrev_b64 v[36:37], 13, v[130:131]
	v_lshl_add_u64 v[36:37], s[62:63], 0, v[36:37]
	v_lshl_add_u64 v[38:39], v[128:129], 0, v[160:161]
	v_lshl_add_u64 v[36:37], v[38:39], 2, v[36:37]
	v_add_co_u32_e32 v36, vcc, 0xf801d000, v36
	s_nop 1
	v_addc_co_u32_e32 v37, vcc, -1, v37, vcc
	global_store_dwordx4 v[36:37], v[24:27], off offset:-3904 sc1
	s_and_b64 vcc, exec, s[2:3]
	s_mov_b64 s[0:1], -1
	s_cbranch_vccz .LBB0_1263

; DI u16 f2bf(float x) { return (u16)(cvtpk(x, 0.f) & 0xffffu); }
; template <int EPI>
; DI void gemm_epilogue(const Params& p, f32x4 (&acc)[8][4], int m0, int n0, int wr, int wc, int fr, int fq, u16* Cb, int ldc) {
;     ...
;           if (!smp) {
;             *(f32x4*)(p.out + O_AVP + (size_t)row * 2048 + c) = acc[m][n];
; #pragma clang loop unroll(full)
;             for (int j = 0; j < 4; ++j) p.VAT[(size_t)(c + j) * MP + row] = f2bf(acc[m][n][j]);
;           } else *(f32x4*)(p.out + O_AVS + (size_t)(row - MP) * 2048 + c) = acc[m][n];
.LBB0_1279:
	v_lshlrev_b64 v[36:37], 13, v[130:131]
	v_lshl_add_u64 v[36:37], s[62:63], 0, v[36:37]
	v_lshl_add_u64 v[38:39], v[128:129], 0, v[160:161]
	v_lshl_add_u64 v[36:37], v[38:39], 2, v[36:37]
	v_add_co_u32_e32 v36, vcc, 0xf803d000, v36
	s_nop 1
	v_addc_co_u32_e32 v37, vcc, -1, v37, vcc
	global_store_dwordx4 v[36:37], v[20:23], off offset:-3904 sc1
	s_and_b64 vcc, exec, s[2:3]
	s_mov_b64 s[0:1], -1
	s_cbranch_vccz .LBB0_1265

; DI u16 f2bf(float x) { return (u16)(cvtpk(x, 0.f) & 0xffffu); }
; template <int EPI>
; DI void gemm_epilogue(const Params& p, f32x4 (&acc)[8][4], int m0, int n0, int wr, int wc, int fr, int fq, u16* Cb, int ldc) {
;     ...
;           if (!smp) {
;             *(f32x4*)(p.out + O_AVP + (size_t)row * 2048 + c) = acc[m][n];
; #pragma clang loop unroll(full)
;             for (int j = 0; j < 4; ++j) p.VAT[(size_t)(c + j) * MP + row] = f2bf(acc[m][n][j]);
;           } else *(f32x4*)(p.out + O_AVS + (size_t)(row - MP) * 2048 + c) = acc[m][n];
.LBB0_1281:
	v_lshlrev_b64 v[36:37], 13, v[130:131]
	v_lshl_add_u64 v[36:37], s[62:63], 0, v[36:37]
	v_lshl_add_u64 v[38:39], v[128:129], 0, v[160:161]
	v_lshl_add_u64 v[36:37], v[38:39], 2, v[36:37]
	v_add_co_u32_e32 v36, vcc, 0xf805d000, v36
	s_nop 1
	v_addc_co_u32_e32 v37, vcc, -1, v37, vcc
	global_store_dwordx4 v[36:37], v[16:19], off offset:-3904 sc1
	s_and_b64 vcc, exec, s[2:3]
	s_mov_b64 s[0:1], -1
	s_cbranch_vccz .LBB0_1267

; DI u16 f2bf(float x) { return (u16)(cvtpk(x, 0.f) & 0xffffu); }
; template <int EPI>
; DI void gemm_epilogue(const Params& p, f32x4 (&acc)[8][4], int m0, int n0, int wr, int wc, int fr, int fq, u16* Cb, int ldc) {
;     ...
;           if (!smp) {
;             *(f32x4*)(p.out + O_AVP + (size_t)row * 2048 + c) = acc[m][n];
; #pragma clang loop unroll(full)
;             for (int j = 0; j < 4; ++j) p.VAT[(size_t)(c + j) * MP + row] = f2bf(acc[m][n][j]);
;           } else *(f32x4*)(p.out + O_AVS + (size_t)(row - MP) * 2048 + c) = acc[m][n];
.LBB0_1283:
	v_lshlrev_b64 v[36:37], 13, v[130:131]
	v_lshl_add_u64 v[36:37], s[62:63], 0, v[36:37]
	v_lshl_add_u64 v[38:39], v[128:129], 0, v[160:161]
	v_lshl_add_u64 v[36:37], v[38:39], 2, v[36:37]
	v_add_co_u32_e32 v36, vcc, 0xf807d000, v36
	s_nop 1
	v_addc_co_u32_e32 v37, vcc, -1, v37, vcc
	global_store_dwordx4 v[36:37], v[12:15], off offset:-3904 sc1
	s_and_b64 vcc, exec, s[2:3]
	s_mov_b64 s[0:1], -1
	s_cbranch_vccz .LBB0_1269

; DI u16 f2bf(float x) { return (u16)(cvtpk(x, 0.f) & 0xffffu); }
; template <int EPI>
; DI void gemm_epilogue(const Params& p, f32x4 (&acc)[8][4], int m0, int n0, int wr, int wc, int fr, int fq, u16* Cb, int ldc) {
;     ...
;           if (!smp) {
;             *(f32x4*)(p.out + O_AVP + (size_t)row * 2048 + c) = acc[m][n];
; #pragma clang loop unroll(full)
;             for (int j = 0; j < 4; ++j) p.VAT[(size_t)(c + j) * MP + row] = f2bf(acc[m][n][j]);
;           } else *(f32x4*)(p.out + O_AVS + (size_t)(row - MP) * 2048 + c) = acc[m][n];
.LBB0_1285:
	v_lshlrev_b64 v[36:37], 13, v[130:131]
	v_lshl_add_u64 v[36:37], s[62:63], 0, v[36:37]
	v_lshl_add_u64 v[38:39], v[128:129], 0, v[160:161]
	v_lshl_add_u64 v[36:37], v[38:39], 2, v[36:37]
	v_add_co_u32_e32 v36, vcc, 0xf809d000, v36
	s_nop 1
	v_addc_co_u32_e32 v37, vcc, -1, v37, vcc
	global_store_dwordx4 v[36:37], v[8:11], off offset:-3904 sc1
	s_and_b64 vcc, exec, s[2:3]
	s_mov_b64 s[0:1], -1
	s_cbranch_vccz .LBB0_1271

; DI u16 f2bf(float x) { return (u16)(cvtpk(x, 0.f) & 0xffffu); }
; template <int EPI>
; DI void gemm_epilogue(const Params& p, f32x4 (&acc)[8][4], int m0, int n0, int wr, int wc, int fr, int fq, u16* Cb, int ldc) {
;     ...
;           if (!smp) {
;             *(f32x4*)(p.out + O_AVP + (size_t)row * 2048 + c) = acc[m][n];
; #pragma clang loop unroll(full)
;             for (int j = 0; j < 4; ++j) p.VAT[(size_t)(c + j) * MP + row] = f2bf(acc[m][n][j]);
;           } else *(f32x4*)(p.out + O_AVS + (size_t)(row - MP) * 2048 + c) = acc[m][n];
.LBB0_1287:
	v_lshlrev_b64 v[36:37], 13, v[130:131]
	v_lshl_add_u64 v[36:37], s[62:63], 0, v[36:37]
	v_lshl_add_u64 v[38:39], v[128:129], 0, v[160:161]
	v_lshl_add_u64 v[36:37], v[38:39], 2, v[36:37]
	v_add_co_u32_e32 v36, vcc, 0xf80bd000, v36
	s_nop 1
	v_addc_co_u32_e32 v37, vcc, -1, v37, vcc
	global_store_dwordx4 v[36:37], v[4:7], off offset:-3904 sc1
	s_and_b64 vcc, exec, s[2:3]
	s_mov_b64 s[0:1], -1
	s_cbranch_vccz .LBB0_1273

; DI u16 f2bf(float x) { return (u16)(cvtpk(x, 0.f) & 0xffffu); }
; template <int EPI>
; DI void gemm_epilogue(const Params& p, f32x4 (&acc)[8][4], int m0, int n0, int wr, int wc, int fr, int fq, u16* Cb, int ldc) {
;     ...
;           if (!smp) {
;             *(f32x4*)(p.out + O_AVP + (size_t)row * 2048 + c) = acc[m][n];
; #pragma clang loop unroll(full)
;             for (int j = 0; j < 4; ++j) p.VAT[(size_t)(c + j) * MP + row] = f2bf(acc[m][n][j]);
;           } else *(f32x4*)(p.out + O_AVS + (size_t)(row - MP) * 2048 + c) = acc[m][n];
.LBB0_1289:
	v_lshlrev_b64 v[32:33], 13, v[130:131]
	v_lshl_add_u64 v[32:33], s[62:63], 0, v[32:33]
	v_lshl_add_u64 v[34:35], v[128:129], 0, v[160:161]
	v_lshl_add_u64 v[32:33], v[34:35], 2, v[32:33]
	v_add_co_u32_e32 v32, vcc, 0xf80dd000, v32
	s_nop 1
	v_addc_co_u32_e32 v33, vcc, -1, v33, vcc
	global_store_dwordx4 v[32:33], v[0:3], off offset:-3904 sc1

; DI u32x2 pack4(f32x4 v) { u32x2 r; r[0] = cvtpk(v[0], v[1]); r[1] = cvtpk(v[2], v[3]); return r; }
; template <int EPI>
; DI void gemm_epilogue(const Params& p, f32x4 (&acc)[8][4], int m0, int n0, int wr, int wc, int fr, int fq, u16* Cb, int ldc) {
;     ...
;       } else if (colt < 4096) {
;         const int c = col - 2048;
; #pragma clang loop unroll(full)
;         for (int m = 0; m < 8; ++m) {
;           const int row = rbase + m * 16;
;           if (!smp) { *(f32x4*)(p.out + O_AKP + (size_t)row * 2048 + c) = acc[m][n]; *(u32x2*)(p.KA + (size_t)row * 2048 + c) = pack4(acc[m][n]); }
;           else *(f32x4*)(p.out + O_AKS + (size_t)(row - MP) * 2048 + c) = acc[m][n];
;         }
.LBB0_1291:
	s_andn2_b64 vcc, exec, s[0:1]
	s_cbranch_vccnz .LBB0_1310
	v_cndmask_b32_e64 v32, 0, 1, s[88:89]
	v_cmp_ne_u32_e64 s[2:3], 1, v32
	s_andn2_b64 vcc, exec, s[88:89]
	s_mov_b64 s[0:1], -1
	s_cbranch_vccnz .LBB0_1312
	v_lshlrev_b64 v[32:33], 13, v[130:131]
	v_lshl_add_u64 v[34:35], v[128:129], 0, v[160:161]
	v_lshl_add_u64 v[32:33], s[8:9], 0, v[32:33]
	v_lshl_add_u64 v[34:35], v[34:35], 0, s[96:97]
	v_lshlrev_b64 v[36:37], 12, v[130:131]
	v_lshl_add_u64 v[32:33], v[34:35], 2, v[32:33]
	v_lshl_add_u64 v[36:37], s[46:47], 0, v[36:37]
	global_store_dwordx4 v[32:33], v[28:31], off offset:192 sc1
	v_cvt_pk_bf16_f32 v32, v28, v29
	v_cvt_pk_bf16_f32 v33, v30, v31
	v_lshl_add_u64 v[34:35], v[34:35], 1, v[36:37]
	global_store_dwordx2 v[34:35], v[32:33], off offset:96
	s_cbranch_execz .LBB0_1313

; DI u32x2 pack4(f32x4 v) { u32x2 r; r[0] = cvtpk(v[0], v[1]); r[1] = cvtpk(v[2], v[3]); return r; }
; template <int EPI>
; DI void gemm_epilogue(const Params& p, f32x4 (&acc)[8][4], int m0, int n0, int wr, int wc, int fr, int fq, u16* Cb, int ldc) {
;     ...
;       } else if (colt < 4096) {
;         const int c = col - 2048;
; #pragma clang loop unroll(full)
;         for (int m = 0; m < 8; ++m) {
;           const int row = rbase + m * 16;
;           if (!smp) { *(f32x4*)(p.out + O_AKP + (size_t)row * 2048 + c) = acc[m][n]; *(u32x2*)(p.KA + (size_t)row * 2048 + c) = pack4(acc[m][n]); }
;           else *(f32x4*)(p.out + O_AKS + (size_t)(row - MP) * 2048 + c) = acc[m][n];
;         }
.LBB0_1295:
	v_lshlrev_b64 v[32:33], 13, v[146:147]
	v_lshl_add_u64 v[34:35], v[128:129], 0, v[160:161]
	v_lshl_add_u64 v[32:33], s[8:9], 0, v[32:33]
	v_lshl_add_u64 v[34:35], v[34:35], 0, s[96:97]
	v_lshlrev_b64 v[36:37], 12, v[146:147]
	v_lshl_add_u64 v[32:33], v[34:35], 2, v[32:33]
	v_lshl_add_u64 v[36:37], s[46:47], 0, v[36:37]
	global_store_dwordx4 v[32:33], v[24:27], off offset:192 sc1
	v_cvt_pk_bf16_f32 v32, v24, v25
	v_cvt_pk_bf16_f32 v33, v26, v27
	v_lshl_add_u64 v[34:35], v[34:35], 1, v[36:37]
	global_store_dwordx2 v[34:35], v[32:33], off offset:96
	s_cbranch_execz .LBB0_1315

; DI u32x2 pack4(f32x4 v) { u32x2 r; r[0] = cvtpk(v[0], v[1]); r[1] = cvtpk(v[2], v[3]); return r; }
; template <int EPI>
; DI void gemm_epilogue(const Params& p, f32x4 (&acc)[8][4], int m0, int n0, int wr, int wc, int fr, int fq, u16* Cb, int ldc) {
;     ...
;       } else if (colt < 4096) {
;         const int c = col - 2048;
; #pragma clang loop unroll(full)
;         for (int m = 0; m < 8; ++m) {
;           const int row = rbase + m * 16;
;           if (!smp) { *(f32x4*)(p.out + O_AKP + (size_t)row * 2048 + c) = acc[m][n]; *(u32x2*)(p.KA + (size_t)row * 2048 + c) = pack4(acc[m][n]); }
;           else *(f32x4*)(p.out + O_AKS + (size_t)(row - MP) * 2048 + c) = acc[m][n];
;         }
.LBB0_1297:
	v_lshlrev_b64 v[32:33], 13, v[144:145]
	v_lshl_add_u64 v[34:35], v[128:129], 0, v[160:161]
	v_lshl_add_u64 v[32:33], s[8:9], 0, v[32:33]
	v_lshl_add_u64 v[34:35], v[34:35], 0, s[96:97]
	v_lshlrev_b64 v[36:37], 12, v[144:145]
	v_lshl_add_u64 v[32:33], v[34:35], 2, v[32:33]
	v_lshl_add_u64 v[36:37], s[46:47], 0, v[36:37]
	global_store_dwordx4 v[32:33], v[20:23], off offset:192 sc1
	v_cvt_pk_bf16_f32 v32, v20, v21
	v_cvt_pk_bf16_f32 v33, v22, v23
	v_lshl_add_u64 v[34:35], v[34:35], 1, v[36:37]
	global_store_dwordx2 v[34:35], v[32:33], off offset:96
	s_cbranch_execz .LBB0_1317

; DI u32x2 pack4(f32x4 v) { u32x2 r; r[0] = cvtpk(v[0], v[1]); r[1] = cvtpk(v[2], v[3]); return r; }
; template <int EPI>
; DI void gemm_epilogue(const Params& p, f32x4 (&acc)[8][4], int m0, int n0, int wr, int wc, int fr, int fq, u16* Cb, int ldc) {
;     ...
;       } else if (colt < 4096) {
;         const int c = col - 2048;
; #pragma clang loop unroll(full)
;         for (int m = 0; m < 8; ++m) {
;           const int row = rbase + m * 16;
;           if (!smp) { *(f32x4*)(p.out + O_AKP + (size_t)row * 2048 + c) = acc[m][n]; *(u32x2*)(p.KA + (size_t)row * 2048 + c) = pack4(acc[m][n]); }
;           else *(f32x4*)(p.out + O_AKS + (size_t)(row - MP) * 2048 + c) = acc[m][n];
;         }
.LBB0_1299:
	v_lshlrev_b64 v[32:33], 13, v[142:143]
	v_lshl_add_u64 v[34:35], v[128:129], 0, v[160:161]
	v_lshl_add_u64 v[32:33], s[8:9], 0, v[32:33]
	v_lshl_add_u64 v[34:35], v[34:35], 0, s[96:97]
	v_lshlrev_b64 v[36:37], 12, v[142:143]
	v_lshl_add_u64 v[32:33], v[34:35], 2, v[32:33]
	v_lshl_add_u64 v[36:37], s[46:47], 0, v[36:37]
	global_store_dwordx4 v[32:33], v[16:19], off offset:192 sc1
	v_cvt_pk_bf16_f32 v32, v16, v17
	v_cvt_pk_bf16_f32 v33, v18, v19
	v_lshl_add_u64 v[34:35], v[34:35], 1, v[36:37]
	global_store_dwordx2 v[34:35], v[32:33], off offset:96
	s_cbranch_execz .LBB0_1319

; DI u32x2 pack4(f32x4 v) { u32x2 r; r[0] = cvtpk(v[0], v[1]); r[1] = cvtpk(v[2], v[3]); return r; }
; template <int EPI>
; DI void gemm_epilogue(const Params& p, f32x4 (&acc)[8][4], int m0, int n0, int wr, int wc, int fr, int fq, u16* Cb, int ldc) {
;     ...
;       } else if (colt < 4096) {
;         const int c = col - 2048;
; #pragma clang loop unroll(full)
;         for (int m = 0; m < 8; ++m) {
;           const int row = rbase + m * 16;
;           if (!smp) { *(f32x4*)(p.out + O_AKP + (size_t)row * 2048 + c) = acc[m][n]; *(u32x2*)(p.KA + (size_t)row * 2048 + c) = pack4(acc[m][n]); }
;           else *(f32x4*)(p.out + O_AKS + (size_t)(row - MP) * 2048 + c) = acc[m][n];
;         }
.LBB0_1301:
	v_lshlrev_b64 v[32:33], 13, v[140:141]
	v_lshl_add_u64 v[34:35], v[128:129], 0, v[160:161]
	v_lshl_add_u64 v[32:33], s[8:9], 0, v[32:33]
	v_lshl_add_u64 v[34:35], v[34:35], 0, s[96:97]
	v_lshlrev_b64 v[36:37], 12, v[140:141]
	v_lshl_add_u64 v[32:33], v[34:35], 2, v[32:33]
	v_lshl_add_u64 v[36:37], s[46:47], 0, v[36:37]
	global_store_dwordx4 v[32:33], v[12:15], off offset:192 sc1
	v_cvt_pk_bf16_f32 v32, v12, v13
	v_cvt_pk_bf16_f32 v33, v14, v15
	v_lshl_add_u64 v[34:35], v[34:35], 1, v[36:37]
	global_store_dwordx2 v[34:35], v[32:33], off offset:96
	s_cbranch_execz .LBB0_1321

; DI u32x2 pack4(f32x4 v) { u32x2 r; r[0] = cvtpk(v[0], v[1]); r[1] = cvtpk(v[2], v[3]); return r; }
; template <int EPI>
; DI void gemm_epilogue(const Params& p, f32x4 (&acc)[8][4], int m0, int n0, int wr, int wc, int fr, int fq, u16* Cb, int ldc) {
;     ...
;       } else if (colt < 4096) {
;         const int c = col - 2048;
; #pragma clang loop unroll(full)
;         for (int m = 0; m < 8; ++m) {
;           const int row = rbase + m * 16;
;           if (!smp) { *(f32x4*)(p.out + O_AKP + (size_t)row * 2048 + c) = acc[m][n]; *(u32x2*)(p.KA + (size_t)row * 2048 + c) = pack4(acc[m][n]); }
;           else *(f32x4*)(p.out + O_AKS + (size_t)(row - MP) * 2048 + c) = acc[m][n];
;         }
.LBB0_1303:
	v_lshlrev_b64 v[32:33], 13, v[138:139]
	v_lshl_add_u64 v[34:35], v[128:129], 0, v[160:161]
	v_lshl_add_u64 v[32:33], s[8:9], 0, v[32:33]
	v_lshl_add_u64 v[34:35], v[34:35], 0, s[96:97]
	v_lshlrev_b64 v[36:37], 12, v[138:139]
	v_lshl_add_u64 v[32:33], v[34:35], 2, v[32:33]
	v_lshl_add_u64 v[36:37], s[46:47], 0, v[36:37]
	global_store_dwordx4 v[32:33], v[8:11], off offset:192 sc1
	v_cvt_pk_bf16_f32 v32, v8, v9
	v_cvt_pk_bf16_f32 v33, v10, v11
	v_lshl_add_u64 v[34:35], v[34:35], 1, v[36:37]
	global_store_dwordx2 v[34:35], v[32:33], off offset:96
	s_cbranch_execz .LBB0_1323

; DI u32x2 pack4(f32x4 v) { u32x2 r; r[0] = cvtpk(v[0], v[1]); r[1] = cvtpk(v[2], v[3]); return r; }
; template <int EPI>
; DI void gemm_epilogue(const Params& p, f32x4 (&acc)[8][4], int m0, int n0, int wr, int wc, int fr, int fq, u16* Cb, int ldc) {
;     ...
;       } else if (colt < 4096) {
;         const int c = col - 2048;
; #pragma clang loop unroll(full)
;         for (int m = 0; m < 8; ++m) {
;           const int row = rbase + m * 16;
;           if (!smp) { *(f32x4*)(p.out + O_AKP + (size_t)row * 2048 + c) = acc[m][n]; *(u32x2*)(p.KA + (size_t)row * 2048 + c) = pack4(acc[m][n]); }
;           else *(f32x4*)(p.out + O_AKS + (size_t)(row - MP) * 2048 + c) = acc[m][n];
;         }
.LBB0_1305:
	v_lshlrev_b64 v[32:33], 13, v[136:137]
	v_lshl_add_u64 v[34:35], v[128:129], 0, v[160:161]
	v_lshl_add_u64 v[32:33], s[8:9], 0, v[32:33]
	v_lshl_add_u64 v[34:35], v[34:35], 0, s[96:97]
	v_lshlrev_b64 v[36:37], 12, v[136:137]
	v_lshl_add_u64 v[32:33], v[34:35], 2, v[32:33]
	v_lshl_add_u64 v[36:37], s[46:47], 0, v[36:37]
	global_store_dwordx4 v[32:33], v[4:7], off offset:192 sc1
	v_cvt_pk_bf16_f32 v32, v4, v5
	v_cvt_pk_bf16_f32 v33, v6, v7
	v_lshl_add_u64 v[34:35], v[34:35], 1, v[36:37]
	global_store_dwordx2 v[34:35], v[32:33], off offset:96
	s_cbranch_execz .LBB0_1325

; DI u32x2 pack4(f32x4 v) { u32x2 r; r[0] = cvtpk(v[0], v[1]); r[1] = cvtpk(v[2], v[3]); return r; }
; template <int EPI>
; DI void gemm_epilogue(const Params& p, f32x4 (&acc)[8][4], int m0, int n0, int wr, int wc, int fr, int fq, u16* Cb, int ldc) {
;     ...
;       } else if (colt < 4096) {
;         const int c = col - 2048;
; #pragma clang loop unroll(full)
;         for (int m = 0; m < 8; ++m) {
;           const int row = rbase + m * 16;
;           if (!smp) { *(f32x4*)(p.out + O_AKP + (size_t)row * 2048 + c) = acc[m][n]; *(u32x2*)(p.KA + (size_t)row * 2048 + c) = pack4(acc[m][n]); }
;           else *(f32x4*)(p.out + O_AKS + (size_t)(row - MP) * 2048 + c) = acc[m][n];
;         }
.LBB0_1307:
	v_lshlrev_b64 v[32:33], 13, v[134:135]
	v_lshl_add_u64 v[34:35], v[128:129], 0, v[160:161]
	v_lshl_add_u64 v[32:33], s[8:9], 0, v[32:33]
	v_lshl_add_u64 v[34:35], v[34:35], 0, s[96:97]
	v_lshlrev_b64 v[36:37], 12, v[134:135]
	v_lshl_add_u64 v[32:33], v[34:35], 2, v[32:33]
	v_lshl_add_u64 v[36:37], s[46:47], 0, v[36:37]
	global_store_dwordx4 v[32:33], v[0:3], off offset:192 sc1
	v_cvt_pk_bf16_f32 v32, v0, v1
	v_cvt_pk_bf16_f32 v33, v2, v3
	v_lshl_add_u64 v[34:35], v[34:35], 1, v[36:37]
	s_mov_b64 s[0:1], 0
	global_store_dwordx2 v[34:35], v[32:33], off offset:96
.LBB0_1308:
	s_andn2_b64 vcc, exec, s[0:1]
	s_cbranch_vccnz .LBB0_1310
	v_lshlrev_b64 v[32:33], 13, v[130:131]
	v_lshl_add_u64 v[32:33], s[64:65], 0, v[32:33]
	v_lshl_add_u64 v[34:35], v[128:129], 0, v[160:161]
	v_lshl_add_u64 v[32:33], v[34:35], 2, v[32:33]
	v_add_co_u32_e32 v32, vcc, 0xf80df000, v32
	s_nop 1
	v_addc_co_u32_e32 v33, vcc, -1, v33, vcc
	global_store_dwordx4 v[32:33], v[0:3], off offset:-3904 sc1

; DI u32x2 pack4(f32x4 v) { u32x2 r; r[0] = cvtpk(v[0], v[1]); r[1] = cvtpk(v[2], v[3]); return r; }
; template <int EPI>
; DI void gemm_epilogue(const Params& p, f32x4 (&acc)[8][4], int m0, int n0, int wr, int wc, int fr, int fq, u16* Cb, int ldc) {
;     ...
; #pragma clang loop unroll(full)
;         for (int m = 0; m < 8; ++m) {
;           const int row = rbase + m * 16;
;           if (!smp) { *(f32x4*)(p.out + O_AKP + (size_t)row * 2048 + c) = acc[m][n]; *(u32x2*)(p.KA + (size_t)row * 2048 + c) = pack4(acc[m][n]); }
;           else *(f32x4*)(p.out + O_AKS + (size_t)(row - MP) * 2048 + c) = acc[m][n];
.LBB0_1313:
	v_lshlrev_b64 v[32:33], 13, v[130:131]
	v_lshl_add_u64 v[32:33], s[64:65], 0, v[32:33]
	v_lshl_add_u64 v[34:35], v[128:129], 0, v[160:161]
	v_lshl_add_u64 v[32:33], v[34:35], 2, v[32:33]
	v_add_co_u32_e32 v32, vcc, 0xf7fff000, v32
	s_nop 1
	v_addc_co_u32_e32 v33, vcc, -1, v33, vcc
	global_store_dwordx4 v[32:33], v[28:31], off offset:-3904 sc1
	s_and_b64 vcc, exec, s[2:3]
	s_mov_b64 s[0:1], -1
	s_cbranch_vccz .LBB0_1295

; DI u32x2 pack4(f32x4 v) { u32x2 r; r[0] = cvtpk(v[0], v[1]); r[1] = cvtpk(v[2], v[3]); return r; }
; template <int EPI>
; DI void gemm_epilogue(const Params& p, f32x4 (&acc)[8][4], int m0, int n0, int wr, int wc, int fr, int fq, u16* Cb, int ldc) {
;     ...
; #pragma clang loop unroll(full)
;         for (int m = 0; m < 8; ++m) {
;           const int row = rbase + m * 16;
;           if (!smp) { *(f32x4*)(p.out + O_AKP + (size_t)row * 2048 + c) = acc[m][n]; *(u32x2*)(p.KA + (size_t)row * 2048 + c) = pack4(acc[m][n]); }
;           else *(f32x4*)(p.out + O_AKS + (size_t)(row - MP) * 2048 + c) = acc[m][n];
.LBB0_1315:
	v_lshlrev_b64 v[32:33], 13, v[130:131]
	v_lshl_add_u64 v[32:33], s[64:65], 0, v[32:33]
	v_lshl_add_u64 v[34:35], v[128:129], 0, v[160:161]
	v_lshl_add_u64 v[32:33], v[34:35], 2, v[32:33]
	v_add_co_u32_e32 v32, vcc, 0xf801f000, v32
	s_nop 1
	v_addc_co_u32_e32 v33, vcc, -1, v33, vcc
	global_store_dwordx4 v[32:33], v[24:27], off offset:-3904 sc1
	s_and_b64 vcc, exec, s[2:3]
	s_mov_b64 s[0:1], -1
	s_cbranch_vccz .LBB0_1297

; DI u32x2 pack4(f32x4 v) { u32x2 r; r[0] = cvtpk(v[0], v[1]); r[1] = cvtpk(v[2], v[3]); return r; }
; template <int EPI>
; DI void gemm_epilogue(const Params& p, f32x4 (&acc)[8][4], int m0, int n0, int wr, int wc, int fr, int fq, u16* Cb, int ldc) {
;     ...
; #pragma clang loop unroll(full)
;         for (int m = 0; m < 8; ++m) {
;           const int row = rbase + m * 16;
;           if (!smp) { *(f32x4*)(p.out + O_AKP + (size_t)row * 2048 + c) = acc[m][n]; *(u32x2*)(p.KA + (size_t)row * 2048 + c) = pack4(acc[m][n]); }
;           else *(f32x4*)(p.out + O_AKS + (size_t)(row - MP) * 2048 + c) = acc[m][n];
.LBB0_1317:
	v_lshlrev_b64 v[32:33], 13, v[130:131]
	v_lshl_add_u64 v[32:33], s[64:65], 0, v[32:33]
	v_lshl_add_u64 v[34:35], v[128:129], 0, v[160:161]
	v_lshl_add_u64 v[32:33], v[34:35], 2, v[32:33]
	v_add_co_u32_e32 v32, vcc, 0xf803f000, v32
	s_nop 1
	v_addc_co_u32_e32 v33, vcc, -1, v33, vcc
	global_store_dwordx4 v[32:33], v[20:23], off offset:-3904 sc1
	s_and_b64 vcc, exec, s[2:3]
	s_mov_b64 s[0:1], -1
	s_cbranch_vccz .LBB0_1299

; DI u32x2 pack4(f32x4 v) { u32x2 r; r[0] = cvtpk(v[0], v[1]); r[1] = cvtpk(v[2], v[3]); return r; }
; template <int EPI>
; DI void gemm_epilogue(const Params& p, f32x4 (&acc)[8][4], int m0, int n0, int wr, int wc, int fr, int fq, u16* Cb, int ldc) {
;     ...
; #pragma clang loop unroll(full)
;         for (int m = 0; m < 8; ++m) {
;           const int row = rbase + m * 16;
;           if (!smp) { *(f32x4*)(p.out + O_AKP + (size_t)row * 2048 + c) = acc[m][n]; *(u32x2*)(p.KA + (size_t)row * 2048 + c) = pack4(acc[m][n]); }
;           else *(f32x4*)(p.out + O_AKS + (size_t)(row - MP) * 2048 + c) = acc[m][n];
.LBB0_1319:
	v_lshlrev_b64 v[32:33], 13, v[130:131]
	v_lshl_add_u64 v[32:33], s[64:65], 0, v[32:33]
	v_lshl_add_u64 v[34:35], v[128:129], 0, v[160:161]
	v_lshl_add_u64 v[32:33], v[34:35], 2, v[32:33]
	v_add_co_u32_e32 v32, vcc, 0xf805f000, v32
	s_nop 1
	v_addc_co_u32_e32 v33, vcc, -1, v33, vcc
	global_store_dwordx4 v[32:33], v[16:19], off offset:-3904 sc1
	s_and_b64 vcc, exec, s[2:3]
	s_mov_b64 s[0:1], -1
	s_cbranch_vccz .LBB0_1301

; DI u32x2 pack4(f32x4 v) { u32x2 r; r[0] = cvtpk(v[0], v[1]); r[1] = cvtpk(v[2], v[3]); return r; }
; template <int EPI>
; DI void gemm_epilogue(const Params& p, f32x4 (&acc)[8][4], int m0, int n0, int wr, int wc, int fr, int fq, u16* Cb, int ldc) {
;     ...
; #pragma clang loop unroll(full)
;         for (int m = 0; m < 8; ++m) {
;           const int row = rbase + m * 16;
;           if (!smp) { *(f32x4*)(p.out + O_AKP + (size_t)row * 2048 + c) = acc[m][n]; *(u32x2*)(p.KA + (size_t)row * 2048 + c) = pack4(acc[m][n]); }
;           else *(f32x4*)(p.out + O_AKS + (size_t)(row - MP) * 2048 + c) = acc[m][n];
.LBB0_1321:
	v_lshlrev_b64 v[32:33], 13, v[130:131]
	v_lshl_add_u64 v[32:33], s[64:65], 0, v[32:33]
	v_lshl_add_u64 v[34:35], v[128:129], 0, v[160:161]
	v_lshl_add_u64 v[32:33], v[34:35], 2, v[32:33]
	v_add_co_u32_e32 v32, vcc, 0xf807f000, v32
	s_nop 1
	v_addc_co_u32_e32 v33, vcc, -1, v33, vcc
	global_store_dwordx4 v[32:33], v[12:15], off offset:-3904 sc1
	s_and_b64 vcc, exec, s[2:3]
	s_mov_b64 s[0:1], -1
	s_cbranch_vccz .LBB0_1303

; DI u32x2 pack4(f32x4 v) { u32x2 r; r[0] = cvtpk(v[0], v[1]); r[1] = cvtpk(v[2], v[3]); return r; }
; template <int EPI>
; DI void gemm_epilogue(const Params& p, f32x4 (&acc)[8][4], int m0, int n0, int wr, int wc, int fr, int fq, u16* Cb, int ldc) {
;     ...
; #pragma clang loop unroll(full)
;         for (int m = 0; m < 8; ++m) {
;           const int row = rbase + m * 16;
;           if (!smp) { *(f32x4*)(p.out + O_AKP + (size_t)row * 2048 + c) = acc[m][n]; *(u32x2*)(p.KA + (size_t)row * 2048 + c) = pack4(acc[m][n]); }
;           else *(f32x4*)(p.out + O_AKS + (size_t)(row - MP) * 2048 + c) = acc[m][n];
.LBB0_1323:
	v_lshlrev_b64 v[32:33], 13, v[130:131]
	v_lshl_add_u64 v[32:33], s[64:65], 0, v[32:33]
	v_lshl_add_u64 v[34:35], v[128:129], 0, v[160:161]
	v_lshl_add_u64 v[32:33], v[34:35], 2, v[32:33]
	v_add_co_u32_e32 v32, vcc, 0xf809f000, v32
	s_nop 1
	v_addc_co_u32_e32 v33, vcc, -1, v33, vcc
	global_store_dwordx4 v[32:33], v[8:11], off offset:-3904 sc1
	s_and_b64 vcc, exec, s[2:3]
	s_mov_b64 s[0:1], -1
	s_cbranch_vccz .LBB0_1305

; DI u32x2 pack4(f32x4 v) { u32x2 r; r[0] = cvtpk(v[0], v[1]); r[1] = cvtpk(v[2], v[3]); return r; }
; template <int EPI>
; DI void gemm_epilogue(const Params& p, f32x4 (&acc)[8][4], int m0, int n0, int wr, int wc, int fr, int fq, u16* Cb, int ldc) {
;     ...
; #pragma clang loop unroll(full)
;         for (int m = 0; m < 8; ++m) {
;           const int row = rbase + m * 16;
;           if (!smp) { *(f32x4*)(p.out + O_AKP + (size_t)row * 2048 + c) = acc[m][n]; *(u32x2*)(p.KA + (size_t)row * 2048 + c) = pack4(acc[m][n]); }
;           else *(f32x4*)(p.out + O_AKS + (size_t)(row - MP) * 2048 + c) = acc[m][n];
.LBB0_1325:
	v_lshlrev_b64 v[32:33], 13, v[130:131]
	v_lshl_add_u64 v[32:33], s[64:65], 0, v[32:33]
	v_lshl_add_u64 v[34:35], v[128:129], 0, v[160:161]
	v_lshl_add_u64 v[32:33], v[34:35], 2, v[32:33]
	v_add_co_u32_e32 v32, vcc, 0xf80bf000, v32
	s_nop 1
	v_addc_co_u32_e32 v33, vcc, -1, v33, vcc
	global_store_dwordx4 v[32:33], v[4:7], off offset:-3904 sc1
	s_and_b64 vcc, exec, s[2:3]
	s_mov_b64 s[0:1], -1
	s_cbranch_vccnz .LBB0_1308
	s_branch .LBB0_1307
